# baseline (speedup 1.0000x reference)
; __device__ __forceinline__ u16 f2bf(float f) {
;   u32 u = __float_as_uint(f);
;   u += 0x7fffu + ((u >> 16) & 1u);
;   return (u16)(u >> 16);
; }
; __device__ __forceinline__ float bf2f(u16 h) { return __uint_as_float(((u32)h) << 16); }
; __device__ __forceinline__ float bflo(u32 w) { return __uint_as_float(w << 16); }
; __device__ __forceinline__ float bfhi(u32 w) { return __uint_as_float(w & 0xffff0000u); }
; __device__ __forceinline__ u32 pack2(float a, float b) { return (u32)f2bf(a) | ((u32)f2bf(b) << 16); }
; __device__ __forceinline__ void gemm_tile(const GemmArgs& ga, int wgid, int next_wgid, bool prefetched, u16* shm, unsigned char* ws, int wv_) {
;     ...
;   } else if (epi == EPI_Z || epi == EPI_PP) {
;     const int ldo = (epi == EPI_Z || ga.ldo) ? ga.ldo : D_;
;     float sc[2][4][4];
;     _Pragma("unroll") for (int ai = 0; ai < 2; ++ai)
;       _Pragma("unroll") for (int m = 0; m < 4; ++m)
;         _Pragma("unroll") for (int j = 0; j < 4; ++j) sc[ai][m][j] = (epi == EPI_Z) ? e_ss[rbase + ai * HALF + m * 16 + j] : 0.f;
;     _Pragma("unroll") for (int ai = 0; ai < 2; ++ai)
;       _Pragma("unroll") for (int m = 0; m < 4; ++m)
;         _Pragma("unroll") for (int j = 0; j < 4; ++j) {
;           int row = rbase + ai * HALF + m * 16 + j;
;           float s = (epi == EPI_Z) ? rsqrtf(sc[ai][m][j] * (1.f / D_) + 1e-6f) : 1.f;
;           *(uint2*)(e_outb + (size_t)row * ldo + bcol + lc4) =
;               make_uint2(pack2(acc[ai][0][m][0][j] * s, acc[ai][0][m][1][j] * s), pack2(acc[ai][1][m][0][j] * s, acc[ai][1][m][1][j] * s));
;         }
.LBB0_1091:
	v_cmp_gt_f32_e32 vcc, s93, v172
	v_mul_f32_e32 v0, 0x4b800000, v172
	s_ashr_i32 s13, s12, 31
	v_cndmask_b32_e32 v0, v172, v0, vcc
	s_lshl_b64 s[6:7], s[12:13], 1
	v_rsq_f32_e32 v0, v0
	s_add_u32 s6, s90, s6
	s_addc_u32 s7, s91, s7
	v_lshlrev_b32_e32 v166, 1, v134
	v_lshl_add_u64 v[128:129], s[6:7], 0, v[166:167]
	v_mad_u64_u32 v[2:3], s[6:7], s2, v168, 0
	v_mul_f32_e32 v1, 0x45800000, v0
	v_mov_b32_e32 v8, v3
	v_cndmask_b32_e32 v0, v0, v1, vcc
	v_mad_u64_u32 v[8:9], s[6:7], s2, v169, v[8:9]
	v_cndmask_b32_e64 v0, 1.0, v0, s[4:5]
	v_mov_b32_e32 v3, v8
	v_mov_b32_e32 v8, v116
	v_mov_b32_e32 v9, v124
	v_pk_mul_f32 v[8:9], v[8:9], v[0:1] op_sel_hi:[1,0]
	v_mov_b32_e32 v10, v112
	v_mov_b32_e32 v11, v120
	v_pk_mul_f32 v[0:1], v[10:11], v[0:1] op_sel_hi:[1,0]
	v_lshl_add_u64 v[2:3], v[2:3], 1, v[128:129]
	v_cvt_pk_bf16_f32 v1, v9, v1
	v_cvt_pk_bf16_f32 v0, v8, v0
	global_store_dwordx2 v[2:3], v[0:1], off
	v_or_b32_e32 v1, 1, v168
	v_rsq_f32_e32 v0, v159
	v_mov_b32_e32 v8, v117
	v_mov_b32_e32 v9, v125
	v_mov_b32_e32 v10, v113
	v_cndmask_b32_e64 v0, 1.0, v0, s[4:5]
	v_mad_u64_u32 v[2:3], s[6:7], s2, v1, 0
	v_ashrrev_i32_e32 v1, 31, v168
	v_pk_mul_f32 v[8:9], v[8:9], v[0:1] op_sel_hi:[1,0]
	v_mov_b32_e32 v11, v121
	v_mul_lo_u32 v159, s2, v1
	v_pk_mul_f32 v[0:1], v[10:11], v[0:1] op_sel_hi:[1,0]
	v_add_u32_e32 v3, v3, v159
	v_lshl_add_u64 v[2:3], v[2:3], 1, v[128:129]
	v_cvt_pk_bf16_f32 v1, v9, v1
	v_cvt_pk_bf16_f32 v0, v8, v0
	global_store_dwordx2 v[2:3], v[0:1], off
	v_or_b32_e32 v1, 2, v168
	v_rsq_f32_e32 v0, v170
	v_mov_b32_e32 v8, v118
	v_mov_b32_e32 v9, v126
	v_mov_b32_e32 v10, v114
	v_cndmask_b32_e64 v0, 1.0, v0, s[4:5]
	v_pk_mul_f32 v[8:9], v[8:9], v[0:1] op_sel_hi:[1,0]
	v_mov_b32_e32 v11, v122
	v_mad_u64_u32 v[2:3], s[6:7], s2, v1, 0
	v_pk_mul_f32 v[0:1], v[10:11], v[0:1] op_sel_hi:[1,0]
	v_add_u32_e32 v3, v3, v159
	v_lshl_add_u64 v[2:3], v[2:3], 1, v[128:129]
	v_cvt_pk_bf16_f32 v1, v9, v1
	v_cvt_pk_bf16_f32 v0, v8, v0
	global_store_dwordx2 v[2:3], v[0:1], off
	v_or_b32_e32 v1, 3, v168
	v_rsq_f32_e32 v0, v165
	v_mov_b32_e32 v8, v119
	v_mov_b32_e32 v9, v127
	v_mov_b32_e32 v10, v115
	v_cndmask_b32_e64 v0, 1.0, v0, s[4:5]
	v_pk_mul_f32 v[8:9], v[8:9], v[0:1] op_sel_hi:[1,0]
	v_mov_b32_e32 v11, v123
	v_mad_u64_u32 v[2:3], s[6:7], s2, v1, 0
	v_pk_mul_f32 v[0:1], v[10:11], v[0:1] op_sel_hi:[1,0]
	v_add_u32_e32 v3, v3, v159
	v_lshl_add_u64 v[2:3], v[2:3], 1, v[128:129]
	v_cvt_pk_bf16_f32 v1, v9, v1
	v_cvt_pk_bf16_f32 v0, v8, v0
	global_store_dwordx2 v[2:3], v[0:1], off
	v_mov_b32_e32 v8, v100
	v_rsq_f32_e32 v0, v164
	v_mov_b32_e32 v9, v108
	v_mov_b32_e32 v10, v96
	v_mov_b32_e32 v11, v104
	v_cndmask_b32_e64 v0, 1.0, v0, s[4:5]
	v_pk_mul_f32 v[8:9], v[8:9], v[0:1] op_sel_hi:[1,0]
	v_pk_mul_f32 v[0:1], v[10:11], v[0:1] op_sel_hi:[1,0]
	v_or_b32_e32 v16, 16, v168
	v_mad_u64_u32 v[2:3], s[6:7], s2, v16, 0
	v_add_u32_e32 v3, v3, v159
	v_lshl_add_u64 v[2:3], v[2:3], 1, v[128:129]
	v_cvt_pk_bf16_f32 v1, v9, v1
	v_cvt_pk_bf16_f32 v0, v8, v0
	global_store_dwordx2 v[2:3], v[0:1], off
	v_or_b32_e32 v1, 17, v168
	v_rsq_f32_e32 v0, v163
	v_mov_b32_e32 v8, v101
	v_mov_b32_e32 v9, v109
	v_mov_b32_e32 v10, v97
	v_cndmask_b32_e64 v0, 1.0, v0, s[4:5]
	v_pk_mul_f32 v[8:9], v[8:9], v[0:1] op_sel_hi:[1,0]
	v_mov_b32_e32 v11, v105
	v_mad_u64_u32 v[2:3], s[6:7], s2, v1, 0
	v_pk_mul_f32 v[0:1], v[10:11], v[0:1] op_sel_hi:[1,0]
	v_add_u32_e32 v3, v3, v159
	v_lshl_add_u64 v[2:3], v[2:3], 1, v[128:129]
	v_cvt_pk_bf16_f32 v1, v9, v1
	v_cvt_pk_bf16_f32 v0, v8, v0
	global_store_dwordx2 v[2:3], v[0:1], off
	v_or_b32_e32 v1, 18, v168
	v_rsq_f32_e32 v0, v162
	v_mov_b32_e32 v8, v102
	v_mov_b32_e32 v9, v110
	v_mov_b32_e32 v10, v98
	v_cndmask_b32_e64 v0, 1.0, v0, s[4:5]
	v_pk_mul_f32 v[8:9], v[8:9], v[0:1] op_sel_hi:[1,0]
	v_mov_b32_e32 v11, v106
	v_mad_u64_u32 v[2:3], s[6:7], s2, v1, 0
	v_pk_mul_f32 v[0:1], v[10:11], v[0:1] op_sel_hi:[1,0]
	v_add_u32_e32 v3, v3, v159
	v_lshl_add_u64 v[2:3], v[2:3], 1, v[128:129]
	v_cvt_pk_bf16_f32 v1, v9, v1
	v_cvt_pk_bf16_f32 v0, v8, v0
	global_store_dwordx2 v[2:3], v[0:1], off
	v_or_b32_e32 v1, 19, v168
	v_rsq_f32_e32 v0, v160
	v_mov_b32_e32 v8, v103
	v_mov_b32_e32 v9, v111
	v_mov_b32_e32 v10, v99
	v_cndmask_b32_e64 v0, 1.0, v0, s[4:5]
	v_pk_mul_f32 v[8:9], v[8:9], v[0:1] op_sel_hi:[1,0]
	v_mov_b32_e32 v11, v107
	v_mad_u64_u32 v[2:3], s[6:7], s2, v1, 0
	v_pk_mul_f32 v[0:1], v[10:11], v[0:1] op_sel_hi:[1,0]
	v_add_u32_e32 v3, v3, v159
	v_lshl_add_u64 v[2:3], v[2:3], 1, v[128:129]
	v_cvt_pk_bf16_f32 v1, v9, v1
	v_cvt_pk_bf16_f32 v0, v8, v0
	global_store_dwordx2 v[2:3], v[0:1], off
	v_mov_b32_e32 v8, v84
	v_rsq_f32_e32 v0, v158
	v_mov_b32_e32 v9, v92
	v_mov_b32_e32 v10, v80
	v_mov_b32_e32 v11, v88
	v_cndmask_b32_e64 v0, 1.0, v0, s[4:5]
	v_pk_mul_f32 v[8:9], v[8:9], v[0:1] op_sel_hi:[1,0]
	v_pk_mul_f32 v[0:1], v[10:11], v[0:1] op_sel_hi:[1,0]
	v_or_b32_e32 v171, 32, v168
	v_mad_u64_u32 v[2:3], s[6:7], s2, v171, 0
	v_add_u32_e32 v3, v3, v159
	v_lshl_add_u64 v[2:3], v[2:3], 1, v[128:129]
	v_cvt_pk_bf16_f32 v1, v9, v1
	v_cvt_pk_bf16_f32 v0, v8, v0
	global_store_dwordx2 v[2:3], v[0:1], off
	v_or_b32_e32 v1, 33, v168
	v_rsq_f32_e32 v0, v157
	v_mov_b32_e32 v8, v85
	v_mov_b32_e32 v9, v93
	v_mov_b32_e32 v10, v81
	v_cndmask_b32_e64 v0, 1.0, v0, s[4:5]
	v_pk_mul_f32 v[8:9], v[8:9], v[0:1] op_sel_hi:[1,0]
	v_mov_b32_e32 v11, v89
	v_mad_u64_u32 v[2:3], s[6:7], s2, v1, 0
	v_pk_mul_f32 v[0:1], v[10:11], v[0:1] op_sel_hi:[1,0]
	v_add_u32_e32 v3, v3, v159
	v_lshl_add_u64 v[2:3], v[2:3], 1, v[128:129]
	v_cvt_pk_bf16_f32 v1, v9, v1
	v_cvt_pk_bf16_f32 v0, v8, v0
	global_store_dwordx2 v[2:3], v[0:1], off
	v_or_b32_e32 v1, 34, v168
	v_rsq_f32_e32 v0, v156
; __device__ __forceinline__ u16 f2bf(float f) {
;   u32 u = __float_as_uint(f);
;   u += 0x7fffu + ((u >> 16) & 1u);
;   return (u16)(u >> 16);
; }
; __device__ __forceinline__ float bf2f(u16 h) { return __uint_as_float(((u32)h) << 16); }
; __device__ __forceinline__ float bflo(u32 w) { return __uint_as_float(w << 16); }
; __device__ __forceinline__ float bfhi(u32 w) { return __uint_as_float(w & 0xffff0000u); }
; __device__ __forceinline__ u32 pack2(float a, float b) { return (u32)f2bf(a) | ((u32)f2bf(b) << 16); }
; __device__ __forceinline__ void gemm_tile(const GemmArgs& ga, int wgid, int next_wgid, bool prefetched, u16* shm, unsigned char* ws, int wv_) {
;     ...
;   } else if (epi == EPI_Z || epi == EPI_PP) {
;     const int ldo = (epi == EPI_Z || ga.ldo) ? ga.ldo : D_;
;     float sc[2][4][4];
;     _Pragma("unroll") for (int ai = 0; ai < 2; ++ai)
;       _Pragma("unroll") for (int m = 0; m < 4; ++m)
;         _Pragma("unroll") for (int j = 0; j < 4; ++j) sc[ai][m][j] = (epi == EPI_Z) ? e_ss[rbase + ai * HALF + m * 16 + j] : 0.f;
;     _Pragma("unroll") for (int ai = 0; ai < 2; ++ai)
;       _Pragma("unroll") for (int m = 0; m < 4; ++m)
;         _Pragma("unroll") for (int j = 0; j < 4; ++j) {
;           int row = rbase + ai * HALF + m * 16 + j;
;           float s = (epi == EPI_Z) ? rsqrtf(sc[ai][m][j] * (1.f / D_) + 1e-6f) : 1.f;
;           *(uint2*)(e_outb + (size_t)row * ldo + bcol + lc4) =
;               make_uint2(pack2(acc[ai][0][m][0][j] * s, acc[ai][0][m][1][j] * s), pack2(acc[ai][1][m][0][j] * s, acc[ai][1][m][1][j] * s));
;         }
	v_mov_b32_e32 v8, v86
	v_mov_b32_e32 v9, v94
	v_mov_b32_e32 v10, v82
	v_cndmask_b32_e64 v0, 1.0, v0, s[4:5]
	v_pk_mul_f32 v[8:9], v[8:9], v[0:1] op_sel_hi:[1,0]
	v_mov_b32_e32 v11, v90
	v_mad_u64_u32 v[2:3], s[6:7], s2, v1, 0
	v_pk_mul_f32 v[0:1], v[10:11], v[0:1] op_sel_hi:[1,0]
	v_add_u32_e32 v3, v3, v159
	v_lshl_add_u64 v[2:3], v[2:3], 1, v[128:129]
	v_cvt_pk_bf16_f32 v1, v9, v1
	v_cvt_pk_bf16_f32 v0, v8, v0
	global_store_dwordx2 v[2:3], v[0:1], off
	v_or_b32_e32 v1, 35, v168
	v_rsq_f32_e32 v0, v155
	v_mov_b32_e32 v8, v87
	v_mov_b32_e32 v9, v95
	v_mov_b32_e32 v10, v83
	v_cndmask_b32_e64 v0, 1.0, v0, s[4:5]
	v_pk_mul_f32 v[8:9], v[8:9], v[0:1] op_sel_hi:[1,0]
	v_mov_b32_e32 v11, v91
	v_mad_u64_u32 v[2:3], s[6:7], s2, v1, 0
	v_pk_mul_f32 v[0:1], v[10:11], v[0:1] op_sel_hi:[1,0]
	v_add_u32_e32 v3, v3, v159
	v_lshl_add_u64 v[2:3], v[2:3], 1, v[128:129]
	v_cvt_pk_bf16_f32 v1, v9, v1
	v_cvt_pk_bf16_f32 v0, v8, v0
	global_store_dwordx2 v[2:3], v[0:1], off
	v_mov_b32_e32 v8, v68
	v_rsq_f32_e32 v0, v153
	v_mov_b32_e32 v9, v76
	v_mov_b32_e32 v10, v64
	v_mov_b32_e32 v11, v72
	v_cndmask_b32_e64 v0, 1.0, v0, s[4:5]
	v_pk_mul_f32 v[8:9], v[8:9], v[0:1] op_sel_hi:[1,0]
	v_pk_mul_f32 v[0:1], v[10:11], v[0:1] op_sel_hi:[1,0]
	v_or_b32_e32 v161, 48, v168
	v_mad_u64_u32 v[2:3], s[6:7], s2, v161, 0
	v_add_u32_e32 v3, v3, v159
	v_lshl_add_u64 v[2:3], v[2:3], 1, v[128:129]
	v_cvt_pk_bf16_f32 v1, v9, v1
	v_cvt_pk_bf16_f32 v0, v8, v0
	global_store_dwordx2 v[2:3], v[0:1], off
	v_or_b32_e32 v1, 49, v168
	v_rsq_f32_e32 v0, v152
	v_mov_b32_e32 v8, v69
	v_mov_b32_e32 v9, v77
	v_mov_b32_e32 v10, v65
	v_cndmask_b32_e64 v0, 1.0, v0, s[4:5]
	v_pk_mul_f32 v[8:9], v[8:9], v[0:1] op_sel_hi:[1,0]
	v_mov_b32_e32 v11, v73
	v_mad_u64_u32 v[2:3], s[6:7], s2, v1, 0
	v_pk_mul_f32 v[0:1], v[10:11], v[0:1] op_sel_hi:[1,0]
	v_add_u32_e32 v3, v3, v159
	v_lshl_add_u64 v[2:3], v[2:3], 1, v[128:129]
	v_cvt_pk_bf16_f32 v1, v9, v1
	v_cvt_pk_bf16_f32 v0, v8, v0
	global_store_dwordx2 v[2:3], v[0:1], off
	v_or_b32_e32 v1, 50, v168
	v_rsq_f32_e32 v0, v151
	v_mov_b32_e32 v8, v70
	v_mov_b32_e32 v9, v78
	v_mov_b32_e32 v10, v66
	v_cndmask_b32_e64 v0, 1.0, v0, s[4:5]
	v_pk_mul_f32 v[8:9], v[8:9], v[0:1] op_sel_hi:[1,0]
	v_mov_b32_e32 v11, v74
	v_mad_u64_u32 v[2:3], s[6:7], s2, v1, 0
	v_pk_mul_f32 v[0:1], v[10:11], v[0:1] op_sel_hi:[1,0]
	v_add_u32_e32 v3, v3, v159
	v_lshl_add_u64 v[2:3], v[2:3], 1, v[128:129]
	v_cvt_pk_bf16_f32 v1, v9, v1
	v_cvt_pk_bf16_f32 v0, v8, v0
	global_store_dwordx2 v[2:3], v[0:1], off
	v_or_b32_e32 v1, 51, v168
	v_rsq_f32_e32 v0, v150
	v_mov_b32_e32 v8, v71
	v_mov_b32_e32 v9, v79
	v_mov_b32_e32 v10, v67
	v_cndmask_b32_e64 v0, 1.0, v0, s[4:5]
	v_pk_mul_f32 v[8:9], v[8:9], v[0:1] op_sel_hi:[1,0]
	v_mov_b32_e32 v11, v75
	v_mad_u64_u32 v[2:3], s[6:7], s2, v1, 0
	v_pk_mul_f32 v[0:1], v[10:11], v[0:1] op_sel_hi:[1,0]
	v_add_u32_e32 v3, v3, v159
	v_lshl_add_u64 v[2:3], v[2:3], 1, v[128:129]
	v_cvt_pk_bf16_f32 v1, v9, v1
	v_cvt_pk_bf16_f32 v0, v8, v0
	global_store_dwordx2 v[2:3], v[0:1], off
	v_add_u32_e32 v154, 0x80, v168
	v_rsq_f32_e32 v0, v149
	v_mad_u64_u32 v[2:3], s[6:7], s2, v154, 0
	v_mov_b32_e32 v8, v3
	v_ashrrev_i32_e32 v1, 31, v154
	v_mad_u64_u32 v[8:9], s[6:7], s2, v1, v[8:9]
	v_cndmask_b32_e64 v0, 1.0, v0, s[4:5]
	v_mov_b32_e32 v3, v8
	v_mov_b32_e32 v8, v52
	v_mov_b32_e32 v9, v60
	v_pk_mul_f32 v[8:9], v[8:9], v[0:1] op_sel_hi:[1,0]
	v_mov_b32_e32 v10, v48
	v_mov_b32_e32 v11, v56
	v_pk_mul_f32 v[0:1], v[10:11], v[0:1] op_sel_hi:[1,0]
	v_lshl_add_u64 v[2:3], v[2:3], 1, v[128:129]
	v_cvt_pk_bf16_f32 v1, v9, v1
	v_cvt_pk_bf16_f32 v0, v8, v0
	global_store_dwordx2 v[2:3], v[0:1], off
	v_add_u32_e32 v1, 0x81, v168
	v_rsq_f32_e32 v0, v147
	v_ashrrev_i32_e32 v9, 31, v1
	v_mov_b32_e32 v10, v49
	v_mov_b32_e32 v11, v57
	v_mad_u64_u32 v[2:3], s[6:7], s2, v1, 0
	v_mov_b32_e32 v8, v3
	v_mad_u64_u32 v[8:9], s[6:7], s2, v9, v[8:9]
	v_cndmask_b32_e64 v0, 1.0, v0, s[4:5]
	v_mov_b32_e32 v3, v8
	v_mov_b32_e32 v8, v53
	v_mov_b32_e32 v9, v61
	v_pk_mul_f32 v[8:9], v[8:9], v[0:1] op_sel_hi:[1,0]
	v_pk_mul_f32 v[0:1], v[10:11], v[0:1] op_sel_hi:[1,0]
	v_lshl_add_u64 v[2:3], v[2:3], 1, v[128:129]
	v_cvt_pk_bf16_f32 v1, v9, v1
	v_cvt_pk_bf16_f32 v0, v8, v0
	global_store_dwordx2 v[2:3], v[0:1], off
	v_add_u32_e32 v1, 0x82, v168
	v_rsq_f32_e32 v0, v146
	v_ashrrev_i32_e32 v9, 31, v1
	v_mov_b32_e32 v10, v50
	v_mov_b32_e32 v11, v58
	v_mad_u64_u32 v[2:3], s[6:7], s2, v1, 0
	v_mov_b32_e32 v8, v3
	v_mad_u64_u32 v[8:9], s[6:7], s2, v9, v[8:9]
	v_cndmask_b32_e64 v0, 1.0, v0, s[4:5]
	v_mov_b32_e32 v3, v8
	v_mov_b32_e32 v8, v54
	v_mov_b32_e32 v9, v62
	v_pk_mul_f32 v[8:9], v[8:9], v[0:1] op_sel_hi:[1,0]
	v_pk_mul_f32 v[0:1], v[10:11], v[0:1] op_sel_hi:[1,0]
	v_lshl_add_u64 v[2:3], v[2:3], 1, v[128:129]
	v_cvt_pk_bf16_f32 v1, v9, v1
	v_cvt_pk_bf16_f32 v0, v8, v0
	global_store_dwordx2 v[2:3], v[0:1], off
	v_add_u32_e32 v1, 0x83, v168
	v_rsq_f32_e32 v0, v145
	v_ashrrev_i32_e32 v9, 31, v1
	v_mov_b32_e32 v10, v51
	v_mov_b32_e32 v11, v59
	v_mad_u64_u32 v[2:3], s[6:7], s2, v1, 0
	v_mov_b32_e32 v8, v3
	v_mad_u64_u32 v[8:9], s[6:7], s2, v9, v[8:9]
	v_cndmask_b32_e64 v0, 1.0, v0, s[4:5]
	v_mov_b32_e32 v3, v8
	v_mov_b32_e32 v8, v55
	v_mov_b32_e32 v9, v63
	v_pk_mul_f32 v[8:9], v[8:9], v[0:1] op_sel_hi:[1,0]
	v_pk_mul_f32 v[0:1], v[10:11], v[0:1] op_sel_hi:[1,0]
	v_lshl_add_u64 v[2:3], v[2:3], 1, v[128:129]
	v_cvt_pk_bf16_f32 v1, v9, v1
	v_cvt_pk_bf16_f32 v0, v8, v0
	global_store_dwordx2 v[2:3], v[0:1], off
	v_add_u32_e32 v148, 0x90, v168
	v_rsq_f32_e32 v0, v144
	v_mad_u64_u32 v[2:3], s[6:7], s2, v148, 0
	v_mov_b32_e32 v8, v3
	v_ashrrev_i32_e32 v1, 31, v148
	v_mad_u64_u32 v[8:9], s[6:7], s2, v1, v[8:9]
; __device__ __forceinline__ u16 f2bf(float f) {
;   u32 u = __float_as_uint(f);
;   u += 0x7fffu + ((u >> 16) & 1u);
;   return (u16)(u >> 16);
; }
; __device__ __forceinline__ float bf2f(u16 h) { return __uint_as_float(((u32)h) << 16); }
; __device__ __forceinline__ float bflo(u32 w) { return __uint_as_float(w << 16); }
; __device__ __forceinline__ float bfhi(u32 w) { return __uint_as_float(w & 0xffff0000u); }
; __device__ __forceinline__ u32 pack2(float a, float b) { return (u32)f2bf(a) | ((u32)f2bf(b) << 16); }
; __device__ __forceinline__ void gemm_tile(const GemmArgs& ga, int wgid, int next_wgid, bool prefetched, u16* shm, unsigned char* ws, int wv_) {
;     ...
;   } else if (epi == EPI_Z || epi == EPI_PP) {
;     const int ldo = (epi == EPI_Z || ga.ldo) ? ga.ldo : D_;
;     float sc[2][4][4];
;     _Pragma("unroll") for (int ai = 0; ai < 2; ++ai)
;       _Pragma("unroll") for (int m = 0; m < 4; ++m)
;         _Pragma("unroll") for (int j = 0; j < 4; ++j) sc[ai][m][j] = (epi == EPI_Z) ? e_ss[rbase + ai * HALF + m * 16 + j] : 0.f;
;     _Pragma("unroll") for (int ai = 0; ai < 2; ++ai)
;       _Pragma("unroll") for (int m = 0; m < 4; ++m)
;         _Pragma("unroll") for (int j = 0; j < 4; ++j) {
;           int row = rbase + ai * HALF + m * 16 + j;
;           float s = (epi == EPI_Z) ? rsqrtf(sc[ai][m][j] * (1.f / D_) + 1e-6f) : 1.f;
;           *(uint2*)(e_outb + (size_t)row * ldo + bcol + lc4) =
;               make_uint2(pack2(acc[ai][0][m][0][j] * s, acc[ai][0][m][1][j] * s), pack2(acc[ai][1][m][0][j] * s, acc[ai][1][m][1][j] * s));
;         }
	v_cndmask_b32_e64 v0, 1.0, v0, s[4:5]
	v_mov_b32_e32 v3, v8
	v_mov_b32_e32 v8, v36
	v_mov_b32_e32 v9, v44
	v_pk_mul_f32 v[8:9], v[8:9], v[0:1] op_sel_hi:[1,0]
	v_mov_b32_e32 v10, v32
	v_mov_b32_e32 v11, v40
	v_pk_mul_f32 v[0:1], v[10:11], v[0:1] op_sel_hi:[1,0]
	v_lshl_add_u64 v[2:3], v[2:3], 1, v[128:129]
	v_cvt_pk_bf16_f32 v1, v9, v1
	v_cvt_pk_bf16_f32 v0, v8, v0
	global_store_dwordx2 v[2:3], v[0:1], off
	v_add_u32_e32 v1, 0x91, v168
	v_rsq_f32_e32 v0, v143
	v_ashrrev_i32_e32 v9, 31, v1
	v_mov_b32_e32 v10, v33
	v_mov_b32_e32 v11, v41
	v_mad_u64_u32 v[2:3], s[6:7], s2, v1, 0
	v_mov_b32_e32 v8, v3
	v_mad_u64_u32 v[8:9], s[6:7], s2, v9, v[8:9]
	v_cndmask_b32_e64 v0, 1.0, v0, s[4:5]
	v_mov_b32_e32 v3, v8
	v_mov_b32_e32 v8, v37
	v_mov_b32_e32 v9, v45
	v_pk_mul_f32 v[8:9], v[8:9], v[0:1] op_sel_hi:[1,0]
	v_pk_mul_f32 v[0:1], v[10:11], v[0:1] op_sel_hi:[1,0]
	v_lshl_add_u64 v[2:3], v[2:3], 1, v[128:129]
	v_cvt_pk_bf16_f32 v1, v9, v1
	v_cvt_pk_bf16_f32 v0, v8, v0
	global_store_dwordx2 v[2:3], v[0:1], off
	v_add_u32_e32 v1, 0x92, v168
	v_rsq_f32_e32 v0, v141
	v_ashrrev_i32_e32 v9, 31, v1
	v_mov_b32_e32 v10, v34
	v_mov_b32_e32 v11, v42
	v_mad_u64_u32 v[2:3], s[6:7], s2, v1, 0
	v_mov_b32_e32 v8, v3
	v_mad_u64_u32 v[8:9], s[6:7], s2, v9, v[8:9]
	v_cndmask_b32_e64 v0, 1.0, v0, s[4:5]
	v_mov_b32_e32 v3, v8
	v_mov_b32_e32 v8, v38
	v_mov_b32_e32 v9, v46
	v_pk_mul_f32 v[8:9], v[8:9], v[0:1] op_sel_hi:[1,0]
	v_pk_mul_f32 v[0:1], v[10:11], v[0:1] op_sel_hi:[1,0]
	v_lshl_add_u64 v[2:3], v[2:3], 1, v[128:129]
	v_cvt_pk_bf16_f32 v1, v9, v1
	v_cvt_pk_bf16_f32 v0, v8, v0
	global_store_dwordx2 v[2:3], v[0:1], off
	v_add_u32_e32 v1, 0x93, v168
	v_rsq_f32_e32 v0, v140
	v_ashrrev_i32_e32 v9, 31, v1
	v_mov_b32_e32 v10, v35
	v_mov_b32_e32 v11, v43
	v_mad_u64_u32 v[2:3], s[6:7], s2, v1, 0
	v_mov_b32_e32 v8, v3
	v_mad_u64_u32 v[8:9], s[6:7], s2, v9, v[8:9]
	v_cndmask_b32_e64 v0, 1.0, v0, s[4:5]
	v_mov_b32_e32 v3, v8
	v_mov_b32_e32 v8, v39
	v_mov_b32_e32 v9, v47
	v_pk_mul_f32 v[8:9], v[8:9], v[0:1] op_sel_hi:[1,0]
	v_pk_mul_f32 v[0:1], v[10:11], v[0:1] op_sel_hi:[1,0]
	v_lshl_add_u64 v[2:3], v[2:3], 1, v[128:129]
	v_cvt_pk_bf16_f32 v1, v9, v1
	v_cvt_pk_bf16_f32 v0, v8, v0
	global_store_dwordx2 v[2:3], v[0:1], off
	v_add_u32_e32 v142, 0xa0, v168
	v_rsq_f32_e32 v0, v139
	v_mad_u64_u32 v[2:3], s[6:7], s2, v142, 0
	v_mov_b32_e32 v8, v3
	v_ashrrev_i32_e32 v1, 31, v142
	v_mad_u64_u32 v[8:9], s[6:7], s2, v1, v[8:9]
	v_cndmask_b32_e64 v0, 1.0, v0, s[4:5]
	v_mov_b32_e32 v3, v8
	v_mov_b32_e32 v8, v20
	v_mov_b32_e32 v9, v244
	v_pk_mul_f32 v[8:9], v[8:9], v[0:1] op_sel_hi:[1,0]
	v_mov_b32_e32 v10, v240
	v_mov_b32_e32 v11, v24
	v_pk_mul_f32 v[0:1], v[10:11], v[0:1] op_sel_hi:[1,0]
	v_lshl_add_u64 v[2:3], v[2:3], 1, v[128:129]
	v_cvt_pk_bf16_f32 v1, v9, v1
	v_cvt_pk_bf16_f32 v0, v8, v0
	global_store_dwordx2 v[2:3], v[0:1], off
	v_add_u32_e32 v1, 0xa1, v168
	v_rsq_f32_e32 v0, v138
	v_ashrrev_i32_e32 v9, 31, v1
	v_mov_b32_e32 v10, v241
	v_mov_b32_e32 v11, v25
	v_mad_u64_u32 v[2:3], s[6:7], s2, v1, 0
	v_mov_b32_e32 v8, v3
	v_mad_u64_u32 v[8:9], s[6:7], s2, v9, v[8:9]
	v_cndmask_b32_e64 v0, 1.0, v0, s[4:5]
	v_mov_b32_e32 v3, v8
	v_mov_b32_e32 v8, v21
	v_mov_b32_e32 v9, v245
	v_pk_mul_f32 v[8:9], v[8:9], v[0:1] op_sel_hi:[1,0]
	v_pk_mul_f32 v[0:1], v[10:11], v[0:1] op_sel_hi:[1,0]
	v_lshl_add_u64 v[2:3], v[2:3], 1, v[128:129]
	v_cvt_pk_bf16_f32 v1, v9, v1
	v_cvt_pk_bf16_f32 v0, v8, v0
	global_store_dwordx2 v[2:3], v[0:1], off
	v_add_u32_e32 v1, 0xa2, v168
	v_rsq_f32_e32 v0, v137
	v_ashrrev_i32_e32 v9, 31, v1
	v_mov_b32_e32 v10, v242
	v_mov_b32_e32 v11, v26
	v_mad_u64_u32 v[2:3], s[6:7], s2, v1, 0
	v_mov_b32_e32 v8, v3
	v_mad_u64_u32 v[8:9], s[6:7], s2, v9, v[8:9]
	v_cndmask_b32_e64 v0, 1.0, v0, s[4:5]
	v_mov_b32_e32 v3, v8
	v_mov_b32_e32 v8, v22
	v_mov_b32_e32 v9, v246
	v_pk_mul_f32 v[8:9], v[8:9], v[0:1] op_sel_hi:[1,0]
	v_pk_mul_f32 v[0:1], v[10:11], v[0:1] op_sel_hi:[1,0]
; __device__ __forceinline__ u16 f2bf(float f) {
;   u32 u = __float_as_uint(f);
;   u += 0x7fffu + ((u >> 16) & 1u);
;   return (u16)(u >> 16);
; }
; __device__ __forceinline__ float bf2f(u16 h) { return __uint_as_float(((u32)h) << 16); }
; __device__ __forceinline__ float bflo(u32 w) { return __uint_as_float(w << 16); }
; __device__ __forceinline__ float bfhi(u32 w) { return __uint_as_float(w & 0xffff0000u); }
; __device__ __forceinline__ u32 pack2(float a, float b) { return (u32)f2bf(a) | ((u32)f2bf(b) << 16); }
; __device__ __forceinline__ void gemm_tile(const GemmArgs& ga, int wgid, int next_wgid, bool prefetched, u16* shm, unsigned char* ws, int wv_) {
;     ...
;   } else if (epi == EPI_Z || epi == EPI_PP) {
;     const int ldo = (epi == EPI_Z || ga.ldo) ? ga.ldo : D_;
;     float sc[2][4][4];
;     _Pragma("unroll") for (int ai = 0; ai < 2; ++ai)
;       _Pragma("unroll") for (int m = 0; m < 4; ++m)
;         _Pragma("unroll") for (int j = 0; j < 4; ++j) sc[ai][m][j] = (epi == EPI_Z) ? e_ss[rbase + ai * HALF + m * 16 + j] : 0.f;
;     _Pragma("unroll") for (int ai = 0; ai < 2; ++ai)
;       _Pragma("unroll") for (int m = 0; m < 4; ++m)
;         _Pragma("unroll") for (int j = 0; j < 4; ++j) {
;           int row = rbase + ai * HALF + m * 16 + j;
;           float s = (epi == EPI_Z) ? rsqrtf(sc[ai][m][j] * (1.f / D_) + 1e-6f) : 1.f;
;           *(uint2*)(e_outb + (size_t)row * ldo + bcol + lc4) =
;               make_uint2(pack2(acc[ai][0][m][0][j] * s, acc[ai][0][m][1][j] * s), pack2(acc[ai][1][m][0][j] * s, acc[ai][1][m][1][j] * s));
;         }
	v_lshl_add_u64 v[2:3], v[2:3], 1, v[128:129]
	v_cvt_pk_bf16_f32 v1, v9, v1
	v_cvt_pk_bf16_f32 v0, v8, v0
	global_store_dwordx2 v[2:3], v[0:1], off
	v_add_u32_e32 v1, 0xa3, v168
	v_rsq_f32_e32 v0, v135
	v_ashrrev_i32_e32 v9, 31, v1
	v_mov_b32_e32 v10, v243
	v_mov_b32_e32 v11, v27
	v_mad_u64_u32 v[2:3], s[6:7], s2, v1, 0
	v_mov_b32_e32 v8, v3
	v_mad_u64_u32 v[8:9], s[6:7], s2, v9, v[8:9]
	v_cndmask_b32_e64 v0, 1.0, v0, s[4:5]
	v_mov_b32_e32 v3, v8
	v_mov_b32_e32 v8, v23
	v_mov_b32_e32 v9, v247
	v_pk_mul_f32 v[8:9], v[8:9], v[0:1] op_sel_hi:[1,0]
	v_pk_mul_f32 v[0:1], v[10:11], v[0:1] op_sel_hi:[1,0]
	v_lshl_add_u64 v[2:3], v[2:3], 1, v[128:129]
	v_cvt_pk_bf16_f32 v1, v9, v1
	v_cvt_pk_bf16_f32 v0, v8, v0
	global_store_dwordx2 v[2:3], v[0:1], off
	v_add_u32_e32 v136, 0xb0, v168
	v_rsq_f32_e32 v0, v133
	v_mad_u64_u32 v[2:3], s[6:7], s2, v136, 0
	v_mov_b32_e32 v8, v3
	v_ashrrev_i32_e32 v1, 31, v136
	v_mad_u64_u32 v[8:9], s[6:7], s2, v1, v[8:9]
	v_cndmask_b32_e64 v0, 1.0, v0, s[4:5]
	v_mov_b32_e32 v3, v8
	v_mov_b32_e32 v8, v204
	v_mov_b32_e32 v9, v12
	v_pk_mul_f32 v[8:9], v[8:9], v[0:1] op_sel_hi:[1,0]
	v_mov_b32_e32 v10, v182
	v_mov_b32_e32 v11, v4
	v_pk_mul_f32 v[0:1], v[10:11], v[0:1] op_sel_hi:[1,0]
	v_lshl_add_u64 v[2:3], v[2:3], 1, v[128:129]
	v_cvt_pk_bf16_f32 v1, v9, v1
	v_cvt_pk_bf16_f32 v0, v8, v0
	global_store_dwordx2 v[2:3], v[0:1], off
	v_add_u32_e32 v1, 0xb1, v168
	v_rsq_f32_e32 v0, v132
	v_ashrrev_i32_e32 v9, 31, v1
	v_mov_b32_e32 v10, v183
	v_mov_b32_e32 v11, v5
	v_mad_u64_u32 v[2:3], s[6:7], s2, v1, 0
	v_mov_b32_e32 v8, v3
	v_mad_u64_u32 v[8:9], s[6:7], s2, v9, v[8:9]
	v_cndmask_b32_e64 v0, 1.0, v0, s[4:5]
	v_mov_b32_e32 v3, v8
	v_mov_b32_e32 v8, v205
	v_mov_b32_e32 v9, v13
	v_pk_mul_f32 v[8:9], v[8:9], v[0:1] op_sel_hi:[1,0]
	v_pk_mul_f32 v[0:1], v[10:11], v[0:1] op_sel_hi:[1,0]
	v_lshl_add_u64 v[2:3], v[2:3], 1, v[128:129]
	v_cvt_pk_bf16_f32 v1, v9, v1
	v_cvt_pk_bf16_f32 v0, v8, v0
	global_store_dwordx2 v[2:3], v[0:1], off
	v_add_u32_e32 v1, 0xb2, v168
	v_rsq_f32_e32 v0, v131
	v_ashrrev_i32_e32 v9, 31, v1
	v_mov_b32_e32 v10, v184
	v_mov_b32_e32 v11, v6
	v_mad_u64_u32 v[2:3], s[6:7], s2, v1, 0
	v_mov_b32_e32 v8, v3
	v_mad_u64_u32 v[8:9], s[6:7], s2, v9, v[8:9]
	v_cndmask_b32_e64 v0, 1.0, v0, s[4:5]
	v_mov_b32_e32 v3, v8
	v_mov_b32_e32 v8, v206
	v_mov_b32_e32 v9, v14
	v_pk_mul_f32 v[8:9], v[8:9], v[0:1] op_sel_hi:[1,0]
	v_pk_mul_f32 v[0:1], v[10:11], v[0:1] op_sel_hi:[1,0]
	v_lshl_add_u64 v[2:3], v[2:3], 1, v[128:129]
	v_cvt_pk_bf16_f32 v1, v9, v1
	v_cvt_pk_bf16_f32 v0, v8, v0
	global_store_dwordx2 v[2:3], v[0:1], off
	v_add_u32_e32 v1, 0xb3, v168
	v_rsq_f32_e32 v0, v130
	v_ashrrev_i32_e32 v9, 31, v1
	v_mov_b32_e32 v10, v185
	v_mov_b32_e32 v11, v7
	v_mad_u64_u32 v[2:3], s[6:7], s2, v1, 0
	v_mov_b32_e32 v8, v3
	v_mad_u64_u32 v[8:9], s[2:3], s2, v9, v[8:9]
	v_cndmask_b32_e64 v0, 1.0, v0, s[4:5]
	v_mov_b32_e32 v3, v8
	v_mov_b32_e32 v8, v207
	v_mov_b32_e32 v9, v15
	v_pk_mul_f32 v[8:9], v[8:9], v[0:1] op_sel_hi:[1,0]
	v_pk_mul_f32 v[0:1], v[10:11], v[0:1] op_sel_hi:[1,0]
	v_and_b32_sdwa v10, v9, v177 dst_sel:DWORD dst_unused:UNUSED_PAD src0_sel:WORD_1 src1_sel:DWORD
	v_and_b32_sdwa v11, v8, v177 dst_sel:DWORD dst_unused:UNUSED_PAD src0_sel:WORD_1 src1_sel:DWORD
	v_add3_u32 v8, v8, v11, s48
	v_add3_u32 v9, v9, v10, s48
	v_and_b32_sdwa v10, v1, v177 dst_sel:DWORD dst_unused:UNUSED_PAD src0_sel:WORD_1 src1_sel:DWORD
	v_and_b32_sdwa v11, v0, v177 dst_sel:DWORD dst_unused:UNUSED_PAD src0_sel:WORD_1 src1_sel:DWORD
	v_add3_u32 v1, v1, v10, s48
	v_add3_u32 v0, v0, v11, s48
	v_and_b32_e32 v1, 0xffff0000, v1
	v_and_b32_e32 v0, 0xffff0000, v0
	v_lshl_add_u64 v[2:3], v[2:3], 1, v[128:129]
	v_or_b32_sdwa v1, v1, v9 dst_sel:DWORD dst_unused:UNUSED_PAD src0_sel:DWORD src1_sel:WORD_1
	v_or_b32_sdwa v0, v0, v8 dst_sel:DWORD dst_unused:UNUSED_PAD src0_sel:DWORD src1_sel:WORD_1
	global_store_dwordx2 v[2:3], v[0:1], off
	s_branch .LBB0_1052

; __device__ __forceinline__ float bflo(u32 w) { return __uint_as_float(w << 16); }
; __device__ __forceinline__ float bfhi(u32 w) { return __uint_as_float(w & 0xffff0000u); }
; __device__ __forceinline__ u32 pack2(float a, float b) { return (u32)f2bf(a) | ((u32)f2bf(b) << 16); }
; __device__ __forceinline__ float sigmoidf_(float x) { return __builtin_amdgcn_rcpf(1.f + __expf(-x)); }
; __device__ __forceinline__ void gemm_tile(const GemmArgs& ga, int wgid, int next_wgid, bool prefetched, u16* shm, unsigned char* ws, int wv_) {
;     ...
;       if (!GATE) { EPI_LOADS(0, 0) }
;       _Pragma("unroll") for (int bb = 0; bb < 8; ++bb) {
;         const int ai = bb >> 2, m = bb & 3;
;         const int cur = GATE ? 0 : (bb & 1);
;         if (GATE) { EPI_LOADS(bb, 0) }
;         else if (bb < 7) { EPI_LOADS(bb + 1, (bb + 1) & 1) }
;         _Pragma("unroll") for (int j = 0; j < 4; ++j) {
;           int row = rbase + ai * HALF + m * 16 + j;
;           unsigned eo = (unsigned)row * (unsigned)D_ + (unsigned)col0;
;           float s = 1.f;
;           if (GATE) s = rsqrtf(sc[j] * (1.f / D_) + 1e-6f);
;           const float a0 = acc[ai][0][m][0][j], a1 = acc[ai][0][m][1][j], a2 = acc[ai][1][m][0][j], a3 = acc[ai][1][m][1][j];
;           float4 xv = xin[cur][j];
;           if (GATE) {
;             xv.x += ga.live * (bflo(pin[j].x) * sigmoidf_(a0 * s));
;             xv.y += ga.live * (bfhi(pin[j].x) * sigmoidf_(a1 * s));
;             xv.z += ga.live * (bflo(pin[j].y) * sigmoidf_(a2 * s));
;             xv.w += ga.live * (bfhi(pin[j].y) * sigmoidf_(a3 * s));
;           } else {
;             const float al = ga.live * ga.alpha;
;             xv.x += al * a0; xv.y += al * a1; xv.z += al * a2; xv.w += al * a3;
;           }
;           *(float4*)(const_cast<char*>(xb) + (size_t)(eo * 4u)) = xv;
;           if (e_gn) *(uint2*)(ob + (size_t)(eo * 2u)) = make_uint2(pack2(xv.x * gn4.x, xv.y * gn4.y), pack2(xv.z * gn4.z, xv.w * gn4.w));
;           float sq = xv.x * xv.x + xv.y * xv.y + xv.z * xv.z + xv.w * xv.w;
;           sq = red16(sq);
.LBB0_1130:
	v_readlane_b32 s8, v254, 61
	v_readlane_b32 s9, v254, 62
	s_add_u32 s8, s22, s8
	s_addc_u32 s9, s23, s9
	v_readlane_b32 s12, v254, 43
	v_writelane_b32 v255, s8, 6
	v_readlane_b32 s13, v254, 44
	v_lshlrev_b32_e32 v190, 11, v168
	v_cndmask_b32_e64 v0, 0, 1, s[6:7]
	v_writelane_b32 v255, s9, 7
	s_mov_b64 s[8:9], -1
	s_and_b64 vcc, exec, s[12:13]
	v_add_u32_e32 v173, v190, v172
	v_cmp_ne_u32_e64 s[6:7], 1, v0
	s_cbranch_vccz .LBB0_1196
	v_ashrrev_i32_e32 v169, 31, v168
	v_lshlrev_b32_e32 v28, 2, v173
	v_lshl_add_u64 v[146:147], v[168:169], 2, s[68:69]
	s_waitcnt lgkmcnt(0)
	global_load_dwordx4 v[0:3], v28, s[78:79]
	global_load_dwordx4 v[134:137], v[146:147], off
	s_add_u32 s8, s14, 0x29140000
	v_add_u32_e32 v10, 0x800, v173
	v_lshlrev_b32_e32 v166, 1, v173
	s_addc_u32 s9, s15, 0
	v_add_u32_e32 v11, 0x1000, v173
	v_add_u32_e32 v16, 0x1800, v173
	v_lshlrev_b32_e32 v17, 2, v10
	global_load_dwordx2 v[8:9], v166, s[8:9]
	v_lshlrev_b32_e32 v10, 1, v10
	v_lshlrev_b32_e32 v18, 2, v11
	v_lshlrev_b32_e32 v11, 1, v11
	v_lshlrev_b32_e32 v19, 2, v16
	v_lshlrev_b32_e32 v16, 1, v16
	global_load_dwordx4 v[142:145], v17, s[78:79]
	global_load_dwordx2 v[152:153], v10, s[8:9]
	global_load_dwordx4 v[138:141], v18, s[78:79]
	global_load_dwordx2 v[150:151], v11, s[8:9]
	global_load_dwordx4 v[130:133], v19, s[78:79]
	global_load_dwordx2 v[148:149], v16, s[8:9]
	s_waitcnt vmcnt(0)
	v_mov_b32_e32 v10, v0
	v_fmamk_f32 v0, v134, 0x3a000000, v175
	v_mov_b32_e32 v11, v2
	s_nop 1
	v_rsq_f32_e32 v16, v0
	v_mov_b32_e32 v2, v1
	v_lshlrev_b32_e32 v1, 16, v9
	v_lshlrev_b32_e32 v0, 16, v8
	v_mul_f32_e32 v17, v116, v16
	v_mul_f32_e32 v18, v112, v16
	v_mul_f32_e32 v19, v124, v16
	v_mul_f32_e32 v16, v120, v16
	v_mul_f32_e32 v17, 0xbfb8aa3b, v17
	v_mul_f32_e32 v18, 0xbfb8aa3b, v18
	v_mul_f32_e32 v19, 0xbfb8aa3b, v19
	v_mul_f32_e32 v16, 0xbfb8aa3b, v16
	v_exp_f32_e32 v17, v17
	v_exp_f32_e32 v18, v18
	v_exp_f32_e32 v19, v19
	v_exp_f32_e32 v16, v16
	v_add_f32_e32 v17, 1.0, v17
	v_add_f32_e32 v18, 1.0, v18
	v_add_f32_e32 v19, 1.0, v19
	v_add_f32_e32 v29, 1.0, v16
	v_rcp_f32_e32 v16, v17
	v_rcp_f32_e32 v18, v18
	v_rcp_f32_e32 v17, v19
	v_rcp_f32_e32 v19, v29
	v_and_b32_e32 v9, 0xffff0000, v9
	v_and_b32_e32 v8, 0xffff0000, v8
	v_pk_fma_f32 v[154:155], v[16:17], v[0:1], v[10:11]
	v_pk_fma_f32 v[156:157], v[18:19], v[8:9], v[2:3]
	v_mov_b32_e32 v0, v154
	v_mov_b32_e32 v1, v156
	v_mov_b32_e32 v2, v155
	v_mov_b32_e32 v3, v157
	s_and_b64 vcc, exec, s[6:7]
	global_store_dwordx4 v28, v[0:3], s[2:3]
	s_cbranch_vccnz .LBB0_1133
	s_nop 0
	v_pk_mul_f32 v[0:1], v[128:129], v[154:155]
	v_pk_mul_f32 v[2:3], v[170:171], v[156:157]
	v_lshl_add_u64 v[8:9], s[90:91], 0, v[166:167]
	v_cvt_pk_bf16_f32 v1, v1, v3
	v_cvt_pk_bf16_f32 v0, v0, v2
	global_store_dwordx2 v[8:9], v[0:1], off
.LBB0_1133:
	s_nop 0
	v_pk_mul_f32 v[0:1], v[154:155], v[154:155]
	v_pk_mul_f32 v[2:3], v[156:157], v[156:157]
	v_lshlrev_b32_e32 v9, 16, v153
	v_add_f32_e32 v0, v0, v2
	v_add_f32_e32 v0, v1, v0
	v_fmamk_f32 v1, v135, 0x3a000000, v175
	v_mul_f32_e32 v2, 0x4b800000, v1
	v_cmp_gt_f32_e32 vcc, s93, v1
	v_add_f32_e32 v0, v3, v0
	v_mov_b32_e32 v10, v142
	v_cndmask_b32_e32 v1, v1, v2, vcc
	v_rsq_f32_e32 v1, v1
	v_add_f32_dpp v0, v0, v0 quad_perm:[1,0,3,2] row_mask:0xf bank_mask:0xf bound_ctrl:1
	v_mov_b32_e32 v11, v144
	v_mov_b32_e32 v144, v143
	v_add_f32_dpp v0, v0, v0 quad_perm:[2,3,0,1] row_mask:0xf bank_mask:0xf bound_ctrl:1
	v_add3_u32 v154, v172, v190, s72
	s_nop 0
	v_add_f32_dpp v158, v0, v0 row_half_mirror row_mask:0xf bank_mask:0xf bound_ctrl:1
	v_mul_f32_e32 v0, 0x45800000, v1
	v_cndmask_b32_e32 v1, v1, v0, vcc
	v_mul_f32_e32 v0, v117, v1
	v_mul_f32_e32 v3, v125, v1
	v_mul_f32_e32 v0, 0xbfb8aa3b, v0
	v_mul_f32_e32 v2, v113, v1
	v_mul_f32_e32 v3, 0xbfb8aa3b, v3
	v_mul_f32_e32 v1, v121, v1
	v_exp_f32_e32 v0, v0
	v_mul_f32_e32 v2, 0xbfb8aa3b, v2
	v_exp_f32_e32 v3, v3
	v_mul_f32_e32 v1, 0xbfb8aa3b, v1
	v_exp_f32_e32 v2, v2
	v_exp_f32_e32 v8, v1
	v_add_f32_e32 v0, 1.0, v0
	v_add_f32_e32 v1, 1.0, v3
	v_rcp_f32_e32 v0, v0
	v_add_f32_e32 v2, 1.0, v2
	v_rcp_f32_e32 v1, v1
	v_add_f32_e32 v3, 1.0, v8
	v_rcp_f32_e32 v2, v2
	v_rcp_f32_e32 v3, v3
	v_lshlrev_b32_e32 v8, 16, v152
	v_pk_fma_f32 v[134:135], v[0:1], v[8:9], v[10:11]
	v_and_b32_e32 v1, 0xffff0000, v153
	v_and_b32_e32 v0, 0xffff0000, v152
	v_pk_fma_f32 v[142:143], v[2:3], v[0:1], v[144:145]
	v_mov_b32_dpp v159, v158 row_mirror row_mask:0xf bank_mask:0xf bound_ctrl:1
	v_lshlrev_b32_e32 v8, 2, v154
	v_mov_b32_e32 v0, v134
	v_mov_b32_e32 v1, v142
	v_mov_b32_e32 v2, v135
	v_mov_b32_e32 v3, v143
	s_and_b64 vcc, exec, s[6:7]
	global_store_dwordx4 v8, v[0:3], s[2:3]
	s_cbranch_vccnz .LBB0_1135
	s_nop 0
	v_pk_mul_f32 v[0:1], v[128:129], v[134:135]
	v_pk_mul_f32 v[2:3], v[170:171], v[142:143]
	v_lshlrev_b32_e32 v8, 1, v154
	v_cvt_pk_bf16_f32 v1, v1, v3
	v_cvt_pk_bf16_f32 v0, v0, v2
	global_store_dwordx2 v8, v[0:1], s[90:91]
; __device__ __forceinline__ float bflo(u32 w) { return __uint_as_float(w << 16); }
; __device__ __forceinline__ float bfhi(u32 w) { return __uint_as_float(w & 0xffff0000u); }
; __device__ __forceinline__ u32 pack2(float a, float b) { return (u32)f2bf(a) | ((u32)f2bf(b) << 16); }
; __device__ __forceinline__ float sigmoidf_(float x) { return __builtin_amdgcn_rcpf(1.f + __expf(-x)); }
; __device__ __forceinline__ void gemm_tile(const GemmArgs& ga, int wgid, int next_wgid, bool prefetched, u16* shm, unsigned char* ws, int wv_) {
;     ...
;       if (!GATE) { EPI_LOADS(0, 0) }
;       _Pragma("unroll") for (int bb = 0; bb < 8; ++bb) {
;         const int ai = bb >> 2, m = bb & 3;
;         const int cur = GATE ? 0 : (bb & 1);
;         if (GATE) { EPI_LOADS(bb, 0) }
;         else if (bb < 7) { EPI_LOADS(bb + 1, (bb + 1) & 1) }
;         _Pragma("unroll") for (int j = 0; j < 4; ++j) {
;           int row = rbase + ai * HALF + m * 16 + j;
;           unsigned eo = (unsigned)row * (unsigned)D_ + (unsigned)col0;
;           float s = 1.f;
;           if (GATE) s = rsqrtf(sc[j] * (1.f / D_) + 1e-6f);
;           const float a0 = acc[ai][0][m][0][j], a1 = acc[ai][0][m][1][j], a2 = acc[ai][1][m][0][j], a3 = acc[ai][1][m][1][j];
;           float4 xv = xin[cur][j];
;           if (GATE) {
;             xv.x += ga.live * (bflo(pin[j].x) * sigmoidf_(a0 * s));
;             xv.y += ga.live * (bfhi(pin[j].x) * sigmoidf_(a1 * s));
;             xv.z += ga.live * (bflo(pin[j].y) * sigmoidf_(a2 * s));
;             xv.w += ga.live * (bfhi(pin[j].y) * sigmoidf_(a3 * s));
;           } else {
;             const float al = ga.live * ga.alpha;
;             xv.x += al * a0; xv.y += al * a1; xv.z += al * a2; xv.w += al * a3;
;           }
;           *(float4*)(const_cast<char*>(xb) + (size_t)(eo * 4u)) = xv;
;           if (e_gn) *(uint2*)(ob + (size_t)(eo * 2u)) = make_uint2(pack2(xv.x * gn4.x, xv.y * gn4.y), pack2(xv.z * gn4.z, xv.w * gn4.w));
;           float sq = xv.x * xv.x + xv.y * xv.y + xv.z * xv.z + xv.w * xv.w;
;           sq = red16(sq);
.LBB0_1135:
	s_nop 0
	v_pk_mul_f32 v[0:1], v[134:135], v[134:135]
	v_pk_mul_f32 v[2:3], v[142:143], v[142:143]
	v_lshlrev_b32_e32 v9, 16, v151
	v_add_f32_e32 v0, v0, v2
	v_add_f32_e32 v0, v1, v0
	v_fmamk_f32 v1, v136, 0x3a000000, v175
	v_mul_f32_e32 v2, 0x4b800000, v1
	v_cmp_gt_f32_e32 vcc, s93, v1
	v_add_f32_e32 v0, v3, v0
	v_mov_b32_e32 v10, v138
	v_cndmask_b32_e32 v1, v1, v2, vcc
	v_rsq_f32_e32 v1, v1
	v_add_f32_dpp v0, v0, v0 quad_perm:[1,0,3,2] row_mask:0xf bank_mask:0xf bound_ctrl:1
	v_mov_b32_e32 v11, v140
	s_movk_i32 s12, 0x1000
	v_add_f32_dpp v0, v0, v0 quad_perm:[2,3,0,1] row_mask:0xf bank_mask:0xf bound_ctrl:1
	v_mov_b32_e32 v140, v139
	v_add3_u32 v136, v172, v190, s12
	v_add_f32_dpp v160, v0, v0 row_half_mirror row_mask:0xf bank_mask:0xf bound_ctrl:1
	v_mul_f32_e32 v0, 0x45800000, v1
	v_cndmask_b32_e32 v1, v1, v0, vcc
	v_mul_f32_e32 v0, v118, v1
	v_mul_f32_e32 v3, v126, v1
	v_mul_f32_e32 v0, 0xbfb8aa3b, v0
	v_mul_f32_e32 v2, v114, v1
	v_mul_f32_e32 v3, 0xbfb8aa3b, v3
	v_mul_f32_e32 v1, v122, v1
	v_exp_f32_e32 v0, v0
	v_mul_f32_e32 v2, 0xbfb8aa3b, v2
	v_exp_f32_e32 v3, v3
	v_mul_f32_e32 v1, 0xbfb8aa3b, v1
	v_exp_f32_e32 v2, v2
	v_exp_f32_e32 v8, v1
	v_add_f32_e32 v0, 1.0, v0
	v_add_f32_e32 v1, 1.0, v3
	v_rcp_f32_e32 v0, v0
	v_add_f32_e32 v2, 1.0, v2
	v_rcp_f32_e32 v1, v1
	v_add_f32_e32 v3, 1.0, v8
	v_rcp_f32_e32 v2, v2
	v_rcp_f32_e32 v3, v3
	v_lshlrev_b32_e32 v8, 16, v150
	v_pk_fma_f32 v[134:135], v[0:1], v[8:9], v[10:11]
	v_and_b32_e32 v1, 0xffff0000, v151
	v_and_b32_e32 v0, 0xffff0000, v150
	v_pk_fma_f32 v[138:139], v[2:3], v[0:1], v[140:141]
	v_mov_b32_dpp v161, v160 row_mirror row_mask:0xf bank_mask:0xf bound_ctrl:1
	v_lshlrev_b32_e32 v8, 2, v136
	v_mov_b32_e32 v0, v134
	v_mov_b32_e32 v1, v138
	v_mov_b32_e32 v2, v135
	v_mov_b32_e32 v3, v139
	s_and_b64 vcc, exec, s[6:7]
	global_store_dwordx4 v8, v[0:3], s[2:3]
	s_cbranch_vccnz .LBB0_1137
	s_nop 0
	v_pk_mul_f32 v[0:1], v[128:129], v[134:135]
	v_pk_mul_f32 v[2:3], v[170:171], v[138:139]
	v_lshlrev_b32_e32 v8, 1, v136
	v_cvt_pk_bf16_f32 v1, v1, v3
	v_cvt_pk_bf16_f32 v0, v0, v2
	global_store_dwordx2 v8, v[0:1], s[90:91]
.LBB0_1137:
	s_nop 0
	v_pk_mul_f32 v[0:1], v[134:135], v[134:135]
	v_pk_mul_f32 v[2:3], v[138:139], v[138:139]
	v_lshlrev_b32_e32 v9, 16, v149
	v_add_f32_e32 v0, v0, v2
	v_add_f32_e32 v0, v1, v0
	v_fmamk_f32 v1, v137, 0x3a000000, v175
	v_mul_f32_e32 v2, 0x4b800000, v1
	v_cmp_gt_f32_e32 vcc, s93, v1
	v_add_f32_e32 v0, v3, v0
	v_mov_b32_e32 v10, v130
	v_cndmask_b32_e32 v1, v1, v2, vcc
	v_rsq_f32_e32 v1, v1
	v_add_f32_dpp v0, v0, v0 quad_perm:[1,0,3,2] row_mask:0xf bank_mask:0xf bound_ctrl:1
	v_mov_b32_e32 v11, v132
	s_movk_i32 s12, 0x1800
	v_add_f32_dpp v0, v0, v0 quad_perm:[2,3,0,1] row_mask:0xf bank_mask:0xf bound_ctrl:1
	v_mov_b32_e32 v132, v131
	v_add3_u32 v136, v172, v190, s12
	v_add_f32_dpp v162, v0, v0 row_half_mirror row_mask:0xf bank_mask:0xf bound_ctrl:1
	v_mul_f32_e32 v0, 0x45800000, v1
	v_cndmask_b32_e32 v1, v1, v0, vcc
	v_mul_f32_e32 v0, v119, v1
	v_mul_f32_e32 v3, v127, v1
	v_mul_f32_e32 v0, 0xbfb8aa3b, v0
	v_mul_f32_e32 v2, v115, v1
	v_mul_f32_e32 v3, 0xbfb8aa3b, v3
	v_mul_f32_e32 v1, v123, v1
	v_exp_f32_e32 v0, v0
	v_mul_f32_e32 v2, 0xbfb8aa3b, v2
	v_exp_f32_e32 v3, v3
	v_mul_f32_e32 v1, 0xbfb8aa3b, v1
	v_exp_f32_e32 v2, v2
	v_exp_f32_e32 v8, v1
	v_add_f32_e32 v0, 1.0, v0
	v_add_f32_e32 v1, 1.0, v3
	v_rcp_f32_e32 v0, v0
	v_add_f32_e32 v2, 1.0, v2
	v_rcp_f32_e32 v1, v1
	v_add_f32_e32 v3, 1.0, v8
	v_rcp_f32_e32 v2, v2
	v_rcp_f32_e32 v3, v3
	v_lshlrev_b32_e32 v8, 16, v148
	v_pk_fma_f32 v[134:135], v[0:1], v[8:9], v[10:11]
	v_and_b32_e32 v1, 0xffff0000, v149
	v_and_b32_e32 v0, 0xffff0000, v148
	v_pk_fma_f32 v[130:131], v[2:3], v[0:1], v[132:133]
	v_mov_b32_dpp v163, v162 row_mirror row_mask:0xf bank_mask:0xf bound_ctrl:1
	v_lshlrev_b32_e32 v8, 2, v136
	v_mov_b32_e32 v0, v134
	v_mov_b32_e32 v1, v130
	v_mov_b32_e32 v2, v135
	v_mov_b32_e32 v3, v131
	s_and_b64 vcc, exec, s[6:7]
	global_store_dwordx4 v8, v[0:3], s[2:3]
	s_cbranch_vccnz .LBB0_1139
	s_nop 0
	v_pk_mul_f32 v[0:1], v[128:129], v[134:135]
	v_pk_mul_f32 v[2:3], v[170:171], v[130:131]
	v_and_b32_sdwa v10, v0, v177 dst_sel:DWORD dst_unused:UNUSED_PAD src0_sel:WORD_1 src1_sel:DWORD
	v_add3_u32 v0, v0, v10, s48
	v_and_b32_sdwa v10, v2, v177 dst_sel:DWORD dst_unused:UNUSED_PAD src0_sel:WORD_1 src1_sel:DWORD
	v_add3_u32 v2, v2, v10, s48
	v_and_b32_e32 v2, 0xffff0000, v2
	v_lshlrev_b32_e32 v8, 1, v136
	v_cvt_pk_bf16_f32 v1, v1, v3
	v_or_b32_sdwa v0, v2, v0 dst_sel:DWORD dst_unused:UNUSED_PAD src0_sel:DWORD src1_sel:WORD_1
	global_store_dwordx2 v8, v[0:1], s[90:91]
; __device__ __forceinline__ float bflo(u32 w) { return __uint_as_float(w << 16); }
; __device__ __forceinline__ float bfhi(u32 w) { return __uint_as_float(w & 0xffff0000u); }
; __device__ __forceinline__ u32 pack2(float a, float b) { return (u32)f2bf(a) | ((u32)f2bf(b) << 16); }
; __device__ __forceinline__ float sigmoidf_(float x) { return __builtin_amdgcn_rcpf(1.f + __expf(-x)); }
; __device__ __forceinline__ void gemm_tile(const GemmArgs& ga, int wgid, int next_wgid, bool prefetched, u16* shm, unsigned char* ws, int wv_) {
;     ...
;       if (!GATE) { EPI_LOADS(0, 0) }
;       _Pragma("unroll") for (int bb = 0; bb < 8; ++bb) {
;         const int ai = bb >> 2, m = bb & 3;
;         const int cur = GATE ? 0 : (bb & 1);
;         if (GATE) { EPI_LOADS(bb, 0) }
;         else if (bb < 7) { EPI_LOADS(bb + 1, (bb + 1) & 1) }
;         _Pragma("unroll") for (int j = 0; j < 4; ++j) {
;           int row = rbase + ai * HALF + m * 16 + j;
;           unsigned eo = (unsigned)row * (unsigned)D_ + (unsigned)col0;
;           float s = 1.f;
;           if (GATE) s = rsqrtf(sc[j] * (1.f / D_) + 1e-6f);
;           const float a0 = acc[ai][0][m][0][j], a1 = acc[ai][0][m][1][j], a2 = acc[ai][1][m][0][j], a3 = acc[ai][1][m][1][j];
;           float4 xv = xin[cur][j];
;           if (GATE) {
;             xv.x += ga.live * (bflo(pin[j].x) * sigmoidf_(a0 * s));
;             xv.y += ga.live * (bfhi(pin[j].x) * sigmoidf_(a1 * s));
;             xv.z += ga.live * (bflo(pin[j].y) * sigmoidf_(a2 * s));
;             xv.w += ga.live * (bfhi(pin[j].y) * sigmoidf_(a3 * s));
;           } else {
;             const float al = ga.live * ga.alpha;
;             xv.x += al * a0; xv.y += al * a1; xv.z += al * a2; xv.w += al * a3;
;           }
;           *(float4*)(const_cast<char*>(xb) + (size_t)(eo * 4u)) = xv;
;           if (e_gn) *(uint2*)(ob + (size_t)(eo * 2u)) = make_uint2(pack2(xv.x * gn4.x, xv.y * gn4.y), pack2(xv.z * gn4.z, xv.w * gn4.w));
;           float sq = xv.x * xv.x + xv.y * xv.y + xv.z * xv.z + xv.w * xv.w;
;           sq = red16(sq);
.LBB0_1139:
	s_nop 0
	v_pk_mul_f32 v[0:1], v[134:135], v[134:135]
	v_pk_mul_f32 v[2:3], v[130:131], v[130:131]
	s_nop 0
	v_add_f32_e32 v0, v0, v2
	v_add_f32_e32 v0, v1, v0
	v_add_f32_e32 v0, v3, v0
	s_nop 1
	v_add_f32_dpp v0, v0, v0 quad_perm:[1,0,3,2] row_mask:0xf bank_mask:0xf bound_ctrl:1
	s_nop 1
	v_add_f32_dpp v0, v0, v0 quad_perm:[2,3,0,1] row_mask:0xf bank_mask:0xf bound_ctrl:1
	s_nop 1
	v_add_f32_dpp v164, v0, v0 row_half_mirror row_mask:0xf bank_mask:0xf bound_ctrl:1
	s_nop 1
	v_mov_b32_dpp v165, v164 row_mirror row_mask:0xf bank_mask:0xf bound_ctrl:1
	global_load_dwordx4 v[130:133], v[146:147], off offset:64
	v_lshl_add_u32 v198, v168, 11, v172
	v_add_u32_e32 v0, 0x8000, v198
	v_lshlrev_b32_e32 v30, 2, v0
	v_lshlrev_b32_e32 v166, 1, v0
	global_load_dwordx4 v[0:3], v30, s[78:79]
	v_add_u32_e32 v10, 0x8800, v198
	v_add_u32_e32 v11, 0x9000, v198
	v_add_u32_e32 v16, 0x9800, v198
	v_lshlrev_b32_e32 v17, 2, v10
	global_load_dwordx2 v[8:9], v166, s[8:9]
	v_lshlrev_b32_e32 v10, 1, v10
	v_lshlrev_b32_e32 v18, 2, v11
	v_lshlrev_b32_e32 v11, 1, v11
	v_lshlrev_b32_e32 v19, 2, v16
	v_lshlrev_b32_e32 v16, 1, v16
	global_load_dwordx4 v[142:145], v17, s[78:79]
	global_load_dwordx2 v[152:153], v10, s[8:9]
	global_load_dwordx4 v[138:141], v18, s[78:79]
	global_load_dwordx2 v[150:151], v11, s[8:9]
	global_load_dwordx4 v[134:137], v19, s[78:79]
	global_load_dwordx2 v[148:149], v16, s[8:9]
	s_waitcnt vmcnt(8)
	v_fmamk_f32 v10, v130, 0x3a000000, v175
	s_waitcnt vmcnt(7)
	v_mov_b32_e32 v16, v0
	v_rsq_f32_e32 v18, v10
	v_mov_b32_e32 v17, v2
	s_waitcnt vmcnt(6)
	v_lshlrev_b32_e32 v11, 16, v9
	v_mov_b32_e32 v0, v18
	v_mul_f32_e32 v2, v100, v0
	v_mul_f32_e32 v18, v96, v0
	v_mul_f32_e32 v19, v108, v0
	v_mul_f32_e32 v0, v104, v0
	v_mul_f32_e32 v2, 0xbfb8aa3b, v2
	v_mul_f32_e32 v18, 0xbfb8aa3b, v18
	v_mul_f32_e32 v19, 0xbfb8aa3b, v19
	v_mul_f32_e32 v0, 0xbfb8aa3b, v0
	v_exp_f32_e32 v2, v2
	v_exp_f32_e32 v18, v18
	v_exp_f32_e32 v19, v19
	v_exp_f32_e32 v0, v0
	v_add_f32_e32 v2, 1.0, v2
	v_add_f32_e32 v28, 1.0, v18
	v_add_f32_e32 v19, 1.0, v19
	v_add_f32_e32 v0, 1.0, v0
	v_rcp_f32_e32 v18, v2
	v_rcp_f32_e32 v28, v28
	v_rcp_f32_e32 v19, v19
	v_rcp_f32_e32 v29, v0
	v_lshlrev_b32_e32 v10, 16, v8
	v_and_b32_e32 v9, 0xffff0000, v9
	v_and_b32_e32 v8, 0xffff0000, v8
	v_mov_b32_e32 v2, v1
	v_pk_fma_f32 v[154:155], v[18:19], v[10:11], v[16:17]
	v_pk_fma_f32 v[156:157], v[28:29], v[8:9], v[2:3]
	v_mov_b32_e32 v0, v154
	v_mov_b32_e32 v1, v156
	v_mov_b32_e32 v2, v155
	v_mov_b32_e32 v3, v157
	s_and_b64 vcc, exec, s[6:7]
	global_store_dwordx4 v30, v[0:3], s[2:3]
	s_cbranch_vccnz .LBB0_1141
	s_nop 0
	v_pk_mul_f32 v[0:1], v[128:129], v[154:155]
	v_pk_mul_f32 v[2:3], v[170:171], v[156:157]
	v_lshl_add_u64 v[8:9], s[90:91], 0, v[166:167]
	v_cvt_pk_bf16_f32 v1, v1, v3
	v_cvt_pk_bf16_f32 v0, v0, v2
	global_store_dwordx2 v[8:9], v[0:1], off
.LBB0_1141:
	s_nop 0
	v_pk_mul_f32 v[0:1], v[154:155], v[154:155]
	v_pk_mul_f32 v[2:3], v[156:157], v[156:157]
	s_waitcnt vmcnt(5)
	v_lshlrev_b32_e32 v9, 16, v153
	v_add_f32_e32 v0, v0, v2
	v_add_f32_e32 v0, v1, v0
	v_fmamk_f32 v1, v131, 0x3a000000, v175
	v_mul_f32_e32 v2, 0x4b800000, v1
	v_cmp_gt_f32_e32 vcc, s93, v1
	v_add_f32_e32 v0, v3, v0
	v_mov_b32_e32 v10, v142
	v_cndmask_b32_e32 v1, v1, v2, vcc
	v_rsq_f32_e32 v1, v1
	v_add_f32_dpp v0, v0, v0 quad_perm:[1,0,3,2] row_mask:0xf bank_mask:0xf bound_ctrl:1
	v_mov_b32_e32 v11, v144
	s_mov_b32 s12, 0x8800
	v_add_f32_dpp v0, v0, v0 quad_perm:[2,3,0,1] row_mask:0xf bank_mask:0xf bound_ctrl:1
	v_mov_b32_e32 v144, v143
	v_add3_u32 v154, v172, v190, s12
	v_add_f32_dpp v169, v0, v0 row_half_mirror row_mask:0xf bank_mask:0xf bound_ctrl:1
	v_mul_f32_e32 v0, 0x45800000, v1
	v_cndmask_b32_e32 v1, v1, v0, vcc
	v_mul_f32_e32 v0, v101, v1
	v_mul_f32_e32 v3, v109, v1
	v_mul_f32_e32 v0, 0xbfb8aa3b, v0
	v_mul_f32_e32 v2, v97, v1
	v_mul_f32_e32 v3, 0xbfb8aa3b, v3
	v_mul_f32_e32 v1, v105, v1
	v_exp_f32_e32 v0, v0
	v_mul_f32_e32 v2, 0xbfb8aa3b, v2
	v_exp_f32_e32 v3, v3
	v_mul_f32_e32 v1, 0xbfb8aa3b, v1
	v_exp_f32_e32 v2, v2
	v_exp_f32_e32 v8, v1
	v_add_f32_e32 v0, 1.0, v0
	v_add_f32_e32 v1, 1.0, v3
	v_rcp_f32_e32 v0, v0
	v_add_f32_e32 v2, 1.0, v2
	v_rcp_f32_e32 v1, v1
	v_add_f32_e32 v3, 1.0, v8
	v_rcp_f32_e32 v2, v2
	v_rcp_f32_e32 v3, v3
	v_lshlrev_b32_e32 v8, 16, v152
	v_pk_fma_f32 v[130:131], v[0:1], v[8:9], v[10:11]
	v_and_b32_e32 v1, 0xffff0000, v153
	v_and_b32_e32 v0, 0xffff0000, v152
	v_pk_fma_f32 v[142:143], v[2:3], v[0:1], v[144:145]
	v_mov_b32_dpp v191, v169 row_mirror row_mask:0xf bank_mask:0xf bound_ctrl:1
	v_lshlrev_b32_e32 v8, 2, v154
	v_mov_b32_e32 v0, v130
	v_mov_b32_e32 v1, v142
	v_mov_b32_e32 v2, v131
	v_mov_b32_e32 v3, v143
	s_and_b64 vcc, exec, s[6:7]
	global_store_dwordx4 v8, v[0:3], s[2:3]
	s_cbranch_vccnz .LBB0_1143
	s_nop 0
	v_pk_mul_f32 v[0:1], v[128:129], v[130:131]
	v_pk_mul_f32 v[2:3], v[170:171], v[142:143]
	v_lshlrev_b32_e32 v8, 1, v154
	v_cvt_pk_bf16_f32 v1, v1, v3
	v_cvt_pk_bf16_f32 v0, v0, v2
	global_store_dwordx2 v8, v[0:1], s[90:91]
; __device__ __forceinline__ float bflo(u32 w) { return __uint_as_float(w << 16); }
; __device__ __forceinline__ float bfhi(u32 w) { return __uint_as_float(w & 0xffff0000u); }
; __device__ __forceinline__ u32 pack2(float a, float b) { return (u32)f2bf(a) | ((u32)f2bf(b) << 16); }
; __device__ __forceinline__ float sigmoidf_(float x) { return __builtin_amdgcn_rcpf(1.f + __expf(-x)); }
; __device__ __forceinline__ void gemm_tile(const GemmArgs& ga, int wgid, int next_wgid, bool prefetched, u16* shm, unsigned char* ws, int wv_) {
;     ...
;       if (!GATE) { EPI_LOADS(0, 0) }
;       _Pragma("unroll") for (int bb = 0; bb < 8; ++bb) {
;         const int ai = bb >> 2, m = bb & 3;
;         const int cur = GATE ? 0 : (bb & 1);
;         if (GATE) { EPI_LOADS(bb, 0) }
;         else if (bb < 7) { EPI_LOADS(bb + 1, (bb + 1) & 1) }
;         _Pragma("unroll") for (int j = 0; j < 4; ++j) {
;           int row = rbase + ai * HALF + m * 16 + j;
;           unsigned eo = (unsigned)row * (unsigned)D_ + (unsigned)col0;
;           float s = 1.f;
;           if (GATE) s = rsqrtf(sc[j] * (1.f / D_) + 1e-6f);
;           const float a0 = acc[ai][0][m][0][j], a1 = acc[ai][0][m][1][j], a2 = acc[ai][1][m][0][j], a3 = acc[ai][1][m][1][j];
;           float4 xv = xin[cur][j];
;           if (GATE) {
;             xv.x += ga.live * (bflo(pin[j].x) * sigmoidf_(a0 * s));
;             xv.y += ga.live * (bfhi(pin[j].x) * sigmoidf_(a1 * s));
;             xv.z += ga.live * (bflo(pin[j].y) * sigmoidf_(a2 * s));
;             xv.w += ga.live * (bfhi(pin[j].y) * sigmoidf_(a3 * s));
;           } else {
;             const float al = ga.live * ga.alpha;
;             xv.x += al * a0; xv.y += al * a1; xv.z += al * a2; xv.w += al * a3;
;           }
;           *(float4*)(const_cast<char*>(xb) + (size_t)(eo * 4u)) = xv;
;           if (e_gn) *(uint2*)(ob + (size_t)(eo * 2u)) = make_uint2(pack2(xv.x * gn4.x, xv.y * gn4.y), pack2(xv.z * gn4.z, xv.w * gn4.w));
;           float sq = xv.x * xv.x + xv.y * xv.y + xv.z * xv.z + xv.w * xv.w;
;           sq = red16(sq);
.LBB0_1143:
	s_nop 0
	v_pk_mul_f32 v[0:1], v[130:131], v[130:131]
	v_pk_mul_f32 v[2:3], v[142:143], v[142:143]
	s_waitcnt vmcnt(4)
	v_lshlrev_b32_e32 v9, 16, v151
	v_add_f32_e32 v0, v0, v2
	v_add_f32_e32 v0, v1, v0
	v_fmamk_f32 v1, v132, 0x3a000000, v175
	v_mul_f32_e32 v2, 0x4b800000, v1
	v_cmp_gt_f32_e32 vcc, s93, v1
	v_add_f32_e32 v0, v3, v0
	v_mov_b32_e32 v10, v138
	v_cndmask_b32_e32 v1, v1, v2, vcc
	v_rsq_f32_e32 v1, v1
	v_add_f32_dpp v0, v0, v0 quad_perm:[1,0,3,2] row_mask:0xf bank_mask:0xf bound_ctrl:1
	v_mov_b32_e32 v11, v140
	s_mov_b32 s12, 0x9000
	v_add_f32_dpp v0, v0, v0 quad_perm:[2,3,0,1] row_mask:0xf bank_mask:0xf bound_ctrl:1
	v_mov_b32_e32 v140, v139
	v_add3_u32 v132, v172, v190, s12
	v_add_f32_dpp v192, v0, v0 row_half_mirror row_mask:0xf bank_mask:0xf bound_ctrl:1
	v_mul_f32_e32 v0, 0x45800000, v1
	v_cndmask_b32_e32 v1, v1, v0, vcc
	v_mul_f32_e32 v0, v102, v1
	v_mul_f32_e32 v3, v110, v1
	v_mul_f32_e32 v0, 0xbfb8aa3b, v0
	v_mul_f32_e32 v2, v98, v1
	v_mul_f32_e32 v3, 0xbfb8aa3b, v3
	v_mul_f32_e32 v1, v106, v1
	v_exp_f32_e32 v0, v0
	v_mul_f32_e32 v2, 0xbfb8aa3b, v2
	v_exp_f32_e32 v3, v3
	v_mul_f32_e32 v1, 0xbfb8aa3b, v1
	v_exp_f32_e32 v2, v2
	v_exp_f32_e32 v8, v1
	v_add_f32_e32 v0, 1.0, v0
	v_add_f32_e32 v1, 1.0, v3
	v_rcp_f32_e32 v0, v0
	v_add_f32_e32 v2, 1.0, v2
	v_rcp_f32_e32 v1, v1
	v_add_f32_e32 v3, 1.0, v8
	v_rcp_f32_e32 v2, v2
	v_rcp_f32_e32 v3, v3
	v_lshlrev_b32_e32 v8, 16, v150
	v_pk_fma_f32 v[130:131], v[0:1], v[8:9], v[10:11]
	v_and_b32_e32 v1, 0xffff0000, v151
	v_and_b32_e32 v0, 0xffff0000, v150
	v_pk_fma_f32 v[138:139], v[2:3], v[0:1], v[140:141]
	v_mov_b32_dpp v193, v192 row_mirror row_mask:0xf bank_mask:0xf bound_ctrl:1
	v_lshlrev_b32_e32 v8, 2, v132
	v_mov_b32_e32 v0, v130
	v_mov_b32_e32 v1, v138
	v_mov_b32_e32 v2, v131
	v_mov_b32_e32 v3, v139
	s_and_b64 vcc, exec, s[6:7]
	global_store_dwordx4 v8, v[0:3], s[2:3]
	s_cbranch_vccnz .LBB0_1145
	s_nop 0
	v_pk_mul_f32 v[0:1], v[128:129], v[130:131]
	v_pk_mul_f32 v[2:3], v[170:171], v[138:139]
	v_lshlrev_b32_e32 v8, 1, v132
	v_cvt_pk_bf16_f32 v1, v1, v3
	v_cvt_pk_bf16_f32 v0, v0, v2
	global_store_dwordx2 v8, v[0:1], s[90:91]
.LBB0_1145:
	s_nop 0
	v_pk_mul_f32 v[0:1], v[130:131], v[130:131]
	v_pk_mul_f32 v[2:3], v[138:139], v[138:139]
	s_waitcnt vmcnt(3)
	v_lshlrev_b32_e32 v9, 16, v149
	v_add_f32_e32 v0, v0, v2
	v_add_f32_e32 v0, v1, v0
	v_fmamk_f32 v1, v133, 0x3a000000, v175
	v_mul_f32_e32 v2, 0x4b800000, v1
	v_cmp_gt_f32_e32 vcc, s93, v1
	v_add_f32_e32 v0, v3, v0
	v_mov_b32_e32 v10, v134
	v_cndmask_b32_e32 v1, v1, v2, vcc
	v_rsq_f32_e32 v1, v1
	v_add_f32_dpp v0, v0, v0 quad_perm:[1,0,3,2] row_mask:0xf bank_mask:0xf bound_ctrl:1
	v_mov_b32_e32 v11, v136
	s_mov_b32 s12, 0x9800
	v_add_f32_dpp v0, v0, v0 quad_perm:[2,3,0,1] row_mask:0xf bank_mask:0xf bound_ctrl:1
	v_mov_b32_e32 v136, v135
	v_add3_u32 v138, v172, v190, s12
	v_add_f32_dpp v194, v0, v0 row_half_mirror row_mask:0xf bank_mask:0xf bound_ctrl:1
	v_mul_f32_e32 v0, 0x45800000, v1
	v_cndmask_b32_e32 v1, v1, v0, vcc
	v_mul_f32_e32 v0, v103, v1
	v_mul_f32_e32 v3, v111, v1
	v_mul_f32_e32 v0, 0xbfb8aa3b, v0
	v_mul_f32_e32 v2, v99, v1
	v_mul_f32_e32 v3, 0xbfb8aa3b, v3
	v_mul_f32_e32 v1, v107, v1
	v_exp_f32_e32 v0, v0
	v_mul_f32_e32 v2, 0xbfb8aa3b, v2
	v_exp_f32_e32 v3, v3
	v_mul_f32_e32 v1, 0xbfb8aa3b, v1
	v_exp_f32_e32 v2, v2
	v_exp_f32_e32 v8, v1
	v_add_f32_e32 v0, 1.0, v0
	v_add_f32_e32 v1, 1.0, v3
	v_rcp_f32_e32 v0, v0
	v_add_f32_e32 v2, 1.0, v2
	v_rcp_f32_e32 v1, v1
	v_add_f32_e32 v3, 1.0, v8
	v_rcp_f32_e32 v2, v2
	v_rcp_f32_e32 v3, v3
	v_lshlrev_b32_e32 v8, 16, v148
	v_pk_fma_f32 v[130:131], v[0:1], v[8:9], v[10:11]
	v_and_b32_e32 v1, 0xffff0000, v149
	v_and_b32_e32 v0, 0xffff0000, v148
	v_pk_fma_f32 v[132:133], v[2:3], v[0:1], v[136:137]
	v_mov_b32_dpp v195, v194 row_mirror row_mask:0xf bank_mask:0xf bound_ctrl:1
	v_lshlrev_b32_e32 v8, 2, v138
	v_mov_b32_e32 v0, v130
	v_mov_b32_e32 v1, v132
	v_mov_b32_e32 v2, v131
	v_mov_b32_e32 v3, v133
	s_and_b64 vcc, exec, s[6:7]
	global_store_dwordx4 v8, v[0:3], s[2:3]
	s_cbranch_vccnz .LBB0_1147
	s_nop 0
	v_pk_mul_f32 v[0:1], v[128:129], v[130:131]
	v_pk_mul_f32 v[2:3], v[170:171], v[132:133]
	v_and_b32_sdwa v10, v0, v177 dst_sel:DWORD dst_unused:UNUSED_PAD src0_sel:WORD_1 src1_sel:DWORD
	v_add3_u32 v0, v0, v10, s48
	v_and_b32_sdwa v10, v2, v177 dst_sel:DWORD dst_unused:UNUSED_PAD src0_sel:WORD_1 src1_sel:DWORD
	v_add3_u32 v2, v2, v10, s48
	v_and_b32_e32 v2, 0xffff0000, v2
	v_lshlrev_b32_e32 v8, 1, v138
	v_cvt_pk_bf16_f32 v1, v1, v3
	v_or_b32_sdwa v0, v2, v0 dst_sel:DWORD dst_unused:UNUSED_PAD src0_sel:DWORD src1_sel:WORD_1
	global_store_dwordx2 v8, v[0:1], s[90:91]
; __device__ __forceinline__ float bflo(u32 w) { return __uint_as_float(w << 16); }
; __device__ __forceinline__ float bfhi(u32 w) { return __uint_as_float(w & 0xffff0000u); }
; __device__ __forceinline__ u32 pack2(float a, float b) { return (u32)f2bf(a) | ((u32)f2bf(b) << 16); }
; __device__ __forceinline__ float sigmoidf_(float x) { return __builtin_amdgcn_rcpf(1.f + __expf(-x)); }
; __device__ __forceinline__ void gemm_tile(const GemmArgs& ga, int wgid, int next_wgid, bool prefetched, u16* shm, unsigned char* ws, int wv_) {
;     ...
;       if (!GATE) { EPI_LOADS(0, 0) }
;       _Pragma("unroll") for (int bb = 0; bb < 8; ++bb) {
;         const int ai = bb >> 2, m = bb & 3;
;         const int cur = GATE ? 0 : (bb & 1);
;         if (GATE) { EPI_LOADS(bb, 0) }
;         else if (bb < 7) { EPI_LOADS(bb + 1, (bb + 1) & 1) }
;         _Pragma("unroll") for (int j = 0; j < 4; ++j) {
;           int row = rbase + ai * HALF + m * 16 + j;
;           unsigned eo = (unsigned)row * (unsigned)D_ + (unsigned)col0;
;           float s = 1.f;
;           if (GATE) s = rsqrtf(sc[j] * (1.f / D_) + 1e-6f);
;           const float a0 = acc[ai][0][m][0][j], a1 = acc[ai][0][m][1][j], a2 = acc[ai][1][m][0][j], a3 = acc[ai][1][m][1][j];
;           float4 xv = xin[cur][j];
;           if (GATE) {
;             xv.x += ga.live * (bflo(pin[j].x) * sigmoidf_(a0 * s));
;             xv.y += ga.live * (bfhi(pin[j].x) * sigmoidf_(a1 * s));
;             xv.z += ga.live * (bflo(pin[j].y) * sigmoidf_(a2 * s));
;             xv.w += ga.live * (bfhi(pin[j].y) * sigmoidf_(a3 * s));
;           } else {
;             const float al = ga.live * ga.alpha;
;             xv.x += al * a0; xv.y += al * a1; xv.z += al * a2; xv.w += al * a3;
;           }
;           *(float4*)(const_cast<char*>(xb) + (size_t)(eo * 4u)) = xv;
;           if (e_gn) *(uint2*)(ob + (size_t)(eo * 2u)) = make_uint2(pack2(xv.x * gn4.x, xv.y * gn4.y), pack2(xv.z * gn4.z, xv.w * gn4.w));
;           float sq = xv.x * xv.x + xv.y * xv.y + xv.z * xv.z + xv.w * xv.w;
;           sq = red16(sq);
.LBB0_1147:
	s_nop 0
	v_pk_mul_f32 v[0:1], v[130:131], v[130:131]
	v_pk_mul_f32 v[2:3], v[132:133], v[132:133]
	s_nop 0
	v_add_f32_e32 v0, v0, v2
	v_add_f32_e32 v0, v1, v0
	v_add_f32_e32 v0, v3, v0
	s_nop 1
	v_add_f32_dpp v0, v0, v0 quad_perm:[1,0,3,2] row_mask:0xf bank_mask:0xf bound_ctrl:1
	s_nop 1
	v_add_f32_dpp v0, v0, v0 quad_perm:[2,3,0,1] row_mask:0xf bank_mask:0xf bound_ctrl:1
	s_nop 1
	v_add_f32_dpp v196, v0, v0 row_half_mirror row_mask:0xf bank_mask:0xf bound_ctrl:1
	s_nop 1
	v_mov_b32_dpp v197, v196 row_mirror row_mask:0xf bank_mask:0xf bound_ctrl:1
	global_load_dwordx4 v[130:133], v[146:147], off offset:128
	v_add_u32_e32 v0, 0x10000, v198
	v_lshlrev_b32_e32 v30, 2, v0
	v_lshlrev_b32_e32 v166, 1, v0
	global_load_dwordx4 v[0:3], v30, s[78:79]
	v_add_u32_e32 v10, 0x10800, v198
	v_add_u32_e32 v11, 0x11000, v198
	v_add_u32_e32 v16, 0x11800, v198
	v_lshlrev_b32_e32 v17, 2, v10
	global_load_dwordx2 v[8:9], v166, s[8:9]
	v_lshlrev_b32_e32 v10, 1, v10
	v_lshlrev_b32_e32 v18, 2, v11
	v_lshlrev_b32_e32 v11, 1, v11
	v_lshlrev_b32_e32 v19, 2, v16
	v_lshlrev_b32_e32 v16, 1, v16
	global_load_dwordx4 v[142:145], v17, s[78:79]
	global_load_dwordx2 v[152:153], v10, s[8:9]
	global_load_dwordx4 v[138:141], v18, s[78:79]
	global_load_dwordx2 v[150:151], v11, s[8:9]
	global_load_dwordx4 v[134:137], v19, s[78:79]
	global_load_dwordx2 v[148:149], v16, s[8:9]
	s_waitcnt vmcnt(8)
	v_fmamk_f32 v10, v130, 0x3a000000, v175
	s_waitcnt vmcnt(7)
	v_mov_b32_e32 v17, v2
	v_rsq_f32_e32 v18, v10
	v_mov_b32_e32 v16, v0
	s_waitcnt vmcnt(6)
	v_lshlrev_b32_e32 v11, 16, v9
	v_mov_b32_e32 v0, v18
	v_mul_f32_e32 v2, v84, v0
	v_mul_f32_e32 v18, v80, v0
	v_mul_f32_e32 v19, v92, v0
	v_mul_f32_e32 v0, v88, v0
	v_mul_f32_e32 v2, 0xbfb8aa3b, v2
	v_mul_f32_e32 v18, 0xbfb8aa3b, v18
	v_mul_f32_e32 v19, 0xbfb8aa3b, v19
	v_mul_f32_e32 v0, 0xbfb8aa3b, v0
	v_exp_f32_e32 v2, v2
	v_exp_f32_e32 v18, v18
	v_exp_f32_e32 v19, v19
	v_exp_f32_e32 v0, v0
	v_add_f32_e32 v2, 1.0, v2
	v_add_f32_e32 v28, 1.0, v18
	v_add_f32_e32 v19, 1.0, v19
	v_add_f32_e32 v0, 1.0, v0
	v_rcp_f32_e32 v18, v2
	v_rcp_f32_e32 v28, v28
	v_rcp_f32_e32 v19, v19
	v_rcp_f32_e32 v29, v0
	v_lshlrev_b32_e32 v10, 16, v8
	v_and_b32_e32 v9, 0xffff0000, v9
	v_and_b32_e32 v8, 0xffff0000, v8
	v_mov_b32_e32 v2, v1
	v_pk_fma_f32 v[154:155], v[18:19], v[10:11], v[16:17]
	v_pk_fma_f32 v[156:157], v[28:29], v[8:9], v[2:3]
	v_mov_b32_e32 v0, v154
	v_mov_b32_e32 v1, v156
	v_mov_b32_e32 v2, v155
	v_mov_b32_e32 v3, v157
	s_and_b64 vcc, exec, s[6:7]
	global_store_dwordx4 v30, v[0:3], s[2:3]
	s_cbranch_vccnz .LBB0_1149
	s_nop 0
	v_pk_mul_f32 v[0:1], v[128:129], v[154:155]
	v_pk_mul_f32 v[2:3], v[170:171], v[156:157]
	v_lshl_add_u64 v[8:9], s[90:91], 0, v[166:167]
	v_cvt_pk_bf16_f32 v1, v1, v3
	v_cvt_pk_bf16_f32 v0, v0, v2
	global_store_dwordx2 v[8:9], v[0:1], off
.LBB0_1149:
	s_nop 0
	v_pk_mul_f32 v[0:1], v[154:155], v[154:155]
	v_pk_mul_f32 v[2:3], v[156:157], v[156:157]
	s_waitcnt vmcnt(5)
	v_lshlrev_b32_e32 v9, 16, v153
	v_add_f32_e32 v0, v0, v2
	v_add_f32_e32 v0, v1, v0
	v_fmamk_f32 v1, v131, 0x3a000000, v175
	v_mul_f32_e32 v2, 0x4b800000, v1
	v_cmp_gt_f32_e32 vcc, s93, v1
	v_add_f32_e32 v0, v3, v0
	v_mov_b32_e32 v10, v142
	v_cndmask_b32_e32 v1, v1, v2, vcc
	v_rsq_f32_e32 v1, v1
	v_add_f32_dpp v0, v0, v0 quad_perm:[1,0,3,2] row_mask:0xf bank_mask:0xf bound_ctrl:1
	v_mov_b32_e32 v11, v144
	s_mov_b32 s12, 0x10800
	v_add_f32_dpp v0, v0, v0 quad_perm:[2,3,0,1] row_mask:0xf bank_mask:0xf bound_ctrl:1
	v_mov_b32_e32 v144, v143
	v_add3_u32 v154, v172, v190, s12
	v_add_f32_dpp v199, v0, v0 row_half_mirror row_mask:0xf bank_mask:0xf bound_ctrl:1
	v_mul_f32_e32 v0, 0x45800000, v1
	v_cndmask_b32_e32 v1, v1, v0, vcc
	v_mul_f32_e32 v0, v85, v1
	v_mul_f32_e32 v3, v93, v1
	v_mul_f32_e32 v0, 0xbfb8aa3b, v0
	v_mul_f32_e32 v2, v81, v1
	v_mul_f32_e32 v3, 0xbfb8aa3b, v3
	v_mul_f32_e32 v1, v89, v1
	v_exp_f32_e32 v0, v0
	v_mul_f32_e32 v2, 0xbfb8aa3b, v2
	v_exp_f32_e32 v3, v3
	v_mul_f32_e32 v1, 0xbfb8aa3b, v1
	v_exp_f32_e32 v2, v2
	v_exp_f32_e32 v8, v1
	v_add_f32_e32 v0, 1.0, v0
	v_add_f32_e32 v1, 1.0, v3
	v_rcp_f32_e32 v0, v0
	v_add_f32_e32 v2, 1.0, v2
	v_rcp_f32_e32 v1, v1
	v_add_f32_e32 v3, 1.0, v8
	v_rcp_f32_e32 v2, v2
	v_rcp_f32_e32 v3, v3
	v_lshlrev_b32_e32 v8, 16, v152
	v_pk_fma_f32 v[130:131], v[0:1], v[8:9], v[10:11]
	v_and_b32_e32 v1, 0xffff0000, v153
	v_and_b32_e32 v0, 0xffff0000, v152
	v_pk_fma_f32 v[142:143], v[2:3], v[0:1], v[144:145]
	v_mov_b32_dpp v200, v199 row_mirror row_mask:0xf bank_mask:0xf bound_ctrl:1
	v_lshlrev_b32_e32 v8, 2, v154
	v_mov_b32_e32 v0, v130
	v_mov_b32_e32 v1, v142
	v_mov_b32_e32 v2, v131
	v_mov_b32_e32 v3, v143
	s_and_b64 vcc, exec, s[6:7]
	global_store_dwordx4 v8, v[0:3], s[2:3]
	s_cbranch_vccnz .LBB0_1151
	s_nop 0
	v_pk_mul_f32 v[0:1], v[128:129], v[130:131]
	v_pk_mul_f32 v[2:3], v[170:171], v[142:143]
	v_lshlrev_b32_e32 v8, 1, v154
	v_cvt_pk_bf16_f32 v1, v1, v3
	v_cvt_pk_bf16_f32 v0, v0, v2
	global_store_dwordx2 v8, v[0:1], s[90:91]
; __device__ __forceinline__ float bflo(u32 w) { return __uint_as_float(w << 16); }
; __device__ __forceinline__ float bfhi(u32 w) { return __uint_as_float(w & 0xffff0000u); }
; __device__ __forceinline__ u32 pack2(float a, float b) { return (u32)f2bf(a) | ((u32)f2bf(b) << 16); }
; __device__ __forceinline__ float sigmoidf_(float x) { return __builtin_amdgcn_rcpf(1.f + __expf(-x)); }
; __device__ __forceinline__ void gemm_tile(const GemmArgs& ga, int wgid, int next_wgid, bool prefetched, u16* shm, unsigned char* ws, int wv_) {
;     ...
;       if (!GATE) { EPI_LOADS(0, 0) }
;       _Pragma("unroll") for (int bb = 0; bb < 8; ++bb) {
;         const int ai = bb >> 2, m = bb & 3;
;         const int cur = GATE ? 0 : (bb & 1);
;         if (GATE) { EPI_LOADS(bb, 0) }
;         else if (bb < 7) { EPI_LOADS(bb + 1, (bb + 1) & 1) }
;         _Pragma("unroll") for (int j = 0; j < 4; ++j) {
;           int row = rbase + ai * HALF + m * 16 + j;
;           unsigned eo = (unsigned)row * (unsigned)D_ + (unsigned)col0;
;           float s = 1.f;
;           if (GATE) s = rsqrtf(sc[j] * (1.f / D_) + 1e-6f);
;           const float a0 = acc[ai][0][m][0][j], a1 = acc[ai][0][m][1][j], a2 = acc[ai][1][m][0][j], a3 = acc[ai][1][m][1][j];
;           float4 xv = xin[cur][j];
;           if (GATE) {
;             xv.x += ga.live * (bflo(pin[j].x) * sigmoidf_(a0 * s));
;             xv.y += ga.live * (bfhi(pin[j].x) * sigmoidf_(a1 * s));
;             xv.z += ga.live * (bflo(pin[j].y) * sigmoidf_(a2 * s));
;             xv.w += ga.live * (bfhi(pin[j].y) * sigmoidf_(a3 * s));
;           } else {
;             const float al = ga.live * ga.alpha;
;             xv.x += al * a0; xv.y += al * a1; xv.z += al * a2; xv.w += al * a3;
;           }
;           *(float4*)(const_cast<char*>(xb) + (size_t)(eo * 4u)) = xv;
;           if (e_gn) *(uint2*)(ob + (size_t)(eo * 2u)) = make_uint2(pack2(xv.x * gn4.x, xv.y * gn4.y), pack2(xv.z * gn4.z, xv.w * gn4.w));
;           float sq = xv.x * xv.x + xv.y * xv.y + xv.z * xv.z + xv.w * xv.w;
;           sq = red16(sq);
.LBB0_1151:
	s_nop 0
	v_pk_mul_f32 v[0:1], v[130:131], v[130:131]
	v_pk_mul_f32 v[2:3], v[142:143], v[142:143]
	s_waitcnt vmcnt(4)
	v_lshlrev_b32_e32 v9, 16, v151
	v_add_f32_e32 v0, v0, v2
	v_add_f32_e32 v0, v1, v0
	v_fmamk_f32 v1, v132, 0x3a000000, v175
	v_mul_f32_e32 v2, 0x4b800000, v1
	v_cmp_gt_f32_e32 vcc, s93, v1
	v_add_f32_e32 v0, v3, v0
	v_mov_b32_e32 v10, v138
	v_cndmask_b32_e32 v1, v1, v2, vcc
	v_rsq_f32_e32 v1, v1
	v_add_f32_dpp v0, v0, v0 quad_perm:[1,0,3,2] row_mask:0xf bank_mask:0xf bound_ctrl:1
	v_mov_b32_e32 v11, v140
	s_mov_b32 s12, 0x11000
	v_add_f32_dpp v0, v0, v0 quad_perm:[2,3,0,1] row_mask:0xf bank_mask:0xf bound_ctrl:1
	v_mov_b32_e32 v140, v139
	v_add3_u32 v132, v172, v190, s12
	v_add_f32_dpp v201, v0, v0 row_half_mirror row_mask:0xf bank_mask:0xf bound_ctrl:1
	v_mul_f32_e32 v0, 0x45800000, v1
	v_cndmask_b32_e32 v1, v1, v0, vcc
	v_mul_f32_e32 v0, v86, v1
	v_mul_f32_e32 v3, v94, v1
	v_mul_f32_e32 v0, 0xbfb8aa3b, v0
	v_mul_f32_e32 v2, v82, v1
	v_mul_f32_e32 v3, 0xbfb8aa3b, v3
	v_mul_f32_e32 v1, v90, v1
	v_exp_f32_e32 v0, v0
	v_mul_f32_e32 v2, 0xbfb8aa3b, v2
	v_exp_f32_e32 v3, v3
	v_mul_f32_e32 v1, 0xbfb8aa3b, v1
	v_exp_f32_e32 v2, v2
	v_exp_f32_e32 v8, v1
	v_add_f32_e32 v0, 1.0, v0
	v_add_f32_e32 v1, 1.0, v3
	v_rcp_f32_e32 v0, v0
	v_add_f32_e32 v2, 1.0, v2
	v_rcp_f32_e32 v1, v1
	v_add_f32_e32 v3, 1.0, v8
	v_rcp_f32_e32 v2, v2
	v_rcp_f32_e32 v3, v3
	v_lshlrev_b32_e32 v8, 16, v150
	v_pk_fma_f32 v[130:131], v[0:1], v[8:9], v[10:11]
	v_and_b32_e32 v1, 0xffff0000, v151
	v_and_b32_e32 v0, 0xffff0000, v150
	v_pk_fma_f32 v[138:139], v[2:3], v[0:1], v[140:141]
	v_mov_b32_dpp v202, v201 row_mirror row_mask:0xf bank_mask:0xf bound_ctrl:1
	v_lshlrev_b32_e32 v8, 2, v132
	v_mov_b32_e32 v0, v130
	v_mov_b32_e32 v1, v138
	v_mov_b32_e32 v2, v131
	v_mov_b32_e32 v3, v139
	s_and_b64 vcc, exec, s[6:7]
	global_store_dwordx4 v8, v[0:3], s[2:3]
	s_cbranch_vccnz .LBB0_1153
	s_nop 0
	v_pk_mul_f32 v[0:1], v[128:129], v[130:131]
	v_pk_mul_f32 v[2:3], v[170:171], v[138:139]
	v_lshlrev_b32_e32 v8, 1, v132
	v_cvt_pk_bf16_f32 v1, v1, v3
	v_cvt_pk_bf16_f32 v0, v0, v2
	global_store_dwordx2 v8, v[0:1], s[90:91]
.LBB0_1153:
	s_nop 0
	v_pk_mul_f32 v[0:1], v[130:131], v[130:131]
	v_pk_mul_f32 v[2:3], v[138:139], v[138:139]
	s_waitcnt vmcnt(3)
	v_lshlrev_b32_e32 v9, 16, v149
	v_add_f32_e32 v0, v0, v2
	v_add_f32_e32 v0, v1, v0
	v_fmamk_f32 v1, v133, 0x3a000000, v175
	v_mul_f32_e32 v2, 0x4b800000, v1
	v_cmp_gt_f32_e32 vcc, s93, v1
	v_add_f32_e32 v0, v3, v0
	v_mov_b32_e32 v10, v134
	v_cndmask_b32_e32 v1, v1, v2, vcc
	v_rsq_f32_e32 v1, v1
	v_add_f32_dpp v0, v0, v0 quad_perm:[1,0,3,2] row_mask:0xf bank_mask:0xf bound_ctrl:1
	v_mov_b32_e32 v11, v136
	s_mov_b32 s12, 0x11800
	v_add_f32_dpp v0, v0, v0 quad_perm:[2,3,0,1] row_mask:0xf bank_mask:0xf bound_ctrl:1
	v_mov_b32_e32 v136, v135
	v_add3_u32 v138, v172, v190, s12
	v_add_f32_dpp v203, v0, v0 row_half_mirror row_mask:0xf bank_mask:0xf bound_ctrl:1
	v_mul_f32_e32 v0, 0x45800000, v1
	v_cndmask_b32_e32 v1, v1, v0, vcc
	v_mul_f32_e32 v0, v87, v1
	v_mul_f32_e32 v3, v95, v1
	v_mul_f32_e32 v0, 0xbfb8aa3b, v0
	v_mul_f32_e32 v2, v83, v1
	v_mul_f32_e32 v3, 0xbfb8aa3b, v3
	v_mul_f32_e32 v1, v91, v1
	v_exp_f32_e32 v0, v0
	v_mul_f32_e32 v2, 0xbfb8aa3b, v2
	v_exp_f32_e32 v3, v3
	v_mul_f32_e32 v1, 0xbfb8aa3b, v1
	v_exp_f32_e32 v2, v2
	v_exp_f32_e32 v8, v1
	v_add_f32_e32 v0, 1.0, v0
	v_add_f32_e32 v1, 1.0, v3
	v_rcp_f32_e32 v0, v0
	v_add_f32_e32 v2, 1.0, v2
	v_rcp_f32_e32 v1, v1
	v_add_f32_e32 v3, 1.0, v8
	v_rcp_f32_e32 v2, v2
	v_rcp_f32_e32 v3, v3
	v_lshlrev_b32_e32 v8, 16, v148
	v_pk_fma_f32 v[130:131], v[0:1], v[8:9], v[10:11]
	v_and_b32_e32 v1, 0xffff0000, v149
	v_and_b32_e32 v0, 0xffff0000, v148
	v_pk_fma_f32 v[132:133], v[2:3], v[0:1], v[136:137]
	v_mov_b32_dpp v174, v203 row_mirror row_mask:0xf bank_mask:0xf bound_ctrl:1
	v_lshlrev_b32_e32 v8, 2, v138
	v_mov_b32_e32 v0, v130
	v_mov_b32_e32 v1, v132
	v_mov_b32_e32 v2, v131
	v_mov_b32_e32 v3, v133
	s_and_b64 vcc, exec, s[6:7]
	global_store_dwordx4 v8, v[0:3], s[2:3]
	s_cbranch_vccnz .LBB0_1155
	s_nop 0
	v_pk_mul_f32 v[0:1], v[128:129], v[130:131]
	v_pk_mul_f32 v[2:3], v[170:171], v[132:133]
	v_and_b32_sdwa v10, v0, v177 dst_sel:DWORD dst_unused:UNUSED_PAD src0_sel:WORD_1 src1_sel:DWORD
	v_add3_u32 v0, v0, v10, s48
	v_and_b32_sdwa v10, v2, v177 dst_sel:DWORD dst_unused:UNUSED_PAD src0_sel:WORD_1 src1_sel:DWORD
	v_add3_u32 v2, v2, v10, s48
	v_and_b32_e32 v2, 0xffff0000, v2
	v_lshlrev_b32_e32 v8, 1, v138
	v_cvt_pk_bf16_f32 v1, v1, v3
	v_or_b32_sdwa v0, v2, v0 dst_sel:DWORD dst_unused:UNUSED_PAD src0_sel:DWORD src1_sel:WORD_1
	global_store_dwordx2 v8, v[0:1], s[90:91]
; __device__ __forceinline__ float bflo(u32 w) { return __uint_as_float(w << 16); }
; __device__ __forceinline__ float bfhi(u32 w) { return __uint_as_float(w & 0xffff0000u); }
; __device__ __forceinline__ u32 pack2(float a, float b) { return (u32)f2bf(a) | ((u32)f2bf(b) << 16); }
; __device__ __forceinline__ float sigmoidf_(float x) { return __builtin_amdgcn_rcpf(1.f + __expf(-x)); }
; __device__ __forceinline__ void gemm_tile(const GemmArgs& ga, int wgid, int next_wgid, bool prefetched, u16* shm, unsigned char* ws, int wv_) {
;     ...
;       if (!GATE) { EPI_LOADS(0, 0) }
;       _Pragma("unroll") for (int bb = 0; bb < 8; ++bb) {
;         const int ai = bb >> 2, m = bb & 3;
;         const int cur = GATE ? 0 : (bb & 1);
;         if (GATE) { EPI_LOADS(bb, 0) }
;         else if (bb < 7) { EPI_LOADS(bb + 1, (bb + 1) & 1) }
;         _Pragma("unroll") for (int j = 0; j < 4; ++j) {
;           int row = rbase + ai * HALF + m * 16 + j;
;           unsigned eo = (unsigned)row * (unsigned)D_ + (unsigned)col0;
;           float s = 1.f;
;           if (GATE) s = rsqrtf(sc[j] * (1.f / D_) + 1e-6f);
;           const float a0 = acc[ai][0][m][0][j], a1 = acc[ai][0][m][1][j], a2 = acc[ai][1][m][0][j], a3 = acc[ai][1][m][1][j];
;           float4 xv = xin[cur][j];
;           if (GATE) {
;             xv.x += ga.live * (bflo(pin[j].x) * sigmoidf_(a0 * s));
;             xv.y += ga.live * (bfhi(pin[j].x) * sigmoidf_(a1 * s));
;             xv.z += ga.live * (bflo(pin[j].y) * sigmoidf_(a2 * s));
;             xv.w += ga.live * (bfhi(pin[j].y) * sigmoidf_(a3 * s));
;           } else {
;             const float al = ga.live * ga.alpha;
;             xv.x += al * a0; xv.y += al * a1; xv.z += al * a2; xv.w += al * a3;
;           }
;           *(float4*)(const_cast<char*>(xb) + (size_t)(eo * 4u)) = xv;
;           if (e_gn) *(uint2*)(ob + (size_t)(eo * 2u)) = make_uint2(pack2(xv.x * gn4.x, xv.y * gn4.y), pack2(xv.z * gn4.z, xv.w * gn4.w));
;           float sq = xv.x * xv.x + xv.y * xv.y + xv.z * xv.z + xv.w * xv.w;
;           sq = red16(sq);
.LBB0_1155:
	s_nop 0
	v_pk_mul_f32 v[0:1], v[130:131], v[130:131]
	v_pk_mul_f32 v[2:3], v[132:133], v[132:133]
	s_nop 0
	v_add_f32_e32 v0, v0, v2
	v_add_f32_e32 v0, v1, v0
	v_add_f32_e32 v0, v3, v0
	s_nop 1
	v_add_f32_dpp v0, v0, v0 quad_perm:[1,0,3,2] row_mask:0xf bank_mask:0xf bound_ctrl:1
	s_nop 1
	v_add_f32_dpp v0, v0, v0 quad_perm:[2,3,0,1] row_mask:0xf bank_mask:0xf bound_ctrl:1
	s_nop 1
	v_add_f32_dpp v186, v0, v0 row_half_mirror row_mask:0xf bank_mask:0xf bound_ctrl:1
	s_nop 1
	v_mov_b32_dpp v237, v186 row_mirror row_mask:0xf bank_mask:0xf bound_ctrl:1
	global_load_dwordx4 v[130:133], v[146:147], off offset:192
	v_add_u32_e32 v0, 0x18000, v198
	v_lshlrev_b32_e32 v30, 2, v0
	v_lshlrev_b32_e32 v166, 1, v0
	global_load_dwordx4 v[0:3], v30, s[78:79]
	v_add_u32_e32 v10, 0x18800, v198
	v_add_u32_e32 v11, 0x19000, v198
	v_add_u32_e32 v16, 0x19800, v198
	v_lshlrev_b32_e32 v17, 2, v10
	global_load_dwordx2 v[8:9], v166, s[8:9]
	v_lshlrev_b32_e32 v10, 1, v10
	v_lshlrev_b32_e32 v18, 2, v11
	v_lshlrev_b32_e32 v11, 1, v11
	v_lshlrev_b32_e32 v19, 2, v16
	v_lshlrev_b32_e32 v16, 1, v16
	global_load_dwordx4 v[142:145], v17, s[78:79]
	global_load_dwordx2 v[152:153], v10, s[8:9]
	global_load_dwordx4 v[138:141], v18, s[78:79]
	global_load_dwordx2 v[150:151], v11, s[8:9]
	global_load_dwordx4 v[134:137], v19, s[78:79]
	global_load_dwordx2 v[148:149], v16, s[8:9]
	s_waitcnt vmcnt(8)
	v_fmamk_f32 v10, v130, 0x3a000000, v175
	s_waitcnt vmcnt(7)
	v_mov_b32_e32 v17, v2
	v_rsq_f32_e32 v18, v10
	v_mov_b32_e32 v16, v0
	s_waitcnt vmcnt(6)
	v_lshlrev_b32_e32 v11, 16, v9
	v_mov_b32_e32 v0, v18
	v_mul_f32_e32 v2, v68, v0
	v_mul_f32_e32 v18, v64, v0
	v_mul_f32_e32 v19, v76, v0
	v_mul_f32_e32 v0, v72, v0
	v_mul_f32_e32 v2, 0xbfb8aa3b, v2
	v_mul_f32_e32 v18, 0xbfb8aa3b, v18
	v_mul_f32_e32 v19, 0xbfb8aa3b, v19
	v_mul_f32_e32 v0, 0xbfb8aa3b, v0
	v_exp_f32_e32 v2, v2
	v_exp_f32_e32 v18, v18
	v_exp_f32_e32 v19, v19
	v_exp_f32_e32 v0, v0
	v_add_f32_e32 v2, 1.0, v2
	v_add_f32_e32 v28, 1.0, v18
	v_add_f32_e32 v19, 1.0, v19
	v_add_f32_e32 v0, 1.0, v0
	v_rcp_f32_e32 v18, v2
	v_rcp_f32_e32 v28, v28
	v_rcp_f32_e32 v19, v19
	v_rcp_f32_e32 v29, v0
	v_lshlrev_b32_e32 v10, 16, v8
	v_and_b32_e32 v9, 0xffff0000, v9
	v_and_b32_e32 v8, 0xffff0000, v8
	v_mov_b32_e32 v2, v1
	v_pk_fma_f32 v[154:155], v[18:19], v[10:11], v[16:17]
	v_pk_fma_f32 v[156:157], v[28:29], v[8:9], v[2:3]
	v_mov_b32_e32 v0, v154
	v_mov_b32_e32 v1, v156
	v_mov_b32_e32 v2, v155
	v_mov_b32_e32 v3, v157
	s_and_b64 vcc, exec, s[6:7]
	global_store_dwordx4 v30, v[0:3], s[2:3]
	s_cbranch_vccnz .LBB0_1157
	s_nop 0
	v_pk_mul_f32 v[0:1], v[128:129], v[154:155]
	v_pk_mul_f32 v[2:3], v[170:171], v[156:157]
	v_lshl_add_u64 v[8:9], s[90:91], 0, v[166:167]
	v_cvt_pk_bf16_f32 v1, v1, v3
	v_cvt_pk_bf16_f32 v0, v0, v2
	global_store_dwordx2 v[8:9], v[0:1], off
.LBB0_1157:
	s_nop 0
	v_pk_mul_f32 v[0:1], v[154:155], v[154:155]
	v_pk_mul_f32 v[2:3], v[156:157], v[156:157]
	s_waitcnt vmcnt(5)
	v_lshlrev_b32_e32 v9, 16, v153
	v_add_f32_e32 v0, v0, v2
	v_add_f32_e32 v0, v1, v0
	v_fmamk_f32 v1, v131, 0x3a000000, v175
	v_mul_f32_e32 v2, 0x4b800000, v1
	v_cmp_gt_f32_e32 vcc, s93, v1
	v_add_f32_e32 v0, v3, v0
	v_mov_b32_e32 v10, v142
	v_cndmask_b32_e32 v1, v1, v2, vcc
	v_rsq_f32_e32 v1, v1
	v_add_f32_dpp v0, v0, v0 quad_perm:[1,0,3,2] row_mask:0xf bank_mask:0xf bound_ctrl:1
	v_mov_b32_e32 v11, v144
	s_mov_b32 s12, 0x18800
	v_add_f32_dpp v0, v0, v0 quad_perm:[2,3,0,1] row_mask:0xf bank_mask:0xf bound_ctrl:1
	v_mov_b32_e32 v144, v143
	v_add3_u32 v154, v172, v190, s12
	v_add_f32_dpp v238, v0, v0 row_half_mirror row_mask:0xf bank_mask:0xf bound_ctrl:1
	v_mul_f32_e32 v0, 0x45800000, v1
	v_cndmask_b32_e32 v1, v1, v0, vcc
	v_mul_f32_e32 v0, v69, v1
	v_mul_f32_e32 v3, v77, v1
	v_mul_f32_e32 v0, 0xbfb8aa3b, v0
	v_mul_f32_e32 v2, v65, v1
	v_mul_f32_e32 v3, 0xbfb8aa3b, v3
	v_mul_f32_e32 v1, v73, v1
	v_exp_f32_e32 v0, v0
	v_mul_f32_e32 v2, 0xbfb8aa3b, v2
	v_exp_f32_e32 v3, v3
	v_mul_f32_e32 v1, 0xbfb8aa3b, v1
	v_exp_f32_e32 v2, v2
	v_exp_f32_e32 v8, v1
	v_add_f32_e32 v0, 1.0, v0
	v_add_f32_e32 v1, 1.0, v3
	v_rcp_f32_e32 v0, v0
	v_add_f32_e32 v2, 1.0, v2
	v_rcp_f32_e32 v1, v1
	v_add_f32_e32 v3, 1.0, v8
	v_rcp_f32_e32 v2, v2
	v_rcp_f32_e32 v3, v3
	v_lshlrev_b32_e32 v8, 16, v152
	v_pk_fma_f32 v[130:131], v[0:1], v[8:9], v[10:11]
	v_and_b32_e32 v1, 0xffff0000, v153
	v_and_b32_e32 v0, 0xffff0000, v152
	v_pk_fma_f32 v[142:143], v[2:3], v[0:1], v[144:145]
	v_mov_b32_dpp v208, v238 row_mirror row_mask:0xf bank_mask:0xf bound_ctrl:1
	v_lshlrev_b32_e32 v8, 2, v154
	v_mov_b32_e32 v0, v130
	v_mov_b32_e32 v1, v142
	v_mov_b32_e32 v2, v131
	v_mov_b32_e32 v3, v143
	s_and_b64 vcc, exec, s[6:7]
	global_store_dwordx4 v8, v[0:3], s[2:3]
	s_cbranch_vccnz .LBB0_1159
	s_nop 0
	v_pk_mul_f32 v[0:1], v[128:129], v[130:131]
	v_pk_mul_f32 v[2:3], v[170:171], v[142:143]
	v_lshlrev_b32_e32 v8, 1, v154
	v_cvt_pk_bf16_f32 v1, v1, v3
	v_cvt_pk_bf16_f32 v0, v0, v2
	global_store_dwordx2 v8, v[0:1], s[90:91]
; __device__ __forceinline__ float bflo(u32 w) { return __uint_as_float(w << 16); }
; __device__ __forceinline__ float bfhi(u32 w) { return __uint_as_float(w & 0xffff0000u); }
; __device__ __forceinline__ u32 pack2(float a, float b) { return (u32)f2bf(a) | ((u32)f2bf(b) << 16); }
; __device__ __forceinline__ float sigmoidf_(float x) { return __builtin_amdgcn_rcpf(1.f + __expf(-x)); }
; __device__ __forceinline__ void gemm_tile(const GemmArgs& ga, int wgid, int next_wgid, bool prefetched, u16* shm, unsigned char* ws, int wv_) {
;     ...
;       if (!GATE) { EPI_LOADS(0, 0) }
;       _Pragma("unroll") for (int bb = 0; bb < 8; ++bb) {
;         const int ai = bb >> 2, m = bb & 3;
;         const int cur = GATE ? 0 : (bb & 1);
;         if (GATE) { EPI_LOADS(bb, 0) }
;         else if (bb < 7) { EPI_LOADS(bb + 1, (bb + 1) & 1) }
;         _Pragma("unroll") for (int j = 0; j < 4; ++j) {
;           int row = rbase + ai * HALF + m * 16 + j;
;           unsigned eo = (unsigned)row * (unsigned)D_ + (unsigned)col0;
;           float s = 1.f;
;           if (GATE) s = rsqrtf(sc[j] * (1.f / D_) + 1e-6f);
;           const float a0 = acc[ai][0][m][0][j], a1 = acc[ai][0][m][1][j], a2 = acc[ai][1][m][0][j], a3 = acc[ai][1][m][1][j];
;           float4 xv = xin[cur][j];
;           if (GATE) {
;             xv.x += ga.live * (bflo(pin[j].x) * sigmoidf_(a0 * s));
;             xv.y += ga.live * (bfhi(pin[j].x) * sigmoidf_(a1 * s));
;             xv.z += ga.live * (bflo(pin[j].y) * sigmoidf_(a2 * s));
;             xv.w += ga.live * (bfhi(pin[j].y) * sigmoidf_(a3 * s));
;           } else {
;             const float al = ga.live * ga.alpha;
;             xv.x += al * a0; xv.y += al * a1; xv.z += al * a2; xv.w += al * a3;
;           }
;           *(float4*)(const_cast<char*>(xb) + (size_t)(eo * 4u)) = xv;
;           if (e_gn) *(uint2*)(ob + (size_t)(eo * 2u)) = make_uint2(pack2(xv.x * gn4.x, xv.y * gn4.y), pack2(xv.z * gn4.z, xv.w * gn4.w));
;           float sq = xv.x * xv.x + xv.y * xv.y + xv.z * xv.z + xv.w * xv.w;
;           sq = red16(sq);
.LBB0_1159:
	s_nop 0
	v_pk_mul_f32 v[0:1], v[130:131], v[130:131]
	v_pk_mul_f32 v[2:3], v[142:143], v[142:143]
	s_waitcnt vmcnt(4)
	v_lshlrev_b32_e32 v9, 16, v151
	v_add_f32_e32 v0, v0, v2
	v_add_f32_e32 v0, v1, v0
	v_fmamk_f32 v1, v132, 0x3a000000, v175
	v_mul_f32_e32 v2, 0x4b800000, v1
	v_cmp_gt_f32_e32 vcc, s93, v1
	v_add_f32_e32 v0, v3, v0
	v_mov_b32_e32 v10, v138
	v_cndmask_b32_e32 v1, v1, v2, vcc
	v_rsq_f32_e32 v1, v1
	v_add_f32_dpp v0, v0, v0 quad_perm:[1,0,3,2] row_mask:0xf bank_mask:0xf bound_ctrl:1
	v_mov_b32_e32 v11, v140
	s_mov_b32 s12, 0x19000
	v_add_f32_dpp v0, v0, v0 quad_perm:[2,3,0,1] row_mask:0xf bank_mask:0xf bound_ctrl:1
	v_mov_b32_e32 v140, v139
	v_add3_u32 v132, v172, v190, s12
	v_add_f32_dpp v209, v0, v0 row_half_mirror row_mask:0xf bank_mask:0xf bound_ctrl:1
	v_mul_f32_e32 v0, 0x45800000, v1
	v_cndmask_b32_e32 v1, v1, v0, vcc
	v_mul_f32_e32 v0, v70, v1
	v_mul_f32_e32 v3, v78, v1
	v_mul_f32_e32 v0, 0xbfb8aa3b, v0
	v_mul_f32_e32 v2, v66, v1
	v_mul_f32_e32 v3, 0xbfb8aa3b, v3
	v_mul_f32_e32 v1, v74, v1
	v_exp_f32_e32 v0, v0
	v_mul_f32_e32 v2, 0xbfb8aa3b, v2
	v_exp_f32_e32 v3, v3
	v_mul_f32_e32 v1, 0xbfb8aa3b, v1
	v_exp_f32_e32 v2, v2
	v_exp_f32_e32 v8, v1
	v_add_f32_e32 v0, 1.0, v0
	v_add_f32_e32 v1, 1.0, v3
	v_rcp_f32_e32 v0, v0
	v_add_f32_e32 v2, 1.0, v2
	v_rcp_f32_e32 v1, v1
	v_add_f32_e32 v3, 1.0, v8
	v_rcp_f32_e32 v2, v2
	v_rcp_f32_e32 v3, v3
	v_lshlrev_b32_e32 v8, 16, v150
	v_pk_fma_f32 v[130:131], v[0:1], v[8:9], v[10:11]
	v_and_b32_e32 v1, 0xffff0000, v151
	v_and_b32_e32 v0, 0xffff0000, v150
	v_pk_fma_f32 v[138:139], v[2:3], v[0:1], v[140:141]
	v_mov_b32_dpp v210, v209 row_mirror row_mask:0xf bank_mask:0xf bound_ctrl:1
	v_lshlrev_b32_e32 v8, 2, v132
	v_mov_b32_e32 v0, v130
	v_mov_b32_e32 v1, v138
	v_mov_b32_e32 v2, v131
	v_mov_b32_e32 v3, v139
	s_and_b64 vcc, exec, s[6:7]
	global_store_dwordx4 v8, v[0:3], s[2:3]
	s_cbranch_vccnz .LBB0_1161
	s_nop 0
	v_pk_mul_f32 v[0:1], v[128:129], v[130:131]
	v_pk_mul_f32 v[2:3], v[170:171], v[138:139]
	v_lshlrev_b32_e32 v8, 1, v132
	v_cvt_pk_bf16_f32 v1, v1, v3
	v_cvt_pk_bf16_f32 v0, v0, v2
	global_store_dwordx2 v8, v[0:1], s[90:91]
.LBB0_1161:
	s_nop 0
	v_pk_mul_f32 v[0:1], v[130:131], v[130:131]
	v_pk_mul_f32 v[2:3], v[138:139], v[138:139]
	s_waitcnt vmcnt(3)
	v_lshlrev_b32_e32 v9, 16, v149
	v_add_f32_e32 v0, v0, v2
	v_add_f32_e32 v0, v1, v0
	v_fmamk_f32 v1, v133, 0x3a000000, v175
	v_mul_f32_e32 v2, 0x4b800000, v1
	v_cmp_gt_f32_e32 vcc, s93, v1
	v_add_f32_e32 v0, v3, v0
	v_mov_b32_e32 v10, v134
	v_cndmask_b32_e32 v1, v1, v2, vcc
	v_rsq_f32_e32 v1, v1
	v_add_f32_dpp v0, v0, v0 quad_perm:[1,0,3,2] row_mask:0xf bank_mask:0xf bound_ctrl:1
	v_mov_b32_e32 v11, v136
	s_mov_b32 s12, 0x19800
	v_add_f32_dpp v0, v0, v0 quad_perm:[2,3,0,1] row_mask:0xf bank_mask:0xf bound_ctrl:1
	v_mov_b32_e32 v136, v135
	v_add3_u32 v138, v172, v190, s12
	v_add_f32_dpp v211, v0, v0 row_half_mirror row_mask:0xf bank_mask:0xf bound_ctrl:1
	v_mul_f32_e32 v0, 0x45800000, v1
	v_cndmask_b32_e32 v1, v1, v0, vcc
	v_mul_f32_e32 v0, v71, v1
	v_mul_f32_e32 v3, v79, v1
	v_mul_f32_e32 v0, 0xbfb8aa3b, v0
	v_mul_f32_e32 v2, v67, v1
	v_mul_f32_e32 v3, 0xbfb8aa3b, v3
	v_mul_f32_e32 v1, v75, v1
	v_exp_f32_e32 v0, v0
	v_mul_f32_e32 v2, 0xbfb8aa3b, v2
	v_exp_f32_e32 v3, v3
	v_mul_f32_e32 v1, 0xbfb8aa3b, v1
	v_exp_f32_e32 v2, v2
	v_exp_f32_e32 v8, v1
	v_add_f32_e32 v0, 1.0, v0
	v_add_f32_e32 v1, 1.0, v3
	v_rcp_f32_e32 v0, v0
	v_add_f32_e32 v2, 1.0, v2
	v_rcp_f32_e32 v1, v1
	v_add_f32_e32 v3, 1.0, v8
	v_rcp_f32_e32 v2, v2
	v_rcp_f32_e32 v3, v3
	v_lshlrev_b32_e32 v8, 16, v148
	v_pk_fma_f32 v[130:131], v[0:1], v[8:9], v[10:11]
	v_and_b32_e32 v1, 0xffff0000, v149
	v_and_b32_e32 v0, 0xffff0000, v148
	v_pk_fma_f32 v[132:133], v[2:3], v[0:1], v[136:137]
	v_mov_b32_dpp v212, v211 row_mirror row_mask:0xf bank_mask:0xf bound_ctrl:1
	v_lshlrev_b32_e32 v8, 2, v138
	v_mov_b32_e32 v0, v130
	v_mov_b32_e32 v1, v132
	v_mov_b32_e32 v2, v131
	v_mov_b32_e32 v3, v133
	s_and_b64 vcc, exec, s[6:7]
	global_store_dwordx4 v8, v[0:3], s[2:3]
	s_cbranch_vccnz .LBB0_1163
	s_nop 0
	v_pk_mul_f32 v[0:1], v[128:129], v[130:131]
	v_pk_mul_f32 v[2:3], v[170:171], v[132:133]
	v_and_b32_sdwa v10, v0, v177 dst_sel:DWORD dst_unused:UNUSED_PAD src0_sel:WORD_1 src1_sel:DWORD
	v_add3_u32 v0, v0, v10, s48
	v_and_b32_sdwa v10, v2, v177 dst_sel:DWORD dst_unused:UNUSED_PAD src0_sel:WORD_1 src1_sel:DWORD
	v_add3_u32 v2, v2, v10, s48
	v_and_b32_e32 v2, 0xffff0000, v2
	v_lshlrev_b32_e32 v8, 1, v138
	v_cvt_pk_bf16_f32 v1, v1, v3
	v_or_b32_sdwa v0, v2, v0 dst_sel:DWORD dst_unused:UNUSED_PAD src0_sel:DWORD src1_sel:WORD_1
	global_store_dwordx2 v8, v[0:1], s[90:91]
; __device__ __forceinline__ float bflo(u32 w) { return __uint_as_float(w << 16); }
; __device__ __forceinline__ float bfhi(u32 w) { return __uint_as_float(w & 0xffff0000u); }
; __device__ __forceinline__ u32 pack2(float a, float b) { return (u32)f2bf(a) | ((u32)f2bf(b) << 16); }
; __device__ __forceinline__ float sigmoidf_(float x) { return __builtin_amdgcn_rcpf(1.f + __expf(-x)); }
; __device__ __forceinline__ void gemm_tile(const GemmArgs& ga, int wgid, int next_wgid, bool prefetched, u16* shm, unsigned char* ws, int wv_) {
;     ...
;       if (!GATE) { EPI_LOADS(0, 0) }
;       _Pragma("unroll") for (int bb = 0; bb < 8; ++bb) {
;         const int ai = bb >> 2, m = bb & 3;
;         const int cur = GATE ? 0 : (bb & 1);
;         if (GATE) { EPI_LOADS(bb, 0) }
;         else if (bb < 7) { EPI_LOADS(bb + 1, (bb + 1) & 1) }
;         _Pragma("unroll") for (int j = 0; j < 4; ++j) {
;           int row = rbase + ai * HALF + m * 16 + j;
;           unsigned eo = (unsigned)row * (unsigned)D_ + (unsigned)col0;
;           float s = 1.f;
;           if (GATE) s = rsqrtf(sc[j] * (1.f / D_) + 1e-6f);
;           const float a0 = acc[ai][0][m][0][j], a1 = acc[ai][0][m][1][j], a2 = acc[ai][1][m][0][j], a3 = acc[ai][1][m][1][j];
;           float4 xv = xin[cur][j];
;           if (GATE) {
;             xv.x += ga.live * (bflo(pin[j].x) * sigmoidf_(a0 * s));
;             xv.y += ga.live * (bfhi(pin[j].x) * sigmoidf_(a1 * s));
;             xv.z += ga.live * (bflo(pin[j].y) * sigmoidf_(a2 * s));
;             xv.w += ga.live * (bfhi(pin[j].y) * sigmoidf_(a3 * s));
;           } else {
;             const float al = ga.live * ga.alpha;
;             xv.x += al * a0; xv.y += al * a1; xv.z += al * a2; xv.w += al * a3;
;           }
;           *(float4*)(const_cast<char*>(xb) + (size_t)(eo * 4u)) = xv;
;           if (e_gn) *(uint2*)(ob + (size_t)(eo * 2u)) = make_uint2(pack2(xv.x * gn4.x, xv.y * gn4.y), pack2(xv.z * gn4.z, xv.w * gn4.w));
;           float sq = xv.x * xv.x + xv.y * xv.y + xv.z * xv.z + xv.w * xv.w;
;           sq = red16(sq);
.LBB0_1163:
	s_nop 0
	v_pk_mul_f32 v[0:1], v[130:131], v[130:131]
	v_pk_mul_f32 v[2:3], v[132:133], v[132:133]
	s_nop 0
	v_add_f32_e32 v0, v0, v2
	v_add_f32_e32 v0, v1, v0
	v_add_f32_e32 v0, v3, v0
	s_nop 1
	v_add_f32_dpp v0, v0, v0 quad_perm:[1,0,3,2] row_mask:0xf bank_mask:0xf bound_ctrl:1
	s_nop 1
	v_add_f32_dpp v0, v0, v0 quad_perm:[2,3,0,1] row_mask:0xf bank_mask:0xf bound_ctrl:1
	s_nop 1
	v_add_f32_dpp v213, v0, v0 row_half_mirror row_mask:0xf bank_mask:0xf bound_ctrl:1
	s_nop 1
	v_mov_b32_dpp v214, v213 row_mirror row_mask:0xf bank_mask:0xf bound_ctrl:1
	global_load_dwordx4 v[130:133], v[146:147], off offset:512
	v_add_u32_e32 v0, 0x40000, v198
	v_lshlrev_b32_e32 v30, 2, v0
	v_lshlrev_b32_e32 v166, 1, v0
	global_load_dwordx4 v[0:3], v30, s[78:79]
	v_add_u32_e32 v10, 0x40800, v198
	v_add_u32_e32 v11, 0x41000, v198
	v_add_u32_e32 v16, 0x41800, v198
	v_lshlrev_b32_e32 v17, 2, v10
	global_load_dwordx2 v[8:9], v166, s[8:9]
	v_lshlrev_b32_e32 v10, 1, v10
	v_lshlrev_b32_e32 v18, 2, v11
	v_lshlrev_b32_e32 v11, 1, v11
	v_lshlrev_b32_e32 v19, 2, v16
	v_lshlrev_b32_e32 v16, 1, v16
	global_load_dwordx4 v[142:145], v17, s[78:79]
	global_load_dwordx2 v[152:153], v10, s[8:9]
	global_load_dwordx4 v[138:141], v18, s[78:79]
	global_load_dwordx2 v[150:151], v11, s[8:9]
	global_load_dwordx4 v[134:137], v19, s[78:79]
	global_load_dwordx2 v[148:149], v16, s[8:9]
	s_waitcnt vmcnt(8)
	v_fmamk_f32 v10, v130, 0x3a000000, v175
	s_waitcnt vmcnt(7)
	v_mov_b32_e32 v17, v2
	v_rsq_f32_e32 v18, v10
	v_mov_b32_e32 v16, v0
	s_waitcnt vmcnt(6)
	v_lshlrev_b32_e32 v11, 16, v9
	v_mov_b32_e32 v0, v18
	v_mul_f32_e32 v2, v52, v0
	v_mul_f32_e32 v18, v48, v0
	v_mul_f32_e32 v19, v60, v0
	v_mul_f32_e32 v0, v56, v0
	v_mul_f32_e32 v2, 0xbfb8aa3b, v2
	v_mul_f32_e32 v18, 0xbfb8aa3b, v18
	v_mul_f32_e32 v19, 0xbfb8aa3b, v19
	v_mul_f32_e32 v0, 0xbfb8aa3b, v0
	v_exp_f32_e32 v2, v2
	v_exp_f32_e32 v18, v18
	v_exp_f32_e32 v19, v19
	v_exp_f32_e32 v0, v0
	v_add_f32_e32 v2, 1.0, v2
	v_add_f32_e32 v28, 1.0, v18
	v_add_f32_e32 v19, 1.0, v19
	v_add_f32_e32 v0, 1.0, v0
	v_rcp_f32_e32 v18, v2
	v_rcp_f32_e32 v28, v28
	v_rcp_f32_e32 v19, v19
	v_rcp_f32_e32 v29, v0
	v_lshlrev_b32_e32 v10, 16, v8
	v_and_b32_e32 v9, 0xffff0000, v9
	v_and_b32_e32 v8, 0xffff0000, v8
	v_mov_b32_e32 v2, v1
	v_pk_fma_f32 v[154:155], v[18:19], v[10:11], v[16:17]
	v_pk_fma_f32 v[156:157], v[28:29], v[8:9], v[2:3]
	v_mov_b32_e32 v0, v154
	v_mov_b32_e32 v1, v156
	v_mov_b32_e32 v2, v155
	v_mov_b32_e32 v3, v157
	s_and_b64 vcc, exec, s[6:7]
	global_store_dwordx4 v30, v[0:3], s[2:3]
	s_cbranch_vccnz .LBB0_1165
	s_nop 0
	v_pk_mul_f32 v[0:1], v[128:129], v[154:155]
	v_pk_mul_f32 v[2:3], v[170:171], v[156:157]
	v_lshl_add_u64 v[8:9], s[90:91], 0, v[166:167]
	v_cvt_pk_bf16_f32 v1, v1, v3
	v_cvt_pk_bf16_f32 v0, v0, v2
	global_store_dwordx2 v[8:9], v[0:1], off
.LBB0_1165:
	s_nop 0
	v_pk_mul_f32 v[0:1], v[154:155], v[154:155]
	v_pk_mul_f32 v[2:3], v[156:157], v[156:157]
	s_waitcnt vmcnt(5)
	v_lshlrev_b32_e32 v9, 16, v153
	v_add_f32_e32 v0, v0, v2
	v_add_f32_e32 v0, v1, v0
	v_fmamk_f32 v1, v131, 0x3a000000, v175
	v_mul_f32_e32 v2, 0x4b800000, v1
	v_cmp_gt_f32_e32 vcc, s93, v1
	v_add_f32_e32 v0, v3, v0
	v_mov_b32_e32 v10, v142
	v_cndmask_b32_e32 v1, v1, v2, vcc
	v_rsq_f32_e32 v1, v1
	v_add_f32_dpp v0, v0, v0 quad_perm:[1,0,3,2] row_mask:0xf bank_mask:0xf bound_ctrl:1
	v_mov_b32_e32 v11, v144
	v_mov_b32_e32 v144, v143
	v_add_f32_dpp v0, v0, v0 quad_perm:[2,3,0,1] row_mask:0xf bank_mask:0xf bound_ctrl:1
	v_add_u32_e32 v154, 0x40800, v173
	s_nop 0
	v_add_f32_dpp v215, v0, v0 row_half_mirror row_mask:0xf bank_mask:0xf bound_ctrl:1
	v_mul_f32_e32 v0, 0x45800000, v1
	v_cndmask_b32_e32 v1, v1, v0, vcc
	v_mul_f32_e32 v0, v53, v1
	v_mul_f32_e32 v3, v61, v1
	v_mul_f32_e32 v0, 0xbfb8aa3b, v0
	v_mul_f32_e32 v2, v49, v1
	v_mul_f32_e32 v3, 0xbfb8aa3b, v3
	v_mul_f32_e32 v1, v57, v1
	v_exp_f32_e32 v0, v0
	v_mul_f32_e32 v2, 0xbfb8aa3b, v2
	v_exp_f32_e32 v3, v3
	v_mul_f32_e32 v1, 0xbfb8aa3b, v1
	v_exp_f32_e32 v2, v2
	v_exp_f32_e32 v8, v1
	v_add_f32_e32 v0, 1.0, v0
	v_add_f32_e32 v1, 1.0, v3
	v_rcp_f32_e32 v0, v0
	v_add_f32_e32 v2, 1.0, v2
	v_rcp_f32_e32 v1, v1
	v_add_f32_e32 v3, 1.0, v8
	v_rcp_f32_e32 v2, v2
	v_rcp_f32_e32 v3, v3
	v_lshlrev_b32_e32 v8, 16, v152
	v_pk_fma_f32 v[130:131], v[0:1], v[8:9], v[10:11]
	v_and_b32_e32 v1, 0xffff0000, v153
	v_and_b32_e32 v0, 0xffff0000, v152
	v_pk_fma_f32 v[142:143], v[2:3], v[0:1], v[144:145]
	v_mov_b32_dpp v216, v215 row_mirror row_mask:0xf bank_mask:0xf bound_ctrl:1
	v_lshlrev_b32_e32 v8, 2, v154
	v_mov_b32_e32 v0, v130
	v_mov_b32_e32 v1, v142
	v_mov_b32_e32 v2, v131
	v_mov_b32_e32 v3, v143
	s_and_b64 vcc, exec, s[6:7]
	global_store_dwordx4 v8, v[0:3], s[2:3]
	s_cbranch_vccnz .LBB0_1167
	s_nop 0
	v_pk_mul_f32 v[0:1], v[128:129], v[130:131]
	v_pk_mul_f32 v[2:3], v[170:171], v[142:143]
	v_lshlrev_b32_e32 v8, 1, v154
	v_cvt_pk_bf16_f32 v1, v1, v3
	v_cvt_pk_bf16_f32 v0, v0, v2
	global_store_dwordx2 v8, v[0:1], s[90:91]
; __device__ __forceinline__ float bflo(u32 w) { return __uint_as_float(w << 16); }
; __device__ __forceinline__ float bfhi(u32 w) { return __uint_as_float(w & 0xffff0000u); }
; __device__ __forceinline__ u32 pack2(float a, float b) { return (u32)f2bf(a) | ((u32)f2bf(b) << 16); }
; __device__ __forceinline__ float sigmoidf_(float x) { return __builtin_amdgcn_rcpf(1.f + __expf(-x)); }
; __device__ __forceinline__ void gemm_tile(const GemmArgs& ga, int wgid, int next_wgid, bool prefetched, u16* shm, unsigned char* ws, int wv_) {
;     ...
;       if (!GATE) { EPI_LOADS(0, 0) }
;       _Pragma("unroll") for (int bb = 0; bb < 8; ++bb) {
;         const int ai = bb >> 2, m = bb & 3;
;         const int cur = GATE ? 0 : (bb & 1);
;         if (GATE) { EPI_LOADS(bb, 0) }
;         else if (bb < 7) { EPI_LOADS(bb + 1, (bb + 1) & 1) }
;         _Pragma("unroll") for (int j = 0; j < 4; ++j) {
;           int row = rbase + ai * HALF + m * 16 + j;
;           unsigned eo = (unsigned)row * (unsigned)D_ + (unsigned)col0;
;           float s = 1.f;
;           if (GATE) s = rsqrtf(sc[j] * (1.f / D_) + 1e-6f);
;           const float a0 = acc[ai][0][m][0][j], a1 = acc[ai][0][m][1][j], a2 = acc[ai][1][m][0][j], a3 = acc[ai][1][m][1][j];
;           float4 xv = xin[cur][j];
;           if (GATE) {
;             xv.x += ga.live * (bflo(pin[j].x) * sigmoidf_(a0 * s));
;             xv.y += ga.live * (bfhi(pin[j].x) * sigmoidf_(a1 * s));
;             xv.z += ga.live * (bflo(pin[j].y) * sigmoidf_(a2 * s));
;             xv.w += ga.live * (bfhi(pin[j].y) * sigmoidf_(a3 * s));
;           } else {
;             const float al = ga.live * ga.alpha;
;             xv.x += al * a0; xv.y += al * a1; xv.z += al * a2; xv.w += al * a3;
;           }
;           *(float4*)(const_cast<char*>(xb) + (size_t)(eo * 4u)) = xv;
;           if (e_gn) *(uint2*)(ob + (size_t)(eo * 2u)) = make_uint2(pack2(xv.x * gn4.x, xv.y * gn4.y), pack2(xv.z * gn4.z, xv.w * gn4.w));
;           float sq = xv.x * xv.x + xv.y * xv.y + xv.z * xv.z + xv.w * xv.w;
;           sq = red16(sq);
.LBB0_1167:
	s_nop 0
	v_pk_mul_f32 v[0:1], v[130:131], v[130:131]
	v_pk_mul_f32 v[2:3], v[142:143], v[142:143]
	s_waitcnt vmcnt(4)
	v_lshlrev_b32_e32 v9, 16, v151
	v_add_f32_e32 v0, v0, v2
	v_add_f32_e32 v0, v1, v0
	v_fmamk_f32 v1, v132, 0x3a000000, v175
	v_mul_f32_e32 v2, 0x4b800000, v1
	v_cmp_gt_f32_e32 vcc, s93, v1
	v_add_f32_e32 v0, v3, v0
	v_mov_b32_e32 v10, v138
	v_cndmask_b32_e32 v1, v1, v2, vcc
	v_rsq_f32_e32 v1, v1
	v_add_f32_dpp v0, v0, v0 quad_perm:[1,0,3,2] row_mask:0xf bank_mask:0xf bound_ctrl:1
	v_mov_b32_e32 v11, v140
	v_mov_b32_e32 v140, v139
	v_add_f32_dpp v0, v0, v0 quad_perm:[2,3,0,1] row_mask:0xf bank_mask:0xf bound_ctrl:1
	v_add_u32_e32 v132, 0x41000, v173
	s_nop 0
	v_add_f32_dpp v217, v0, v0 row_half_mirror row_mask:0xf bank_mask:0xf bound_ctrl:1
	v_mul_f32_e32 v0, 0x45800000, v1
	v_cndmask_b32_e32 v1, v1, v0, vcc
	v_mul_f32_e32 v0, v54, v1
	v_mul_f32_e32 v3, v62, v1
	v_mul_f32_e32 v0, 0xbfb8aa3b, v0
	v_mul_f32_e32 v2, v50, v1
	v_mul_f32_e32 v3, 0xbfb8aa3b, v3
	v_mul_f32_e32 v1, v58, v1
	v_exp_f32_e32 v0, v0
	v_mul_f32_e32 v2, 0xbfb8aa3b, v2
	v_exp_f32_e32 v3, v3
	v_mul_f32_e32 v1, 0xbfb8aa3b, v1
	v_exp_f32_e32 v2, v2
	v_exp_f32_e32 v8, v1
	v_add_f32_e32 v0, 1.0, v0
	v_add_f32_e32 v1, 1.0, v3
	v_rcp_f32_e32 v0, v0
	v_add_f32_e32 v2, 1.0, v2
	v_rcp_f32_e32 v1, v1
	v_add_f32_e32 v3, 1.0, v8
	v_rcp_f32_e32 v2, v2
	v_rcp_f32_e32 v3, v3
	v_lshlrev_b32_e32 v8, 16, v150
	v_pk_fma_f32 v[130:131], v[0:1], v[8:9], v[10:11]
	v_and_b32_e32 v1, 0xffff0000, v151
	v_and_b32_e32 v0, 0xffff0000, v150
	v_pk_fma_f32 v[138:139], v[2:3], v[0:1], v[140:141]
	v_mov_b32_dpp v218, v217 row_mirror row_mask:0xf bank_mask:0xf bound_ctrl:1
	v_lshlrev_b32_e32 v8, 2, v132
	v_mov_b32_e32 v0, v130
	v_mov_b32_e32 v1, v138
	v_mov_b32_e32 v2, v131
	v_mov_b32_e32 v3, v139
	s_and_b64 vcc, exec, s[6:7]
	global_store_dwordx4 v8, v[0:3], s[2:3]
	s_cbranch_vccnz .LBB0_1169
	s_nop 0
	v_pk_mul_f32 v[0:1], v[128:129], v[130:131]
	v_pk_mul_f32 v[2:3], v[170:171], v[138:139]
	v_lshlrev_b32_e32 v8, 1, v132
	v_cvt_pk_bf16_f32 v1, v1, v3
	v_cvt_pk_bf16_f32 v0, v0, v2
	global_store_dwordx2 v8, v[0:1], s[90:91]
.LBB0_1169:
	s_nop 0
	v_pk_mul_f32 v[0:1], v[130:131], v[130:131]
	v_pk_mul_f32 v[2:3], v[138:139], v[138:139]
	s_waitcnt vmcnt(3)
	v_lshlrev_b32_e32 v9, 16, v149
	v_add_f32_e32 v0, v0, v2
	v_add_f32_e32 v0, v1, v0
	v_fmamk_f32 v1, v133, 0x3a000000, v175
	v_mul_f32_e32 v2, 0x4b800000, v1
	v_cmp_gt_f32_e32 vcc, s93, v1
	v_add_f32_e32 v0, v3, v0
	v_mov_b32_e32 v10, v134
	v_cndmask_b32_e32 v1, v1, v2, vcc
	v_rsq_f32_e32 v1, v1
	v_add_f32_dpp v0, v0, v0 quad_perm:[1,0,3,2] row_mask:0xf bank_mask:0xf bound_ctrl:1
	v_mov_b32_e32 v11, v136
	v_mov_b32_e32 v136, v135
	v_add_f32_dpp v0, v0, v0 quad_perm:[2,3,0,1] row_mask:0xf bank_mask:0xf bound_ctrl:1
	v_add_u32_e32 v138, 0x41800, v173
	s_nop 0
	v_add_f32_dpp v219, v0, v0 row_half_mirror row_mask:0xf bank_mask:0xf bound_ctrl:1
	v_mul_f32_e32 v0, 0x45800000, v1
	v_cndmask_b32_e32 v1, v1, v0, vcc
	v_mul_f32_e32 v0, v55, v1
	v_mul_f32_e32 v3, v63, v1
	v_mul_f32_e32 v0, 0xbfb8aa3b, v0
	v_mul_f32_e32 v2, v51, v1
	v_mul_f32_e32 v3, 0xbfb8aa3b, v3
	v_mul_f32_e32 v1, v59, v1
	v_exp_f32_e32 v0, v0
	v_mul_f32_e32 v2, 0xbfb8aa3b, v2
	v_exp_f32_e32 v3, v3
	v_mul_f32_e32 v1, 0xbfb8aa3b, v1
	v_exp_f32_e32 v2, v2
	v_exp_f32_e32 v8, v1
	v_add_f32_e32 v0, 1.0, v0
	v_add_f32_e32 v1, 1.0, v3
	v_rcp_f32_e32 v0, v0
	v_add_f32_e32 v2, 1.0, v2
	v_rcp_f32_e32 v1, v1
	v_add_f32_e32 v3, 1.0, v8
	v_rcp_f32_e32 v2, v2
	v_rcp_f32_e32 v3, v3
	v_lshlrev_b32_e32 v8, 16, v148
	v_pk_fma_f32 v[130:131], v[0:1], v[8:9], v[10:11]
	v_and_b32_e32 v1, 0xffff0000, v149
	v_and_b32_e32 v0, 0xffff0000, v148
	v_pk_fma_f32 v[132:133], v[2:3], v[0:1], v[136:137]
	v_mov_b32_dpp v220, v219 row_mirror row_mask:0xf bank_mask:0xf bound_ctrl:1
	v_lshlrev_b32_e32 v8, 2, v138
	v_mov_b32_e32 v0, v130
	v_mov_b32_e32 v1, v132
	v_mov_b32_e32 v2, v131
	v_mov_b32_e32 v3, v133
	s_and_b64 vcc, exec, s[6:7]
	global_store_dwordx4 v8, v[0:3], s[2:3]
	s_cbranch_vccnz .LBB0_1171
	s_nop 0
	v_pk_mul_f32 v[0:1], v[128:129], v[130:131]
	v_pk_mul_f32 v[2:3], v[170:171], v[132:133]
	v_and_b32_sdwa v10, v0, v177 dst_sel:DWORD dst_unused:UNUSED_PAD src0_sel:WORD_1 src1_sel:DWORD
	v_add3_u32 v0, v0, v10, s48
	v_and_b32_sdwa v10, v2, v177 dst_sel:DWORD dst_unused:UNUSED_PAD src0_sel:WORD_1 src1_sel:DWORD
	v_add3_u32 v2, v2, v10, s48
	v_and_b32_e32 v2, 0xffff0000, v2
	v_lshlrev_b32_e32 v8, 1, v138
	v_cvt_pk_bf16_f32 v1, v1, v3
	v_or_b32_sdwa v0, v2, v0 dst_sel:DWORD dst_unused:UNUSED_PAD src0_sel:DWORD src1_sel:WORD_1
	global_store_dwordx2 v8, v[0:1], s[90:91]
; __device__ __forceinline__ float bflo(u32 w) { return __uint_as_float(w << 16); }
; __device__ __forceinline__ float bfhi(u32 w) { return __uint_as_float(w & 0xffff0000u); }
; __device__ __forceinline__ u32 pack2(float a, float b) { return (u32)f2bf(a) | ((u32)f2bf(b) << 16); }
; __device__ __forceinline__ float sigmoidf_(float x) { return __builtin_amdgcn_rcpf(1.f + __expf(-x)); }
; __device__ __forceinline__ void gemm_tile(const GemmArgs& ga, int wgid, int next_wgid, bool prefetched, u16* shm, unsigned char* ws, int wv_) {
;     ...
;       if (!GATE) { EPI_LOADS(0, 0) }
;       _Pragma("unroll") for (int bb = 0; bb < 8; ++bb) {
;         const int ai = bb >> 2, m = bb & 3;
;         const int cur = GATE ? 0 : (bb & 1);
;         if (GATE) { EPI_LOADS(bb, 0) }
;         else if (bb < 7) { EPI_LOADS(bb + 1, (bb + 1) & 1) }
;         _Pragma("unroll") for (int j = 0; j < 4; ++j) {
;           int row = rbase + ai * HALF + m * 16 + j;
;           unsigned eo = (unsigned)row * (unsigned)D_ + (unsigned)col0;
;           float s = 1.f;
;           if (GATE) s = rsqrtf(sc[j] * (1.f / D_) + 1e-6f);
;           const float a0 = acc[ai][0][m][0][j], a1 = acc[ai][0][m][1][j], a2 = acc[ai][1][m][0][j], a3 = acc[ai][1][m][1][j];
;           float4 xv = xin[cur][j];
;           if (GATE) {
;             xv.x += ga.live * (bflo(pin[j].x) * sigmoidf_(a0 * s));
;             xv.y += ga.live * (bfhi(pin[j].x) * sigmoidf_(a1 * s));
;             xv.z += ga.live * (bflo(pin[j].y) * sigmoidf_(a2 * s));
;             xv.w += ga.live * (bfhi(pin[j].y) * sigmoidf_(a3 * s));
;           } else {
;             const float al = ga.live * ga.alpha;
;             xv.x += al * a0; xv.y += al * a1; xv.z += al * a2; xv.w += al * a3;
;           }
;           *(float4*)(const_cast<char*>(xb) + (size_t)(eo * 4u)) = xv;
;           if (e_gn) *(uint2*)(ob + (size_t)(eo * 2u)) = make_uint2(pack2(xv.x * gn4.x, xv.y * gn4.y), pack2(xv.z * gn4.z, xv.w * gn4.w));
;           float sq = xv.x * xv.x + xv.y * xv.y + xv.z * xv.z + xv.w * xv.w;
;           sq = red16(sq);
.LBB0_1171:
	s_nop 0
	v_pk_mul_f32 v[0:1], v[130:131], v[130:131]
	v_pk_mul_f32 v[2:3], v[132:133], v[132:133]
	s_nop 0
	v_add_f32_e32 v0, v0, v2
	v_add_f32_e32 v0, v1, v0
	v_add_f32_e32 v0, v3, v0
	s_nop 1
	v_add_f32_dpp v0, v0, v0 quad_perm:[1,0,3,2] row_mask:0xf bank_mask:0xf bound_ctrl:1
	s_nop 1
	v_add_f32_dpp v0, v0, v0 quad_perm:[2,3,0,1] row_mask:0xf bank_mask:0xf bound_ctrl:1
	s_nop 1
	v_add_f32_dpp v221, v0, v0 row_half_mirror row_mask:0xf bank_mask:0xf bound_ctrl:1
	s_nop 1
	v_mov_b32_dpp v222, v221 row_mirror row_mask:0xf bank_mask:0xf bound_ctrl:1
	global_load_dwordx4 v[130:133], v[146:147], off offset:576
	v_add_u32_e32 v0, 0x48000, v198
	v_lshlrev_b32_e32 v30, 2, v0
	v_lshlrev_b32_e32 v166, 1, v0
	global_load_dwordx4 v[0:3], v30, s[78:79]
	v_add_u32_e32 v10, 0x48800, v198
	v_add_u32_e32 v11, 0x49000, v198
	v_add_u32_e32 v16, 0x49800, v198
	v_lshlrev_b32_e32 v17, 2, v10
	global_load_dwordx2 v[8:9], v166, s[8:9]
	v_lshlrev_b32_e32 v10, 1, v10
	v_lshlrev_b32_e32 v18, 2, v11
	v_lshlrev_b32_e32 v11, 1, v11
	v_lshlrev_b32_e32 v19, 2, v16
	v_lshlrev_b32_e32 v16, 1, v16
	global_load_dwordx4 v[142:145], v17, s[78:79]
	global_load_dwordx2 v[152:153], v10, s[8:9]
	global_load_dwordx4 v[138:141], v18, s[78:79]
	global_load_dwordx2 v[150:151], v11, s[8:9]
	global_load_dwordx4 v[134:137], v19, s[78:79]
	global_load_dwordx2 v[148:149], v16, s[8:9]
	s_waitcnt vmcnt(8)
	v_fmamk_f32 v10, v130, 0x3a000000, v175
	s_waitcnt vmcnt(7)
	v_mov_b32_e32 v17, v2
	v_rsq_f32_e32 v18, v10
	v_mov_b32_e32 v16, v0
	s_waitcnt vmcnt(6)
	v_lshlrev_b32_e32 v11, 16, v9
	v_mov_b32_e32 v0, v18
	v_mul_f32_e32 v2, v36, v0
	v_mul_f32_e32 v18, v32, v0
	v_mul_f32_e32 v19, v44, v0
	v_mul_f32_e32 v0, v40, v0
	v_mul_f32_e32 v2, 0xbfb8aa3b, v2
	v_mul_f32_e32 v18, 0xbfb8aa3b, v18
	v_mul_f32_e32 v19, 0xbfb8aa3b, v19
	v_mul_f32_e32 v0, 0xbfb8aa3b, v0
	v_exp_f32_e32 v2, v2
	v_exp_f32_e32 v18, v18
	v_exp_f32_e32 v19, v19
	v_exp_f32_e32 v0, v0
	v_add_f32_e32 v2, 1.0, v2
	v_add_f32_e32 v28, 1.0, v18
	v_add_f32_e32 v19, 1.0, v19
	v_add_f32_e32 v0, 1.0, v0
	v_rcp_f32_e32 v18, v2
	v_rcp_f32_e32 v28, v28
	v_rcp_f32_e32 v19, v19
	v_rcp_f32_e32 v29, v0
	v_lshlrev_b32_e32 v10, 16, v8
	v_and_b32_e32 v9, 0xffff0000, v9
	v_and_b32_e32 v8, 0xffff0000, v8
	v_mov_b32_e32 v2, v1
	v_pk_fma_f32 v[154:155], v[18:19], v[10:11], v[16:17]
	v_pk_fma_f32 v[156:157], v[28:29], v[8:9], v[2:3]
	v_mov_b32_e32 v0, v154
	v_mov_b32_e32 v1, v156
	v_mov_b32_e32 v2, v155
	v_mov_b32_e32 v3, v157
	s_and_b64 vcc, exec, s[6:7]
	global_store_dwordx4 v30, v[0:3], s[2:3]
	s_cbranch_vccnz .LBB0_1173
	s_nop 0
	v_pk_mul_f32 v[0:1], v[128:129], v[154:155]
	v_pk_mul_f32 v[2:3], v[170:171], v[156:157]
	v_lshl_add_u64 v[8:9], s[90:91], 0, v[166:167]
	v_cvt_pk_bf16_f32 v1, v1, v3
	v_cvt_pk_bf16_f32 v0, v0, v2
	global_store_dwordx2 v[8:9], v[0:1], off
.LBB0_1173:
	s_nop 0
	v_pk_mul_f32 v[0:1], v[154:155], v[154:155]
	v_pk_mul_f32 v[2:3], v[156:157], v[156:157]
	s_waitcnt vmcnt(5)
	v_lshlrev_b32_e32 v9, 16, v153
	v_add_f32_e32 v0, v0, v2
	v_add_f32_e32 v0, v1, v0
	v_fmamk_f32 v1, v131, 0x3a000000, v175
	v_mul_f32_e32 v2, 0x4b800000, v1
	v_cmp_gt_f32_e32 vcc, s93, v1
	v_add_f32_e32 v0, v3, v0
	v_mov_b32_e32 v10, v142
	v_cndmask_b32_e32 v1, v1, v2, vcc
	v_rsq_f32_e32 v1, v1
	v_add_f32_dpp v0, v0, v0 quad_perm:[1,0,3,2] row_mask:0xf bank_mask:0xf bound_ctrl:1
	v_mov_b32_e32 v11, v144
	v_mov_b32_e32 v144, v143
	v_add_f32_dpp v0, v0, v0 quad_perm:[2,3,0,1] row_mask:0xf bank_mask:0xf bound_ctrl:1
	v_add_u32_e32 v154, 0x48800, v173
	s_nop 0
	v_add_f32_dpp v223, v0, v0 row_half_mirror row_mask:0xf bank_mask:0xf bound_ctrl:1
	v_mul_f32_e32 v0, 0x45800000, v1
	v_cndmask_b32_e32 v1, v1, v0, vcc
	v_mul_f32_e32 v0, v37, v1
	v_mul_f32_e32 v3, v45, v1
	v_mul_f32_e32 v0, 0xbfb8aa3b, v0
	v_mul_f32_e32 v2, v33, v1
	v_mul_f32_e32 v3, 0xbfb8aa3b, v3
	v_mul_f32_e32 v1, v41, v1
	v_exp_f32_e32 v0, v0
	v_mul_f32_e32 v2, 0xbfb8aa3b, v2
	v_exp_f32_e32 v3, v3
	v_mul_f32_e32 v1, 0xbfb8aa3b, v1
	v_exp_f32_e32 v2, v2
	v_exp_f32_e32 v8, v1
	v_add_f32_e32 v0, 1.0, v0
	v_add_f32_e32 v1, 1.0, v3
	v_rcp_f32_e32 v0, v0
	v_add_f32_e32 v2, 1.0, v2
	v_rcp_f32_e32 v1, v1
	v_add_f32_e32 v3, 1.0, v8
	v_rcp_f32_e32 v2, v2
	v_rcp_f32_e32 v3, v3
	v_lshlrev_b32_e32 v8, 16, v152
	v_pk_fma_f32 v[130:131], v[0:1], v[8:9], v[10:11]
	v_and_b32_e32 v1, 0xffff0000, v153
	v_and_b32_e32 v0, 0xffff0000, v152
	v_pk_fma_f32 v[142:143], v[2:3], v[0:1], v[144:145]
	v_mov_b32_dpp v224, v223 row_mirror row_mask:0xf bank_mask:0xf bound_ctrl:1
	v_lshlrev_b32_e32 v8, 2, v154
	v_mov_b32_e32 v0, v130
	v_mov_b32_e32 v1, v142
	v_mov_b32_e32 v2, v131
	v_mov_b32_e32 v3, v143
	s_and_b64 vcc, exec, s[6:7]
	global_store_dwordx4 v8, v[0:3], s[2:3]
	s_cbranch_vccnz .LBB0_1175
	s_nop 0
	v_pk_mul_f32 v[0:1], v[128:129], v[130:131]
	v_pk_mul_f32 v[2:3], v[170:171], v[142:143]
	v_lshlrev_b32_e32 v8, 1, v154
	v_cvt_pk_bf16_f32 v1, v1, v3
	v_cvt_pk_bf16_f32 v0, v0, v2
	global_store_dwordx2 v8, v[0:1], s[90:91]
; __device__ __forceinline__ float bflo(u32 w) { return __uint_as_float(w << 16); }
; __device__ __forceinline__ float bfhi(u32 w) { return __uint_as_float(w & 0xffff0000u); }
; __device__ __forceinline__ u32 pack2(float a, float b) { return (u32)f2bf(a) | ((u32)f2bf(b) << 16); }
; __device__ __forceinline__ float sigmoidf_(float x) { return __builtin_amdgcn_rcpf(1.f + __expf(-x)); }
; __device__ __forceinline__ void gemm_tile(const GemmArgs& ga, int wgid, int next_wgid, bool prefetched, u16* shm, unsigned char* ws, int wv_) {
;     ...
;       if (!GATE) { EPI_LOADS(0, 0) }
;       _Pragma("unroll") for (int bb = 0; bb < 8; ++bb) {
;         const int ai = bb >> 2, m = bb & 3;
;         const int cur = GATE ? 0 : (bb & 1);
;         if (GATE) { EPI_LOADS(bb, 0) }
;         else if (bb < 7) { EPI_LOADS(bb + 1, (bb + 1) & 1) }
;         _Pragma("unroll") for (int j = 0; j < 4; ++j) {
;           int row = rbase + ai * HALF + m * 16 + j;
;           unsigned eo = (unsigned)row * (unsigned)D_ + (unsigned)col0;
;           float s = 1.f;
;           if (GATE) s = rsqrtf(sc[j] * (1.f / D_) + 1e-6f);
;           const float a0 = acc[ai][0][m][0][j], a1 = acc[ai][0][m][1][j], a2 = acc[ai][1][m][0][j], a3 = acc[ai][1][m][1][j];
;           float4 xv = xin[cur][j];
;           if (GATE) {
;             xv.x += ga.live * (bflo(pin[j].x) * sigmoidf_(a0 * s));
;             xv.y += ga.live * (bfhi(pin[j].x) * sigmoidf_(a1 * s));
;             xv.z += ga.live * (bflo(pin[j].y) * sigmoidf_(a2 * s));
;             xv.w += ga.live * (bfhi(pin[j].y) * sigmoidf_(a3 * s));
;           } else {
;             const float al = ga.live * ga.alpha;
;             xv.x += al * a0; xv.y += al * a1; xv.z += al * a2; xv.w += al * a3;
;           }
;           *(float4*)(const_cast<char*>(xb) + (size_t)(eo * 4u)) = xv;
;           if (e_gn) *(uint2*)(ob + (size_t)(eo * 2u)) = make_uint2(pack2(xv.x * gn4.x, xv.y * gn4.y), pack2(xv.z * gn4.z, xv.w * gn4.w));
;           float sq = xv.x * xv.x + xv.y * xv.y + xv.z * xv.z + xv.w * xv.w;
;           sq = red16(sq);
.LBB0_1175:
	s_nop 0
	v_pk_mul_f32 v[0:1], v[130:131], v[130:131]
	v_pk_mul_f32 v[2:3], v[142:143], v[142:143]
	s_waitcnt vmcnt(4)
	v_lshlrev_b32_e32 v9, 16, v151
	v_add_f32_e32 v0, v0, v2
	v_add_f32_e32 v0, v1, v0
	v_fmamk_f32 v1, v132, 0x3a000000, v175
	v_mul_f32_e32 v2, 0x4b800000, v1
	v_cmp_gt_f32_e32 vcc, s93, v1
	v_add_f32_e32 v0, v3, v0
	v_mov_b32_e32 v10, v138
	v_cndmask_b32_e32 v1, v1, v2, vcc
	v_rsq_f32_e32 v1, v1
	v_add_f32_dpp v0, v0, v0 quad_perm:[1,0,3,2] row_mask:0xf bank_mask:0xf bound_ctrl:1
	v_mov_b32_e32 v11, v140
	v_mov_b32_e32 v140, v139
	v_add_f32_dpp v0, v0, v0 quad_perm:[2,3,0,1] row_mask:0xf bank_mask:0xf bound_ctrl:1
	v_add_u32_e32 v132, 0x49000, v173
	s_nop 0
	v_add_f32_dpp v225, v0, v0 row_half_mirror row_mask:0xf bank_mask:0xf bound_ctrl:1
	v_mul_f32_e32 v0, 0x45800000, v1
	v_cndmask_b32_e32 v1, v1, v0, vcc
	v_mul_f32_e32 v0, v38, v1
	v_mul_f32_e32 v3, v46, v1
	v_mul_f32_e32 v0, 0xbfb8aa3b, v0
	v_mul_f32_e32 v2, v34, v1
	v_mul_f32_e32 v3, 0xbfb8aa3b, v3
	v_mul_f32_e32 v1, v42, v1
	v_exp_f32_e32 v0, v0
	v_mul_f32_e32 v2, 0xbfb8aa3b, v2
	v_exp_f32_e32 v3, v3
	v_mul_f32_e32 v1, 0xbfb8aa3b, v1
	v_exp_f32_e32 v2, v2
	v_exp_f32_e32 v8, v1
	v_add_f32_e32 v0, 1.0, v0
	v_add_f32_e32 v1, 1.0, v3
	v_rcp_f32_e32 v0, v0
	v_add_f32_e32 v2, 1.0, v2
	v_rcp_f32_e32 v1, v1
	v_add_f32_e32 v3, 1.0, v8
	v_rcp_f32_e32 v2, v2
	v_rcp_f32_e32 v3, v3
	v_lshlrev_b32_e32 v8, 16, v150
	v_pk_fma_f32 v[130:131], v[0:1], v[8:9], v[10:11]
	v_and_b32_e32 v1, 0xffff0000, v151
	v_and_b32_e32 v0, 0xffff0000, v150
	v_pk_fma_f32 v[138:139], v[2:3], v[0:1], v[140:141]
	v_mov_b32_dpp v226, v225 row_mirror row_mask:0xf bank_mask:0xf bound_ctrl:1
	v_lshlrev_b32_e32 v8, 2, v132
	v_mov_b32_e32 v0, v130
	v_mov_b32_e32 v1, v138
	v_mov_b32_e32 v2, v131
	v_mov_b32_e32 v3, v139
	s_and_b64 vcc, exec, s[6:7]
	global_store_dwordx4 v8, v[0:3], s[2:3]
	s_cbranch_vccnz .LBB0_1177
	s_nop 0
	v_pk_mul_f32 v[0:1], v[128:129], v[130:131]
	v_pk_mul_f32 v[2:3], v[170:171], v[138:139]
	v_lshlrev_b32_e32 v8, 1, v132
	v_cvt_pk_bf16_f32 v1, v1, v3
	v_cvt_pk_bf16_f32 v0, v0, v2
	global_store_dwordx2 v8, v[0:1], s[90:91]
.LBB0_1177:
	s_nop 0
	v_pk_mul_f32 v[0:1], v[130:131], v[130:131]
	v_pk_mul_f32 v[2:3], v[138:139], v[138:139]
	s_waitcnt vmcnt(3)
	v_lshlrev_b32_e32 v9, 16, v149
	v_add_f32_e32 v0, v0, v2
	v_add_f32_e32 v0, v1, v0
	v_fmamk_f32 v1, v133, 0x3a000000, v175
	v_mul_f32_e32 v2, 0x4b800000, v1
	v_cmp_gt_f32_e32 vcc, s93, v1
	v_add_f32_e32 v0, v3, v0
	v_mov_b32_e32 v10, v134
	v_cndmask_b32_e32 v1, v1, v2, vcc
	v_rsq_f32_e32 v1, v1
	v_add_f32_dpp v0, v0, v0 quad_perm:[1,0,3,2] row_mask:0xf bank_mask:0xf bound_ctrl:1
	v_mov_b32_e32 v11, v136
	v_mov_b32_e32 v136, v135
	v_add_f32_dpp v0, v0, v0 quad_perm:[2,3,0,1] row_mask:0xf bank_mask:0xf bound_ctrl:1
	v_add_u32_e32 v138, 0x49800, v173
	s_nop 0
	v_add_f32_dpp v227, v0, v0 row_half_mirror row_mask:0xf bank_mask:0xf bound_ctrl:1
	v_mul_f32_e32 v0, 0x45800000, v1
	v_cndmask_b32_e32 v1, v1, v0, vcc
	v_mul_f32_e32 v0, v39, v1
	v_mul_f32_e32 v3, v47, v1
	v_mul_f32_e32 v0, 0xbfb8aa3b, v0
	v_mul_f32_e32 v2, v35, v1
	v_mul_f32_e32 v3, 0xbfb8aa3b, v3
	v_mul_f32_e32 v1, v43, v1
	v_exp_f32_e32 v0, v0
	v_mul_f32_e32 v2, 0xbfb8aa3b, v2
	v_exp_f32_e32 v3, v3
	v_mul_f32_e32 v1, 0xbfb8aa3b, v1
	v_exp_f32_e32 v2, v2
	v_exp_f32_e32 v8, v1
	v_add_f32_e32 v0, 1.0, v0
	v_add_f32_e32 v1, 1.0, v3
	v_rcp_f32_e32 v0, v0
	v_add_f32_e32 v2, 1.0, v2
	v_rcp_f32_e32 v1, v1
	v_add_f32_e32 v3, 1.0, v8
	v_rcp_f32_e32 v2, v2
	v_rcp_f32_e32 v3, v3
	v_lshlrev_b32_e32 v8, 16, v148
	v_pk_fma_f32 v[130:131], v[0:1], v[8:9], v[10:11]
	v_and_b32_e32 v1, 0xffff0000, v149
	v_and_b32_e32 v0, 0xffff0000, v148
	v_pk_fma_f32 v[132:133], v[2:3], v[0:1], v[136:137]
	v_mov_b32_dpp v228, v227 row_mirror row_mask:0xf bank_mask:0xf bound_ctrl:1
	v_lshlrev_b32_e32 v8, 2, v138
	v_mov_b32_e32 v0, v130
	v_mov_b32_e32 v1, v132
	v_mov_b32_e32 v2, v131
	v_mov_b32_e32 v3, v133
	s_and_b64 vcc, exec, s[6:7]
	global_store_dwordx4 v8, v[0:3], s[2:3]
	s_cbranch_vccnz .LBB0_1179
	s_nop 0
	v_pk_mul_f32 v[0:1], v[128:129], v[130:131]
	v_pk_mul_f32 v[2:3], v[170:171], v[132:133]
	v_and_b32_sdwa v10, v0, v177 dst_sel:DWORD dst_unused:UNUSED_PAD src0_sel:WORD_1 src1_sel:DWORD
	v_add3_u32 v0, v0, v10, s48
	v_and_b32_sdwa v10, v2, v177 dst_sel:DWORD dst_unused:UNUSED_PAD src0_sel:WORD_1 src1_sel:DWORD
	v_add3_u32 v2, v2, v10, s48
	v_and_b32_e32 v2, 0xffff0000, v2
	v_lshlrev_b32_e32 v8, 1, v138
	v_cvt_pk_bf16_f32 v1, v1, v3
	v_or_b32_sdwa v0, v2, v0 dst_sel:DWORD dst_unused:UNUSED_PAD src0_sel:DWORD src1_sel:WORD_1
	global_store_dwordx2 v8, v[0:1], s[90:91]
; __device__ __forceinline__ float bflo(u32 w) { return __uint_as_float(w << 16); }
; __device__ __forceinline__ float bfhi(u32 w) { return __uint_as_float(w & 0xffff0000u); }
; __device__ __forceinline__ u32 pack2(float a, float b) { return (u32)f2bf(a) | ((u32)f2bf(b) << 16); }
; __device__ __forceinline__ float sigmoidf_(float x) { return __builtin_amdgcn_rcpf(1.f + __expf(-x)); }
; __device__ __forceinline__ void gemm_tile(const GemmArgs& ga, int wgid, int next_wgid, bool prefetched, u16* shm, unsigned char* ws, int wv_) {
;     ...
;       if (!GATE) { EPI_LOADS(0, 0) }
;       _Pragma("unroll") for (int bb = 0; bb < 8; ++bb) {
;         const int ai = bb >> 2, m = bb & 3;
;         const int cur = GATE ? 0 : (bb & 1);
;         if (GATE) { EPI_LOADS(bb, 0) }
;         else if (bb < 7) { EPI_LOADS(bb + 1, (bb + 1) & 1) }
;         _Pragma("unroll") for (int j = 0; j < 4; ++j) {
;           int row = rbase + ai * HALF + m * 16 + j;
;           unsigned eo = (unsigned)row * (unsigned)D_ + (unsigned)col0;
;           float s = 1.f;
;           if (GATE) s = rsqrtf(sc[j] * (1.f / D_) + 1e-6f);
;           const float a0 = acc[ai][0][m][0][j], a1 = acc[ai][0][m][1][j], a2 = acc[ai][1][m][0][j], a3 = acc[ai][1][m][1][j];
;           float4 xv = xin[cur][j];
;           if (GATE) {
;             xv.x += ga.live * (bflo(pin[j].x) * sigmoidf_(a0 * s));
;             xv.y += ga.live * (bfhi(pin[j].x) * sigmoidf_(a1 * s));
;             xv.z += ga.live * (bflo(pin[j].y) * sigmoidf_(a2 * s));
;             xv.w += ga.live * (bfhi(pin[j].y) * sigmoidf_(a3 * s));
;           } else {
;             const float al = ga.live * ga.alpha;
;             xv.x += al * a0; xv.y += al * a1; xv.z += al * a2; xv.w += al * a3;
;           }
;           *(float4*)(const_cast<char*>(xb) + (size_t)(eo * 4u)) = xv;
;           if (e_gn) *(uint2*)(ob + (size_t)(eo * 2u)) = make_uint2(pack2(xv.x * gn4.x, xv.y * gn4.y), pack2(xv.z * gn4.z, xv.w * gn4.w));
;           float sq = xv.x * xv.x + xv.y * xv.y + xv.z * xv.z + xv.w * xv.w;
;           sq = red16(sq);
.LBB0_1179:
	s_nop 0
	v_pk_mul_f32 v[0:1], v[130:131], v[130:131]
	v_pk_mul_f32 v[2:3], v[132:133], v[132:133]
	s_nop 0
	v_add_f32_e32 v0, v0, v2
	v_add_f32_e32 v0, v1, v0
	v_add_f32_e32 v0, v3, v0
	s_nop 1
	v_add_f32_dpp v0, v0, v0 quad_perm:[1,0,3,2] row_mask:0xf bank_mask:0xf bound_ctrl:1
	s_nop 1
	v_add_f32_dpp v0, v0, v0 quad_perm:[2,3,0,1] row_mask:0xf bank_mask:0xf bound_ctrl:1
	s_nop 1
	v_add_f32_dpp v229, v0, v0 row_half_mirror row_mask:0xf bank_mask:0xf bound_ctrl:1
	s_nop 1
	v_mov_b32_dpp v230, v229 row_mirror row_mask:0xf bank_mask:0xf bound_ctrl:1
	global_load_dwordx4 v[130:133], v[146:147], off offset:640
	v_add_u32_e32 v0, 0x50000, v198
	v_lshlrev_b32_e32 v30, 2, v0
	v_lshlrev_b32_e32 v166, 1, v0
	global_load_dwordx4 v[0:3], v30, s[78:79]
	v_add_u32_e32 v10, 0x50800, v198
	v_add_u32_e32 v11, 0x51000, v198
	v_add_u32_e32 v16, 0x51800, v198
	v_lshlrev_b32_e32 v17, 2, v10
	global_load_dwordx2 v[8:9], v166, s[8:9]
	v_lshlrev_b32_e32 v10, 1, v10
	v_lshlrev_b32_e32 v18, 2, v11
	v_lshlrev_b32_e32 v11, 1, v11
	v_lshlrev_b32_e32 v19, 2, v16
	v_lshlrev_b32_e32 v16, 1, v16
	global_load_dwordx4 v[142:145], v17, s[78:79]
	global_load_dwordx2 v[152:153], v10, s[8:9]
	global_load_dwordx4 v[138:141], v18, s[78:79]
	global_load_dwordx2 v[150:151], v11, s[8:9]
	global_load_dwordx4 v[134:137], v19, s[78:79]
	global_load_dwordx2 v[148:149], v16, s[8:9]
	s_waitcnt vmcnt(8)
	v_fmamk_f32 v10, v130, 0x3a000000, v175
	s_waitcnt vmcnt(7)
	v_mov_b32_e32 v17, v2
	v_rsq_f32_e32 v18, v10
	v_mov_b32_e32 v16, v0
	s_waitcnt vmcnt(6)
	v_lshlrev_b32_e32 v11, 16, v9
	v_mov_b32_e32 v0, v18
	v_mul_f32_e32 v2, v20, v0
	v_mul_f32_e32 v18, v240, v0
	v_mul_f32_e32 v19, v244, v0
	v_mul_f32_e32 v0, v24, v0
	v_mul_f32_e32 v2, 0xbfb8aa3b, v2
	v_mul_f32_e32 v18, 0xbfb8aa3b, v18
	v_mul_f32_e32 v19, 0xbfb8aa3b, v19
	v_mul_f32_e32 v0, 0xbfb8aa3b, v0
	v_exp_f32_e32 v2, v2
	v_exp_f32_e32 v18, v18
	v_exp_f32_e32 v19, v19
	v_exp_f32_e32 v0, v0
	v_add_f32_e32 v2, 1.0, v2
	v_add_f32_e32 v28, 1.0, v18
	v_add_f32_e32 v19, 1.0, v19
	v_add_f32_e32 v0, 1.0, v0
	v_rcp_f32_e32 v18, v2
	v_rcp_f32_e32 v28, v28
	v_rcp_f32_e32 v19, v19
	v_rcp_f32_e32 v29, v0
	v_lshlrev_b32_e32 v10, 16, v8
	v_and_b32_e32 v9, 0xffff0000, v9
	v_and_b32_e32 v8, 0xffff0000, v8
	v_mov_b32_e32 v2, v1
	v_pk_fma_f32 v[154:155], v[18:19], v[10:11], v[16:17]
	v_pk_fma_f32 v[156:157], v[28:29], v[8:9], v[2:3]
	v_mov_b32_e32 v0, v154
	v_mov_b32_e32 v1, v156
	v_mov_b32_e32 v2, v155
	v_mov_b32_e32 v3, v157
	s_and_b64 vcc, exec, s[6:7]
	global_store_dwordx4 v30, v[0:3], s[2:3]
	s_cbranch_vccnz .LBB0_1181
	s_nop 0
	v_pk_mul_f32 v[0:1], v[128:129], v[154:155]
	v_pk_mul_f32 v[2:3], v[170:171], v[156:157]
	v_lshl_add_u64 v[8:9], s[90:91], 0, v[166:167]
	v_cvt_pk_bf16_f32 v1, v1, v3
	v_cvt_pk_bf16_f32 v0, v0, v2
	global_store_dwordx2 v[8:9], v[0:1], off
.LBB0_1181:
	s_nop 0
	v_pk_mul_f32 v[0:1], v[154:155], v[154:155]
	v_pk_mul_f32 v[2:3], v[156:157], v[156:157]
	s_waitcnt vmcnt(5)
	v_lshlrev_b32_e32 v9, 16, v153
	v_add_f32_e32 v0, v0, v2
	v_add_f32_e32 v0, v1, v0
	v_fmamk_f32 v1, v131, 0x3a000000, v175
	v_mul_f32_e32 v2, 0x4b800000, v1
	v_cmp_gt_f32_e32 vcc, s93, v1
	v_add_f32_e32 v0, v3, v0
	v_mov_b32_e32 v10, v142
	v_cndmask_b32_e32 v1, v1, v2, vcc
	v_rsq_f32_e32 v1, v1
	v_add_f32_dpp v0, v0, v0 quad_perm:[1,0,3,2] row_mask:0xf bank_mask:0xf bound_ctrl:1
	v_mov_b32_e32 v11, v144
	v_mov_b32_e32 v144, v143
	v_add_f32_dpp v0, v0, v0 quad_perm:[2,3,0,1] row_mask:0xf bank_mask:0xf bound_ctrl:1
	v_add_u32_e32 v154, 0x50800, v173
	s_nop 0
	v_add_f32_dpp v156, v0, v0 row_half_mirror row_mask:0xf bank_mask:0xf bound_ctrl:1
	v_mul_f32_e32 v0, 0x45800000, v1
	v_cndmask_b32_e32 v1, v1, v0, vcc
	v_mul_f32_e32 v0, v21, v1
	v_mul_f32_e32 v3, v245, v1
	v_mul_f32_e32 v0, 0xbfb8aa3b, v0
	v_mul_f32_e32 v2, v241, v1
	v_mul_f32_e32 v3, 0xbfb8aa3b, v3
	v_mul_f32_e32 v1, v25, v1
	v_exp_f32_e32 v0, v0
	v_mul_f32_e32 v2, 0xbfb8aa3b, v2
	v_exp_f32_e32 v3, v3
	v_mul_f32_e32 v1, 0xbfb8aa3b, v1
	v_exp_f32_e32 v2, v2
	v_exp_f32_e32 v8, v1
	v_add_f32_e32 v0, 1.0, v0
	v_add_f32_e32 v1, 1.0, v3
	v_rcp_f32_e32 v0, v0
	v_add_f32_e32 v2, 1.0, v2
	v_rcp_f32_e32 v1, v1
	v_add_f32_e32 v3, 1.0, v8
	v_rcp_f32_e32 v2, v2
	v_rcp_f32_e32 v3, v3
	v_lshlrev_b32_e32 v8, 16, v152
	v_pk_fma_f32 v[130:131], v[0:1], v[8:9], v[10:11]
	v_and_b32_e32 v1, 0xffff0000, v153
	v_and_b32_e32 v0, 0xffff0000, v152
	v_pk_fma_f32 v[142:143], v[2:3], v[0:1], v[144:145]
	v_mov_b32_dpp v157, v156 row_mirror row_mask:0xf bank_mask:0xf bound_ctrl:1
	v_lshlrev_b32_e32 v8, 2, v154
	v_mov_b32_e32 v0, v130
	v_mov_b32_e32 v1, v142
	v_mov_b32_e32 v2, v131
	v_mov_b32_e32 v3, v143
	s_and_b64 vcc, exec, s[6:7]
	global_store_dwordx4 v8, v[0:3], s[2:3]
	s_cbranch_vccnz .LBB0_1183
	s_nop 0
	v_pk_mul_f32 v[0:1], v[128:129], v[130:131]
	v_pk_mul_f32 v[2:3], v[170:171], v[142:143]
	v_lshlrev_b32_e32 v8, 1, v154
	v_cvt_pk_bf16_f32 v1, v1, v3
	v_cvt_pk_bf16_f32 v0, v0, v2
	global_store_dwordx2 v8, v[0:1], s[90:91]
; __device__ __forceinline__ float bflo(u32 w) { return __uint_as_float(w << 16); }
; __device__ __forceinline__ float bfhi(u32 w) { return __uint_as_float(w & 0xffff0000u); }
; __device__ __forceinline__ u32 pack2(float a, float b) { return (u32)f2bf(a) | ((u32)f2bf(b) << 16); }
; __device__ __forceinline__ float sigmoidf_(float x) { return __builtin_amdgcn_rcpf(1.f + __expf(-x)); }
; __device__ __forceinline__ void gemm_tile(const GemmArgs& ga, int wgid, int next_wgid, bool prefetched, u16* shm, unsigned char* ws, int wv_) {
;     ...
;       if (!GATE) { EPI_LOADS(0, 0) }
;       _Pragma("unroll") for (int bb = 0; bb < 8; ++bb) {
;         const int ai = bb >> 2, m = bb & 3;
;         const int cur = GATE ? 0 : (bb & 1);
;         if (GATE) { EPI_LOADS(bb, 0) }
;         else if (bb < 7) { EPI_LOADS(bb + 1, (bb + 1) & 1) }
;         _Pragma("unroll") for (int j = 0; j < 4; ++j) {
;           int row = rbase + ai * HALF + m * 16 + j;
;           unsigned eo = (unsigned)row * (unsigned)D_ + (unsigned)col0;
;           float s = 1.f;
;           if (GATE) s = rsqrtf(sc[j] * (1.f / D_) + 1e-6f);
;           const float a0 = acc[ai][0][m][0][j], a1 = acc[ai][0][m][1][j], a2 = acc[ai][1][m][0][j], a3 = acc[ai][1][m][1][j];
;           float4 xv = xin[cur][j];
;           if (GATE) {
;             xv.x += ga.live * (bflo(pin[j].x) * sigmoidf_(a0 * s));
;             xv.y += ga.live * (bfhi(pin[j].x) * sigmoidf_(a1 * s));
;             xv.z += ga.live * (bflo(pin[j].y) * sigmoidf_(a2 * s));
;             xv.w += ga.live * (bfhi(pin[j].y) * sigmoidf_(a3 * s));
;           } else {
;             const float al = ga.live * ga.alpha;
;             xv.x += al * a0; xv.y += al * a1; xv.z += al * a2; xv.w += al * a3;
;           }
;           *(float4*)(const_cast<char*>(xb) + (size_t)(eo * 4u)) = xv;
;           if (e_gn) *(uint2*)(ob + (size_t)(eo * 2u)) = make_uint2(pack2(xv.x * gn4.x, xv.y * gn4.y), pack2(xv.z * gn4.z, xv.w * gn4.w));
;           float sq = xv.x * xv.x + xv.y * xv.y + xv.z * xv.z + xv.w * xv.w;
;           sq = red16(sq);
.LBB0_1183:
	s_nop 0
	v_pk_mul_f32 v[0:1], v[130:131], v[130:131]
	v_pk_mul_f32 v[2:3], v[142:143], v[142:143]
	s_waitcnt vmcnt(4)
	v_lshlrev_b32_e32 v9, 16, v151
	v_add_f32_e32 v0, v0, v2
	v_add_f32_e32 v0, v1, v0
	v_fmamk_f32 v1, v132, 0x3a000000, v175
	v_mul_f32_e32 v2, 0x4b800000, v1
	v_cmp_gt_f32_e32 vcc, s93, v1
	v_add_f32_e32 v0, v3, v0
	v_mov_b32_e32 v10, v138
	v_cndmask_b32_e32 v1, v1, v2, vcc
	v_rsq_f32_e32 v1, v1
	v_add_f32_dpp v0, v0, v0 quad_perm:[1,0,3,2] row_mask:0xf bank_mask:0xf bound_ctrl:1
	v_mov_b32_e32 v11, v140
	v_mov_b32_e32 v140, v139
	v_add_f32_dpp v0, v0, v0 quad_perm:[2,3,0,1] row_mask:0xf bank_mask:0xf bound_ctrl:1
	v_add_u32_e32 v132, 0x51000, v173
	s_mov_b32 s84, s56
	v_add_f32_dpp v231, v0, v0 row_half_mirror row_mask:0xf bank_mask:0xf bound_ctrl:1
	v_mul_f32_e32 v0, 0x45800000, v1
	v_cndmask_b32_e32 v1, v1, v0, vcc
	v_mul_f32_e32 v0, v22, v1
	v_mul_f32_e32 v3, v246, v1
	v_mul_f32_e32 v0, 0xbfb8aa3b, v0
	v_mul_f32_e32 v2, v242, v1
	v_mul_f32_e32 v3, 0xbfb8aa3b, v3
	v_mul_f32_e32 v1, v26, v1
	v_exp_f32_e32 v0, v0
	v_mul_f32_e32 v2, 0xbfb8aa3b, v2
	v_exp_f32_e32 v3, v3
	v_mul_f32_e32 v1, 0xbfb8aa3b, v1
	v_exp_f32_e32 v2, v2
	v_exp_f32_e32 v8, v1
	v_add_f32_e32 v0, 1.0, v0
	v_add_f32_e32 v1, 1.0, v3
	v_rcp_f32_e32 v0, v0
	v_add_f32_e32 v2, 1.0, v2
	v_rcp_f32_e32 v1, v1
	v_add_f32_e32 v3, 1.0, v8
	v_rcp_f32_e32 v2, v2
	v_rcp_f32_e32 v3, v3
	v_lshlrev_b32_e32 v8, 16, v150
	v_pk_fma_f32 v[130:131], v[0:1], v[8:9], v[10:11]
	v_and_b32_e32 v1, 0xffff0000, v151
	v_and_b32_e32 v0, 0xffff0000, v150
	v_pk_fma_f32 v[138:139], v[2:3], v[0:1], v[140:141]
	v_mov_b32_dpp v232, v231 row_mirror row_mask:0xf bank_mask:0xf bound_ctrl:1
	v_lshlrev_b32_e32 v8, 2, v132
	v_mov_b32_e32 v0, v130
	v_mov_b32_e32 v1, v138
	v_mov_b32_e32 v2, v131
	v_mov_b32_e32 v3, v139
	s_and_b64 vcc, exec, s[6:7]
	global_store_dwordx4 v8, v[0:3], s[2:3]
	s_cbranch_vccnz .LBB0_1185
	s_nop 0
	v_pk_mul_f32 v[0:1], v[128:129], v[130:131]
	v_pk_mul_f32 v[2:3], v[170:171], v[138:139]
	v_lshlrev_b32_e32 v8, 1, v132
	v_cvt_pk_bf16_f32 v1, v1, v3
	v_cvt_pk_bf16_f32 v0, v0, v2
	global_store_dwordx2 v8, v[0:1], s[90:91]
.LBB0_1185:
	s_nop 0
	v_pk_mul_f32 v[0:1], v[130:131], v[130:131]
	v_pk_mul_f32 v[2:3], v[138:139], v[138:139]
	s_waitcnt vmcnt(3)
	v_lshlrev_b32_e32 v9, 16, v149
	v_add_f32_e32 v0, v0, v2
	v_add_f32_e32 v0, v1, v0
	v_fmamk_f32 v1, v133, 0x3a000000, v175
	v_mul_f32_e32 v2, 0x4b800000, v1
	v_cmp_gt_f32_e32 vcc, s93, v1
	v_add_f32_e32 v0, v3, v0
	v_mov_b32_e32 v10, v134
	v_cndmask_b32_e32 v1, v1, v2, vcc
	v_rsq_f32_e32 v1, v1
	v_add_f32_dpp v0, v0, v0 quad_perm:[1,0,3,2] row_mask:0xf bank_mask:0xf bound_ctrl:1
	v_mov_b32_e32 v11, v136
	v_mov_b32_e32 v136, v135
	v_add_f32_dpp v0, v0, v0 quad_perm:[2,3,0,1] row_mask:0xf bank_mask:0xf bound_ctrl:1
	v_add_u32_e32 v138, 0x51800, v173
	s_mov_b32 s57, s60
	v_add_f32_dpp v233, v0, v0 row_half_mirror row_mask:0xf bank_mask:0xf bound_ctrl:1
	v_mul_f32_e32 v0, 0x45800000, v1
	v_cndmask_b32_e32 v1, v1, v0, vcc
	v_mul_f32_e32 v0, v23, v1
	v_mul_f32_e32 v3, v247, v1
	v_mul_f32_e32 v0, 0xbfb8aa3b, v0
	v_mul_f32_e32 v2, v243, v1
	v_mul_f32_e32 v3, 0xbfb8aa3b, v3
	v_mul_f32_e32 v1, v27, v1
	v_exp_f32_e32 v0, v0
	v_mul_f32_e32 v2, 0xbfb8aa3b, v2
	v_exp_f32_e32 v3, v3
	v_mul_f32_e32 v1, 0xbfb8aa3b, v1
	v_exp_f32_e32 v2, v2
	v_exp_f32_e32 v8, v1
	v_add_f32_e32 v0, 1.0, v0
	v_add_f32_e32 v1, 1.0, v3
	v_rcp_f32_e32 v0, v0
	v_add_f32_e32 v2, 1.0, v2
	v_rcp_f32_e32 v1, v1
	v_add_f32_e32 v3, 1.0, v8
	v_rcp_f32_e32 v2, v2
	v_rcp_f32_e32 v3, v3
	v_lshlrev_b32_e32 v8, 16, v148
	v_pk_fma_f32 v[130:131], v[0:1], v[8:9], v[10:11]
	v_and_b32_e32 v1, 0xffff0000, v149
	v_and_b32_e32 v0, 0xffff0000, v148
	v_pk_fma_f32 v[132:133], v[2:3], v[0:1], v[136:137]
	v_mov_b32_dpp v234, v233 row_mirror row_mask:0xf bank_mask:0xf bound_ctrl:1
	v_lshlrev_b32_e32 v8, 2, v138
	v_mov_b32_e32 v0, v130
	v_mov_b32_e32 v1, v132
	v_mov_b32_e32 v2, v131
	v_mov_b32_e32 v3, v133
	s_and_b64 vcc, exec, s[6:7]
	global_store_dwordx4 v8, v[0:3], s[2:3]
	s_cbranch_vccnz .LBB0_1187
	s_nop 0
	v_pk_mul_f32 v[0:1], v[128:129], v[130:131]
	v_pk_mul_f32 v[2:3], v[170:171], v[132:133]
	v_and_b32_sdwa v10, v0, v177 dst_sel:DWORD dst_unused:UNUSED_PAD src0_sel:WORD_1 src1_sel:DWORD
	v_add3_u32 v0, v0, v10, s48
	v_and_b32_sdwa v10, v2, v177 dst_sel:DWORD dst_unused:UNUSED_PAD src0_sel:WORD_1 src1_sel:DWORD
	v_add3_u32 v2, v2, v10, s48
	v_and_b32_e32 v2, 0xffff0000, v2
	v_lshlrev_b32_e32 v8, 1, v138
	v_cvt_pk_bf16_f32 v1, v1, v3
	v_or_b32_sdwa v0, v2, v0 dst_sel:DWORD dst_unused:UNUSED_PAD src0_sel:DWORD src1_sel:WORD_1
	global_store_dwordx2 v8, v[0:1], s[90:91]
; __device__ __forceinline__ float bflo(u32 w) { return __uint_as_float(w << 16); }
; __device__ __forceinline__ float bfhi(u32 w) { return __uint_as_float(w & 0xffff0000u); }
; __device__ __forceinline__ u32 pack2(float a, float b) { return (u32)f2bf(a) | ((u32)f2bf(b) << 16); }
; __device__ __forceinline__ float sigmoidf_(float x) { return __builtin_amdgcn_rcpf(1.f + __expf(-x)); }
; __device__ __forceinline__ void gemm_tile(const GemmArgs& ga, int wgid, int next_wgid, bool prefetched, u16* shm, unsigned char* ws, int wv_) {
;     ...
;       if (!GATE) { EPI_LOADS(0, 0) }
;       _Pragma("unroll") for (int bb = 0; bb < 8; ++bb) {
;         const int ai = bb >> 2, m = bb & 3;
;         const int cur = GATE ? 0 : (bb & 1);
;         if (GATE) { EPI_LOADS(bb, 0) }
;         else if (bb < 7) { EPI_LOADS(bb + 1, (bb + 1) & 1) }
;         _Pragma("unroll") for (int j = 0; j < 4; ++j) {
;           int row = rbase + ai * HALF + m * 16 + j;
;           unsigned eo = (unsigned)row * (unsigned)D_ + (unsigned)col0;
;           float s = 1.f;
;           if (GATE) s = rsqrtf(sc[j] * (1.f / D_) + 1e-6f);
;           const float a0 = acc[ai][0][m][0][j], a1 = acc[ai][0][m][1][j], a2 = acc[ai][1][m][0][j], a3 = acc[ai][1][m][1][j];
;           float4 xv = xin[cur][j];
;           if (GATE) {
;             xv.x += ga.live * (bflo(pin[j].x) * sigmoidf_(a0 * s));
;             xv.y += ga.live * (bfhi(pin[j].x) * sigmoidf_(a1 * s));
;             xv.z += ga.live * (bflo(pin[j].y) * sigmoidf_(a2 * s));
;             xv.w += ga.live * (bfhi(pin[j].y) * sigmoidf_(a3 * s));
;           } else {
;             const float al = ga.live * ga.alpha;
;             xv.x += al * a0; xv.y += al * a1; xv.z += al * a2; xv.w += al * a3;
;           }
;           *(float4*)(const_cast<char*>(xb) + (size_t)(eo * 4u)) = xv;
;           if (e_gn) *(uint2*)(ob + (size_t)(eo * 2u)) = make_uint2(pack2(xv.x * gn4.x, xv.y * gn4.y), pack2(xv.z * gn4.z, xv.w * gn4.w));
;           float sq = xv.x * xv.x + xv.y * xv.y + xv.z * xv.z + xv.w * xv.w;
;           sq = red16(sq);
.LBB0_1187:
	s_nop 0
	v_pk_mul_f32 v[0:1], v[130:131], v[130:131]
	v_pk_mul_f32 v[2:3], v[132:133], v[132:133]
	s_mov_b64 s[60:61], s[88:89]
	v_add_f32_e32 v0, v0, v2
	v_add_f32_e32 v0, v1, v0
	v_add_f32_e32 v0, v3, v0
	s_nop 1
	v_add_f32_dpp v0, v0, v0 quad_perm:[1,0,3,2] row_mask:0xf bank_mask:0xf bound_ctrl:1
	s_nop 1
	v_add_f32_dpp v0, v0, v0 quad_perm:[2,3,0,1] row_mask:0xf bank_mask:0xf bound_ctrl:1
	s_nop 1
	v_add_f32_dpp v235, v0, v0 row_half_mirror row_mask:0xf bank_mask:0xf bound_ctrl:1
	s_nop 1
	v_mov_b32_dpp v236, v235 row_mirror row_mask:0xf bank_mask:0xf bound_ctrl:1
	global_load_dwordx4 v[130:133], v[146:147], off offset:704
	v_add_u32_e32 v0, 0x58000, v198
	v_lshlrev_b32_e32 v30, 2, v0
	v_lshlrev_b32_e32 v166, 1, v0
	global_load_dwordx4 v[0:3], v30, s[78:79]
	v_add_u32_e32 v10, 0x58800, v198
	v_add_u32_e32 v11, 0x59000, v198
	v_add_u32_e32 v16, 0x59800, v198
	v_lshlrev_b32_e32 v17, 2, v10
	global_load_dwordx2 v[8:9], v166, s[8:9]
	v_lshlrev_b32_e32 v10, 1, v10
	v_lshlrev_b32_e32 v18, 2, v11
	v_lshlrev_b32_e32 v11, 1, v11
	v_lshlrev_b32_e32 v19, 2, v16
	v_lshlrev_b32_e32 v16, 1, v16
	global_load_dwordx4 v[142:145], v17, s[78:79]
	global_load_dwordx2 v[150:151], v10, s[8:9]
	global_load_dwordx4 v[138:141], v18, s[78:79]
	global_load_dwordx2 v[148:149], v11, s[8:9]
	global_load_dwordx4 v[134:137], v19, s[78:79]
	global_load_dwordx2 v[146:147], v16, s[8:9]
	s_waitcnt vmcnt(8)
	v_fmamk_f32 v10, v130, 0x3a000000, v175
	s_waitcnt vmcnt(7)
	v_mov_b32_e32 v17, v2
	v_rsq_f32_e32 v18, v10
	v_mov_b32_e32 v16, v0
	s_waitcnt vmcnt(6)
	v_lshlrev_b32_e32 v11, 16, v9
	v_mov_b32_e32 v0, v18
	v_mul_f32_e32 v2, v204, v0
	v_mul_f32_e32 v18, v182, v0
	v_mul_f32_e32 v19, v12, v0
	v_mul_f32_e32 v0, v4, v0
	v_mul_f32_e32 v2, 0xbfb8aa3b, v2
	v_mul_f32_e32 v18, 0xbfb8aa3b, v18
	v_mul_f32_e32 v19, 0xbfb8aa3b, v19
	v_mul_f32_e32 v0, 0xbfb8aa3b, v0
	v_exp_f32_e32 v2, v2
	v_exp_f32_e32 v18, v18
	v_exp_f32_e32 v19, v19
	v_exp_f32_e32 v0, v0
	v_add_f32_e32 v2, 1.0, v2
	v_add_f32_e32 v28, 1.0, v18
	v_add_f32_e32 v19, 1.0, v19
	v_add_f32_e32 v0, 1.0, v0
	v_rcp_f32_e32 v18, v2
	v_rcp_f32_e32 v28, v28
	v_rcp_f32_e32 v19, v19
	v_rcp_f32_e32 v29, v0
	v_lshlrev_b32_e32 v10, 16, v8
	v_and_b32_e32 v9, 0xffff0000, v9
	v_and_b32_e32 v8, 0xffff0000, v8
	v_mov_b32_e32 v2, v1
	v_pk_fma_f32 v[152:153], v[18:19], v[10:11], v[16:17]
	v_pk_fma_f32 v[154:155], v[28:29], v[8:9], v[2:3]
	v_mov_b32_e32 v0, v152
	v_mov_b32_e32 v1, v154
	v_mov_b32_e32 v2, v153
	v_mov_b32_e32 v3, v155
	s_and_b64 vcc, exec, s[6:7]
	global_store_dwordx4 v30, v[0:3], s[2:3]
	s_cbranch_vccnz .LBB0_1189
	s_nop 0
	v_pk_mul_f32 v[0:1], v[128:129], v[152:153]
	v_pk_mul_f32 v[2:3], v[170:171], v[154:155]
	v_lshl_add_u64 v[8:9], s[90:91], 0, v[166:167]
	v_cvt_pk_bf16_f32 v1, v1, v3
	v_cvt_pk_bf16_f32 v0, v0, v2
	global_store_dwordx2 v[8:9], v[0:1], off
.LBB0_1189:
	s_nop 0
	v_pk_mul_f32 v[0:1], v[152:153], v[152:153]
	v_pk_mul_f32 v[2:3], v[154:155], v[154:155]
	s_waitcnt vmcnt(5)
	v_lshlrev_b32_e32 v9, 16, v151
	v_add_f32_e32 v0, v0, v2
	v_add_f32_e32 v0, v1, v0
	v_fmamk_f32 v1, v131, 0x3a000000, v175
	v_mul_f32_e32 v2, 0x4b800000, v1
	v_cmp_gt_f32_e32 vcc, s93, v1
	v_add_f32_e32 v0, v3, v0
	v_mov_b32_e32 v10, v142
	v_cndmask_b32_e32 v1, v1, v2, vcc
	v_rsq_f32_e32 v1, v1
	v_add_f32_dpp v0, v0, v0 quad_perm:[1,0,3,2] row_mask:0xf bank_mask:0xf bound_ctrl:1
	v_mov_b32_e32 v11, v144
	v_mov_b32_e32 v144, v143
	v_add_f32_dpp v0, v0, v0 quad_perm:[2,3,0,1] row_mask:0xf bank_mask:0xf bound_ctrl:1
	v_add_u32_e32 v154, 0x58800, v173
	s_mov_b32 s56, s63
	v_add_f32_dpp v152, v0, v0 row_half_mirror row_mask:0xf bank_mask:0xf bound_ctrl:1
	v_mul_f32_e32 v0, 0x45800000, v1
	v_cndmask_b32_e32 v1, v1, v0, vcc
	v_mul_f32_e32 v0, v205, v1
	v_mul_f32_e32 v3, v13, v1
	v_mul_f32_e32 v0, 0xbfb8aa3b, v0
	v_mul_f32_e32 v2, v183, v1
	v_mul_f32_e32 v3, 0xbfb8aa3b, v3
	v_mul_f32_e32 v1, v5, v1
	v_exp_f32_e32 v0, v0
	v_mul_f32_e32 v2, 0xbfb8aa3b, v2
	v_exp_f32_e32 v3, v3
	v_mul_f32_e32 v1, 0xbfb8aa3b, v1
	v_exp_f32_e32 v2, v2
	v_exp_f32_e32 v8, v1
	v_add_f32_e32 v0, 1.0, v0
	v_add_f32_e32 v1, 1.0, v3
	v_rcp_f32_e32 v0, v0
	v_add_f32_e32 v2, 1.0, v2
	v_rcp_f32_e32 v1, v1
	v_add_f32_e32 v3, 1.0, v8
	v_rcp_f32_e32 v2, v2
	v_rcp_f32_e32 v3, v3
	v_lshlrev_b32_e32 v8, 16, v150
	v_pk_fma_f32 v[130:131], v[0:1], v[8:9], v[10:11]
	v_and_b32_e32 v1, 0xffff0000, v151
	v_and_b32_e32 v0, 0xffff0000, v150
	v_pk_fma_f32 v[142:143], v[2:3], v[0:1], v[144:145]
	v_mov_b32_dpp v153, v152 row_mirror row_mask:0xf bank_mask:0xf bound_ctrl:1
	v_lshlrev_b32_e32 v8, 2, v154
	v_mov_b32_e32 v0, v130
	v_mov_b32_e32 v1, v142
	v_mov_b32_e32 v2, v131
	v_mov_b32_e32 v3, v143
	s_and_b64 vcc, exec, s[6:7]
	global_store_dwordx4 v8, v[0:3], s[2:3]
	s_cbranch_vccnz .LBB0_1191
	s_nop 0
	v_pk_mul_f32 v[0:1], v[128:129], v[130:131]
	v_pk_mul_f32 v[2:3], v[170:171], v[142:143]
	v_lshlrev_b32_e32 v8, 1, v154
	v_cvt_pk_bf16_f32 v1, v1, v3
	v_cvt_pk_bf16_f32 v0, v0, v2
	global_store_dwordx2 v8, v[0:1], s[90:91]
; __device__ __forceinline__ float bflo(u32 w) { return __uint_as_float(w << 16); }
; __device__ __forceinline__ float bfhi(u32 w) { return __uint_as_float(w & 0xffff0000u); }
; __device__ __forceinline__ u32 pack2(float a, float b) { return (u32)f2bf(a) | ((u32)f2bf(b) << 16); }
; __device__ __forceinline__ float sigmoidf_(float x) { return __builtin_amdgcn_rcpf(1.f + __expf(-x)); }
; __device__ __forceinline__ void gemm_tile(const GemmArgs& ga, int wgid, int next_wgid, bool prefetched, u16* shm, unsigned char* ws, int wv_) {
;     ...
;       if (!GATE) { EPI_LOADS(0, 0) }
;       _Pragma("unroll") for (int bb = 0; bb < 8; ++bb) {
;         const int ai = bb >> 2, m = bb & 3;
;         const int cur = GATE ? 0 : (bb & 1);
;         if (GATE) { EPI_LOADS(bb, 0) }
;         else if (bb < 7) { EPI_LOADS(bb + 1, (bb + 1) & 1) }
;         _Pragma("unroll") for (int j = 0; j < 4; ++j) {
;           int row = rbase + ai * HALF + m * 16 + j;
;           unsigned eo = (unsigned)row * (unsigned)D_ + (unsigned)col0;
;           float s = 1.f;
;           if (GATE) s = rsqrtf(sc[j] * (1.f / D_) + 1e-6f);
;           const float a0 = acc[ai][0][m][0][j], a1 = acc[ai][0][m][1][j], a2 = acc[ai][1][m][0][j], a3 = acc[ai][1][m][1][j];
;           float4 xv = xin[cur][j];
;           if (GATE) {
;             xv.x += ga.live * (bflo(pin[j].x) * sigmoidf_(a0 * s));
;             xv.y += ga.live * (bfhi(pin[j].x) * sigmoidf_(a1 * s));
;             xv.z += ga.live * (bflo(pin[j].y) * sigmoidf_(a2 * s));
;             xv.w += ga.live * (bfhi(pin[j].y) * sigmoidf_(a3 * s));
;           } else {
;             const float al = ga.live * ga.alpha;
;             xv.x += al * a0; xv.y += al * a1; xv.z += al * a2; xv.w += al * a3;
;           }
;           *(float4*)(const_cast<char*>(xb) + (size_t)(eo * 4u)) = xv;
;           if (e_gn) *(uint2*)(ob + (size_t)(eo * 2u)) = make_uint2(pack2(xv.x * gn4.x, xv.y * gn4.y), pack2(xv.z * gn4.z, xv.w * gn4.w));
;           float sq = xv.x * xv.x + xv.y * xv.y + xv.z * xv.z + xv.w * xv.w;
;           sq = red16(sq);
.LBB0_1191:
	s_nop 0
	v_pk_mul_f32 v[0:1], v[130:131], v[130:131]
	v_pk_mul_f32 v[2:3], v[142:143], v[142:143]
	s_waitcnt vmcnt(4)
	v_lshlrev_b32_e32 v9, 16, v149
	v_add_f32_e32 v0, v0, v2
	v_add_f32_e32 v0, v1, v0
	v_fmamk_f32 v1, v132, 0x3a000000, v175
	v_mul_f32_e32 v2, 0x4b800000, v1
	v_cmp_gt_f32_e32 vcc, s93, v1
	v_add_f32_e32 v0, v3, v0
	v_mov_b32_e32 v10, v138
	v_cndmask_b32_e32 v1, v1, v2, vcc
	v_rsq_f32_e32 v1, v1
	v_add_f32_dpp v0, v0, v0 quad_perm:[1,0,3,2] row_mask:0xf bank_mask:0xf bound_ctrl:1
	v_mov_b32_e32 v11, v140
	v_mov_b32_e32 v140, v139
	v_add_f32_dpp v0, v0, v0 quad_perm:[2,3,0,1] row_mask:0xf bank_mask:0xf bound_ctrl:1
	v_add_u32_e32 v132, 0x59000, v173
	s_mov_b32 s63, s35
	v_add_f32_dpp v142, v0, v0 row_half_mirror row_mask:0xf bank_mask:0xf bound_ctrl:1
	v_mul_f32_e32 v0, 0x45800000, v1
	v_cndmask_b32_e32 v1, v1, v0, vcc
	v_mul_f32_e32 v0, v206, v1
	v_mul_f32_e32 v3, v14, v1
	v_mul_f32_e32 v0, 0xbfb8aa3b, v0
	v_mul_f32_e32 v2, v184, v1
	v_mul_f32_e32 v3, 0xbfb8aa3b, v3
	v_mul_f32_e32 v1, v6, v1
	v_exp_f32_e32 v0, v0
	v_mul_f32_e32 v2, 0xbfb8aa3b, v2
	v_exp_f32_e32 v3, v3
	v_mul_f32_e32 v1, 0xbfb8aa3b, v1
	v_exp_f32_e32 v2, v2
	v_exp_f32_e32 v8, v1
	v_add_f32_e32 v0, 1.0, v0
	v_add_f32_e32 v1, 1.0, v3
	v_rcp_f32_e32 v0, v0
	v_add_f32_e32 v2, 1.0, v2
	v_rcp_f32_e32 v1, v1
	v_add_f32_e32 v3, 1.0, v8
	v_rcp_f32_e32 v2, v2
	v_rcp_f32_e32 v3, v3
	v_lshlrev_b32_e32 v8, 16, v148
	v_pk_fma_f32 v[130:131], v[0:1], v[8:9], v[10:11]
	v_and_b32_e32 v1, 0xffff0000, v149
	v_and_b32_e32 v0, 0xffff0000, v148
	v_pk_fma_f32 v[138:139], v[2:3], v[0:1], v[140:141]
	v_mov_b32_dpp v143, v142 row_mirror row_mask:0xf bank_mask:0xf bound_ctrl:1
	v_lshlrev_b32_e32 v8, 2, v132
	v_mov_b32_e32 v0, v130
	v_mov_b32_e32 v1, v138
	v_mov_b32_e32 v2, v131
	v_mov_b32_e32 v3, v139
	s_and_b64 vcc, exec, s[6:7]
	global_store_dwordx4 v8, v[0:3], s[2:3]
	s_cbranch_vccnz .LBB0_1193
	s_nop 0
	v_pk_mul_f32 v[0:1], v[128:129], v[130:131]
	v_pk_mul_f32 v[2:3], v[170:171], v[138:139]
	v_lshlrev_b32_e32 v8, 1, v132
	v_cvt_pk_bf16_f32 v1, v1, v3
	v_cvt_pk_bf16_f32 v0, v0, v2
	global_store_dwordx2 v8, v[0:1], s[90:91]
.LBB0_1193:
	s_nop 0
	v_pk_mul_f32 v[0:1], v[130:131], v[130:131]
	v_pk_mul_f32 v[2:3], v[138:139], v[138:139]
	s_waitcnt vmcnt(3)
	v_lshlrev_b32_e32 v9, 16, v147
	v_add_f32_e32 v0, v0, v2
	v_add_f32_e32 v0, v1, v0
	v_fmamk_f32 v1, v133, 0x3a000000, v175
	v_mul_f32_e32 v2, 0x4b800000, v1
	v_cmp_gt_f32_e32 vcc, s93, v1
	v_add_f32_e32 v0, v3, v0
	v_mov_b32_e32 v10, v134
	v_cndmask_b32_e32 v1, v1, v2, vcc
	v_rsq_f32_e32 v1, v1
	v_add_f32_dpp v0, v0, v0 quad_perm:[1,0,3,2] row_mask:0xf bank_mask:0xf bound_ctrl:1
	v_mov_b32_e32 v11, v136
	v_mov_b32_e32 v136, v135
	v_add_f32_dpp v0, v0, v0 quad_perm:[2,3,0,1] row_mask:0xf bank_mask:0xf bound_ctrl:1
	v_add_u32_e32 v140, 0x59800, v173
	s_mov_b64 s[82:83], s[18:19]
	v_add_f32_dpp v138, v0, v0 row_half_mirror row_mask:0xf bank_mask:0xf bound_ctrl:1
	v_mul_f32_e32 v0, 0x45800000, v1
	v_cndmask_b32_e32 v1, v1, v0, vcc
	v_mul_f32_e32 v0, v207, v1
	v_mul_f32_e32 v3, v15, v1
	v_mul_f32_e32 v0, 0xbfb8aa3b, v0
	v_mul_f32_e32 v2, v185, v1
	v_mul_f32_e32 v3, 0xbfb8aa3b, v3
	v_mul_f32_e32 v1, v7, v1
	v_exp_f32_e32 v0, v0
	v_mul_f32_e32 v2, 0xbfb8aa3b, v2
	v_exp_f32_e32 v3, v3
	v_mul_f32_e32 v1, 0xbfb8aa3b, v1
	v_exp_f32_e32 v2, v2
	v_exp_f32_e32 v8, v1
	v_add_f32_e32 v0, 1.0, v0
	v_add_f32_e32 v1, 1.0, v3
	v_rcp_f32_e32 v0, v0
	v_add_f32_e32 v2, 1.0, v2
	v_rcp_f32_e32 v1, v1
	v_add_f32_e32 v3, 1.0, v8
	v_rcp_f32_e32 v2, v2
	v_rcp_f32_e32 v3, v3
	v_lshlrev_b32_e32 v8, 16, v146
	v_pk_fma_f32 v[130:131], v[0:1], v[8:9], v[10:11]
	v_and_b32_e32 v1, 0xffff0000, v147
	v_and_b32_e32 v0, 0xffff0000, v146
	v_pk_fma_f32 v[132:133], v[2:3], v[0:1], v[136:137]
	s_mov_b64 s[88:89], s[40:41]
	v_mov_b32_dpp v139, v138 row_mirror row_mask:0xf bank_mask:0xf bound_ctrl:1
	v_lshlrev_b32_e32 v8, 2, v140
	v_mov_b32_e32 v0, v130
	v_mov_b32_e32 v1, v132
	v_mov_b32_e32 v2, v131
	v_mov_b32_e32 v3, v133
	s_and_b64 vcc, exec, s[6:7]
	global_store_dwordx4 v8, v[0:3], s[2:3]
	s_cbranch_vccnz .LBB0_1195
	s_nop 0
	v_pk_mul_f32 v[0:1], v[128:129], v[130:131]
	v_pk_mul_f32 v[2:3], v[170:171], v[132:133]
	v_lshlrev_b32_e32 v8, 1, v140
	v_cvt_pk_bf16_f32 v1, v1, v3
	v_cvt_pk_bf16_f32 v0, v0, v2
	global_store_dwordx2 v8, v[0:1], s[90:91]

; __device__ __forceinline__ float bflo(u32 w) { return __uint_as_float(w << 16); }
; __device__ __forceinline__ float bfhi(u32 w) { return __uint_as_float(w & 0xffff0000u); }
; __device__ __forceinline__ u32 pack2(float a, float b) { return (u32)f2bf(a) | ((u32)f2bf(b) << 16); }
; __device__ __forceinline__ float sigmoidf_(float x) { return __builtin_amdgcn_rcpf(1.f + __expf(-x)); }
; __device__ __forceinline__ void gemm_tile(const GemmArgs& ga, int wgid, int next_wgid, bool prefetched, u16* shm, unsigned char* ws, int wv_) {
;     ...
;       if (!GATE) { EPI_LOADS(0, 0) }
;       _Pragma("unroll") for (int bb = 0; bb < 8; ++bb) {
;         const int ai = bb >> 2, m = bb & 3;
;         const int cur = GATE ? 0 : (bb & 1);
;         if (GATE) { EPI_LOADS(bb, 0) }
;         else if (bb < 7) { EPI_LOADS(bb + 1, (bb + 1) & 1) }
;         _Pragma("unroll") for (int j = 0; j < 4; ++j) {
;           int row = rbase + ai * HALF + m * 16 + j;
;           unsigned eo = (unsigned)row * (unsigned)D_ + (unsigned)col0;
;           float s = 1.f;
;           if (GATE) s = rsqrtf(sc[j] * (1.f / D_) + 1e-6f);
;           const float a0 = acc[ai][0][m][0][j], a1 = acc[ai][0][m][1][j], a2 = acc[ai][1][m][0][j], a3 = acc[ai][1][m][1][j];
;           float4 xv = xin[cur][j];
;           if (GATE) {
;             xv.x += ga.live * (bflo(pin[j].x) * sigmoidf_(a0 * s));
;             xv.y += ga.live * (bfhi(pin[j].x) * sigmoidf_(a1 * s));
;             xv.z += ga.live * (bflo(pin[j].y) * sigmoidf_(a2 * s));
;             xv.w += ga.live * (bfhi(pin[j].y) * sigmoidf_(a3 * s));
;           } else {
;             const float al = ga.live * ga.alpha;
;             xv.x += al * a0; xv.y += al * a1; xv.z += al * a2; xv.w += al * a3;
;           }
;           *(float4*)(const_cast<char*>(xb) + (size_t)(eo * 4u)) = xv;
;           if (e_gn) *(uint2*)(ob + (size_t)(eo * 2u)) = make_uint2(pack2(xv.x * gn4.x, xv.y * gn4.y), pack2(xv.z * gn4.z, xv.w * gn4.w));
;           float sq = xv.x * xv.x + xv.y * xv.y + xv.z * xv.z + xv.w * xv.w;
;           sq = red16(sq);
.LBB0_1196:
	s_and_b64 vcc, exec, s[8:9]
	s_cbranch_vccz .LBB0_1262
	v_lshlrev_b32_e32 v0, 13, v168
	v_lshl_add_u32 v201, v172, 2, v0
	v_add_u32_e32 v0, 0x2000, v201
	s_waitcnt lgkmcnt(0)
	global_load_dwordx4 v[154:157], v0, s[78:79]
	v_add_u32_e32 v0, 0x4000, v201
	global_load_dwordx4 v[150:153], v0, s[78:79]
	v_add_u32_e32 v0, 0x6000, v201
	global_load_dwordx4 v[142:145], v0, s[78:79]
	v_add_u32_e32 v0, 0x20000, v201
	global_load_dwordx4 v[146:149], v0, s[78:79]
	v_add_u32_e32 v0, 0x22000, v201
	global_load_dwordx4 v[138:141], v0, s[78:79]
	v_add_u32_e32 v0, 0x24000, v201
	global_load_dwordx4 v[134:137], v0, s[78:79]
	v_add_u32_e32 v0, 0x26000, v201
	global_load_dwordx4 v[130:133], v0, s[78:79]
	s_nop 0
	global_load_dwordx4 v[0:3], v201, s[78:79]
	v_mov_b32_e32 v8, v116
	v_mov_b32_e32 v9, v124
	s_and_b64 vcc, exec, s[6:7]
	s_waitcnt vmcnt(0)
	v_mov_b32_e32 v10, v0
	v_mov_b32_e32 v11, v2
	v_pk_fma_f32 v[158:159], s[80:81], v[8:9], v[10:11]
	v_mov_b32_e32 v8, v112
	v_mov_b32_e32 v9, v120
	v_mov_b32_e32 v2, v1
	v_pk_fma_f32 v[160:161], s[80:81], v[8:9], v[2:3]
	v_lshlrev_b32_e32 v8, 2, v173
	v_mov_b32_e32 v0, v158
	v_mov_b32_e32 v1, v160
	v_mov_b32_e32 v2, v159
	v_mov_b32_e32 v3, v161
	global_store_dwordx4 v8, v[0:3], s[2:3]
	s_cbranch_vccnz .LBB0_1199
	s_nop 0
	v_pk_mul_f32 v[0:1], v[128:129], v[158:159]
	v_pk_mul_f32 v[2:3], v[170:171], v[160:161]
	v_lshlrev_b32_e32 v8, 1, v173
	v_cvt_pk_bf16_f32 v1, v1, v3
	v_cvt_pk_bf16_f32 v0, v0, v2
	global_store_dwordx2 v8, v[0:1], s[90:91]
.LBB0_1199:
	s_nop 0
	v_pk_mul_f32 v[0:1], v[158:159], v[158:159]
	v_pk_mul_f32 v[2:3], v[160:161], v[160:161]
	v_add3_u32 v160, v172, v190, s72
	v_add_f32_e32 v0, v0, v2
	v_add_f32_e32 v0, v1, v0
	v_add_f32_e32 v0, v3, v0
	v_mov_b32_e32 v1, v125
	v_mov_b32_e32 v2, v154
	v_add_f32_dpp v0, v0, v0 quad_perm:[1,0,3,2] row_mask:0xf bank_mask:0xf bound_ctrl:1
	v_mov_b32_e32 v3, v156
	v_mov_b32_e32 v156, v155
	v_add_f32_dpp v0, v0, v0 quad_perm:[2,3,0,1] row_mask:0xf bank_mask:0xf bound_ctrl:1
	v_lshlrev_b32_e32 v8, 2, v160
	s_and_b64 vcc, exec, s[6:7]
	v_add_f32_dpp v166, v0, v0 row_half_mirror row_mask:0xf bank_mask:0xf bound_ctrl:1
	v_mov_b32_e32 v0, v117
	v_pk_fma_f32 v[158:159], s[80:81], v[0:1], v[2:3]
	v_mov_b32_e32 v0, v113
	v_mov_b32_e32 v1, v121
	v_pk_fma_f32 v[154:155], s[80:81], v[0:1], v[156:157]
	v_mov_b32_dpp v169, v166 row_mirror row_mask:0xf bank_mask:0xf bound_ctrl:1
	v_mov_b32_e32 v0, v158
	v_mov_b32_e32 v1, v154
	v_mov_b32_e32 v2, v159
	v_mov_b32_e32 v3, v155
	global_store_dwordx4 v8, v[0:3], s[2:3]
	s_cbranch_vccnz .LBB0_1201
	s_nop 0
	v_pk_mul_f32 v[0:1], v[128:129], v[158:159]
	v_pk_mul_f32 v[2:3], v[170:171], v[154:155]
	v_and_b32_sdwa v9, v1, v177 dst_sel:DWORD dst_unused:UNUSED_PAD src0_sel:WORD_1 src1_sel:DWORD
	v_add3_u32 v1, v1, v9, s48
	v_and_b32_sdwa v9, v3, v177 dst_sel:DWORD dst_unused:UNUSED_PAD src0_sel:WORD_1 src1_sel:DWORD
	v_add3_u32 v3, v3, v9, s48
	v_and_b32_e32 v3, 0xffff0000, v3
	v_lshlrev_b32_e32 v8, 1, v160
	v_or_b32_sdwa v1, v3, v1 dst_sel:DWORD dst_unused:UNUSED_PAD src0_sel:DWORD src1_sel:WORD_1
	v_cvt_pk_bf16_f32 v0, v0, v2
	global_store_dwordx2 v8, v[0:1], s[90:91]
.LBB0_1201:
	s_nop 0
	v_pk_mul_f32 v[0:1], v[158:159], v[158:159]
	v_pk_mul_f32 v[2:3], v[154:155], v[154:155]
	s_movk_i32 s8, 0x1000
	v_add_f32_e32 v0, v0, v2
	v_add_f32_e32 v0, v1, v0
	v_add_f32_e32 v0, v3, v0
	v_mov_b32_e32 v1, v126
	v_mov_b32_e32 v2, v150
	v_add_f32_dpp v0, v0, v0 quad_perm:[1,0,3,2] row_mask:0xf bank_mask:0xf bound_ctrl:1
	v_mov_b32_e32 v3, v152
	v_mov_b32_e32 v152, v151
	v_add_f32_dpp v0, v0, v0 quad_perm:[2,3,0,1] row_mask:0xf bank_mask:0xf bound_ctrl:1
	v_add3_u32 v156, v172, v190, s8
	v_lshlrev_b32_e32 v8, 2, v156
	v_add_f32_dpp v191, v0, v0 row_half_mirror row_mask:0xf bank_mask:0xf bound_ctrl:1
	v_mov_b32_e32 v0, v118
	v_pk_fma_f32 v[154:155], s[80:81], v[0:1], v[2:3]
	v_mov_b32_e32 v0, v114
	v_mov_b32_e32 v1, v122
	v_pk_fma_f32 v[150:151], s[80:81], v[0:1], v[152:153]
	v_mov_b32_dpp v192, v191 row_mirror row_mask:0xf bank_mask:0xf bound_ctrl:1
	v_mov_b32_e32 v0, v154
	v_mov_b32_e32 v1, v150
	v_mov_b32_e32 v2, v155
	v_mov_b32_e32 v3, v151
	s_and_b64 vcc, exec, s[6:7]
	global_store_dwordx4 v8, v[0:3], s[2:3]
	s_cbranch_vccnz .LBB0_1203
	s_nop 0
	v_pk_mul_f32 v[0:1], v[128:129], v[154:155]
	v_pk_mul_f32 v[2:3], v[170:171], v[150:151]
	v_lshlrev_b32_e32 v8, 1, v156
	v_cvt_pk_bf16_f32 v1, v1, v3
	v_cvt_pk_bf16_f32 v0, v0, v2
	global_store_dwordx2 v8, v[0:1], s[90:91]
.LBB0_1203:
	s_nop 0
	v_pk_mul_f32 v[0:1], v[154:155], v[154:155]
	v_pk_mul_f32 v[2:3], v[150:151], v[150:151]
	s_movk_i32 s8, 0x1800
	v_add_f32_e32 v0, v0, v2
	v_add_f32_e32 v0, v1, v0
	v_add_f32_e32 v0, v3, v0
	v_mov_b32_e32 v1, v127
	v_mov_b32_e32 v2, v142
	v_add_f32_dpp v0, v0, v0 quad_perm:[1,0,3,2] row_mask:0xf bank_mask:0xf bound_ctrl:1
	v_mov_b32_e32 v3, v144
	v_mov_b32_e32 v144, v143
	v_add_f32_dpp v0, v0, v0 quad_perm:[2,3,0,1] row_mask:0xf bank_mask:0xf bound_ctrl:1
	v_add3_u32 v152, v172, v190, s8
	v_lshlrev_b32_e32 v8, 2, v152
	v_add_f32_dpp v193, v0, v0 row_half_mirror row_mask:0xf bank_mask:0xf bound_ctrl:1
	v_mov_b32_e32 v0, v119
	v_pk_fma_f32 v[150:151], s[80:81], v[0:1], v[2:3]
	v_mov_b32_e32 v0, v115
	v_mov_b32_e32 v1, v123
	v_pk_fma_f32 v[142:143], s[80:81], v[0:1], v[144:145]
	v_mov_b32_dpp v194, v193 row_mirror row_mask:0xf bank_mask:0xf bound_ctrl:1
	v_mov_b32_e32 v0, v150
	v_mov_b32_e32 v1, v142
	v_mov_b32_e32 v2, v151
	v_mov_b32_e32 v3, v143
	s_and_b64 vcc, exec, s[6:7]
	global_store_dwordx4 v8, v[0:3], s[2:3]
	s_cbranch_vccnz .LBB0_1205
	s_nop 0
	v_pk_mul_f32 v[0:1], v[128:129], v[150:151]
	v_pk_mul_f32 v[2:3], v[170:171], v[142:143]
	v_and_b32_sdwa v10, v0, v177 dst_sel:DWORD dst_unused:UNUSED_PAD src0_sel:WORD_1 src1_sel:DWORD
	v_add3_u32 v0, v0, v10, s48
	v_and_b32_sdwa v10, v2, v177 dst_sel:DWORD dst_unused:UNUSED_PAD src0_sel:WORD_1 src1_sel:DWORD
	v_add3_u32 v2, v2, v10, s48
	v_and_b32_e32 v2, 0xffff0000, v2
	v_lshlrev_b32_e32 v8, 1, v152
	v_cvt_pk_bf16_f32 v1, v1, v3
	v_or_b32_sdwa v0, v2, v0 dst_sel:DWORD dst_unused:UNUSED_PAD src0_sel:DWORD src1_sel:WORD_1
	global_store_dwordx2 v8, v[0:1], s[90:91]
; __device__ __forceinline__ float bflo(u32 w) { return __uint_as_float(w << 16); }
; __device__ __forceinline__ float bfhi(u32 w) { return __uint_as_float(w & 0xffff0000u); }
; __device__ __forceinline__ u32 pack2(float a, float b) { return (u32)f2bf(a) | ((u32)f2bf(b) << 16); }
; __device__ __forceinline__ float sigmoidf_(float x) { return __builtin_amdgcn_rcpf(1.f + __expf(-x)); }
; __device__ __forceinline__ void gemm_tile(const GemmArgs& ga, int wgid, int next_wgid, bool prefetched, u16* shm, unsigned char* ws, int wv_) {
;     ...
;       if (!GATE) { EPI_LOADS(0, 0) }
;       _Pragma("unroll") for (int bb = 0; bb < 8; ++bb) {
;         const int ai = bb >> 2, m = bb & 3;
;         const int cur = GATE ? 0 : (bb & 1);
;         if (GATE) { EPI_LOADS(bb, 0) }
;         else if (bb < 7) { EPI_LOADS(bb + 1, (bb + 1) & 1) }
;         _Pragma("unroll") for (int j = 0; j < 4; ++j) {
;           int row = rbase + ai * HALF + m * 16 + j;
;           unsigned eo = (unsigned)row * (unsigned)D_ + (unsigned)col0;
;           float s = 1.f;
;           if (GATE) s = rsqrtf(sc[j] * (1.f / D_) + 1e-6f);
;           const float a0 = acc[ai][0][m][0][j], a1 = acc[ai][0][m][1][j], a2 = acc[ai][1][m][0][j], a3 = acc[ai][1][m][1][j];
;           float4 xv = xin[cur][j];
;           if (GATE) {
;             xv.x += ga.live * (bflo(pin[j].x) * sigmoidf_(a0 * s));
;             xv.y += ga.live * (bfhi(pin[j].x) * sigmoidf_(a1 * s));
;             xv.z += ga.live * (bflo(pin[j].y) * sigmoidf_(a2 * s));
;             xv.w += ga.live * (bfhi(pin[j].y) * sigmoidf_(a3 * s));
;           } else {
;             const float al = ga.live * ga.alpha;
;             xv.x += al * a0; xv.y += al * a1; xv.z += al * a2; xv.w += al * a3;
;           }
;           *(float4*)(const_cast<char*>(xb) + (size_t)(eo * 4u)) = xv;
;           if (e_gn) *(uint2*)(ob + (size_t)(eo * 2u)) = make_uint2(pack2(xv.x * gn4.x, xv.y * gn4.y), pack2(xv.z * gn4.z, xv.w * gn4.w));
;           float sq = xv.x * xv.x + xv.y * xv.y + xv.z * xv.z + xv.w * xv.w;
;           sq = red16(sq);
.LBB0_1205:
	s_nop 0
	v_pk_mul_f32 v[0:1], v[150:151], v[150:151]
	v_pk_mul_f32 v[2:3], v[142:143], v[142:143]
	s_nop 0
	v_add_f32_e32 v0, v0, v2
	v_add_f32_e32 v0, v1, v0
	v_add_f32_e32 v0, v3, v0
	s_nop 1
	v_add_f32_dpp v0, v0, v0 quad_perm:[1,0,3,2] row_mask:0xf bank_mask:0xf bound_ctrl:1
	s_nop 1
	v_add_f32_dpp v0, v0, v0 quad_perm:[2,3,0,1] row_mask:0xf bank_mask:0xf bound_ctrl:1
	s_nop 1
	v_add_f32_dpp v195, v0, v0 row_half_mirror row_mask:0xf bank_mask:0xf bound_ctrl:1
	s_nop 1
	v_mov_b32_dpp v196, v195 row_mirror row_mask:0xf bank_mask:0xf bound_ctrl:1
	v_add_u32_e32 v0, 0x40000, v201
	v_add_u32_e32 v1, 0x42000, v201
	global_load_dwordx4 v[158:161], v0, s[78:79]
	global_load_dwordx4 v[154:157], v1, s[78:79]
	v_add_u32_e32 v0, 0x44000, v201
	v_add_u32_e32 v1, 0x46000, v201
	global_load_dwordx4 v[150:153], v0, s[78:79]
	global_load_dwordx4 v[142:145], v1, s[78:79]
	v_mov_b32_e32 v0, v100
	v_mov_b32_e32 v1, v108
	v_mov_b32_e32 v2, v146
	v_mov_b32_e32 v3, v148
	s_mov_b32 s8, 0x8000
	v_pk_fma_f32 v[162:163], s[80:81], v[0:1], v[2:3]
	v_mov_b32_e32 v0, v96
	v_mov_b32_e32 v1, v104
	v_mov_b32_e32 v148, v147
	v_add3_u32 v164, v172, v190, s8
	v_pk_fma_f32 v[146:147], s[80:81], v[0:1], v[148:149]
	v_lshlrev_b32_e32 v8, 2, v164
	v_mov_b32_e32 v0, v162
	v_mov_b32_e32 v1, v146
	v_mov_b32_e32 v2, v163
	v_mov_b32_e32 v3, v147
	s_and_b64 vcc, exec, s[6:7]
	global_store_dwordx4 v8, v[0:3], s[2:3]
	s_cbranch_vccnz .LBB0_1207
	s_nop 0
	v_pk_mul_f32 v[0:1], v[128:129], v[162:163]
	v_pk_mul_f32 v[2:3], v[170:171], v[146:147]
	v_lshlrev_b32_e32 v8, 1, v164
	v_cvt_pk_bf16_f32 v1, v1, v3
	v_cvt_pk_bf16_f32 v0, v0, v2
	global_store_dwordx2 v8, v[0:1], s[90:91]
.LBB0_1207:
	s_nop 0
	v_pk_mul_f32 v[0:1], v[162:163], v[162:163]
	v_pk_mul_f32 v[2:3], v[146:147], v[146:147]
	s_mov_b32 s8, 0x8800
	v_add_f32_e32 v0, v0, v2
	v_add_f32_e32 v0, v1, v0
	v_add_f32_e32 v0, v3, v0
	v_mov_b32_e32 v1, v109
	v_mov_b32_e32 v2, v138
	v_add_f32_dpp v0, v0, v0 quad_perm:[1,0,3,2] row_mask:0xf bank_mask:0xf bound_ctrl:1
	v_mov_b32_e32 v3, v140
	v_mov_b32_e32 v140, v139
	v_add_f32_dpp v0, v0, v0 quad_perm:[2,3,0,1] row_mask:0xf bank_mask:0xf bound_ctrl:1
	v_add3_u32 v148, v172, v190, s8
	v_lshlrev_b32_e32 v8, 2, v148
	v_add_f32_dpp v197, v0, v0 row_half_mirror row_mask:0xf bank_mask:0xf bound_ctrl:1
	v_mov_b32_e32 v0, v101
	v_pk_fma_f32 v[146:147], s[80:81], v[0:1], v[2:3]
	v_mov_b32_e32 v0, v97
	v_mov_b32_e32 v1, v105
	v_pk_fma_f32 v[138:139], s[80:81], v[0:1], v[140:141]
	v_mov_b32_dpp v198, v197 row_mirror row_mask:0xf bank_mask:0xf bound_ctrl:1
	v_mov_b32_e32 v0, v146
	v_mov_b32_e32 v1, v138
	v_mov_b32_e32 v2, v147
	v_mov_b32_e32 v3, v139
	s_and_b64 vcc, exec, s[6:7]
	global_store_dwordx4 v8, v[0:3], s[2:3]
	s_cbranch_vccnz .LBB0_1209
	s_nop 0
	v_pk_mul_f32 v[0:1], v[128:129], v[146:147]
	v_pk_mul_f32 v[2:3], v[170:171], v[138:139]
	v_lshlrev_b32_e32 v8, 1, v148
	v_cvt_pk_bf16_f32 v1, v1, v3
	v_cvt_pk_bf16_f32 v0, v0, v2
	global_store_dwordx2 v8, v[0:1], s[90:91]
.LBB0_1209:
	s_nop 0
	v_pk_mul_f32 v[0:1], v[146:147], v[146:147]
	v_pk_mul_f32 v[2:3], v[138:139], v[138:139]
	s_mov_b32 s8, 0x9000
	v_add_f32_e32 v0, v0, v2
	v_add_f32_e32 v0, v1, v0
	v_add_f32_e32 v0, v3, v0
	v_mov_b32_e32 v1, v110
	v_mov_b32_e32 v2, v134
	v_add_f32_dpp v0, v0, v0 quad_perm:[1,0,3,2] row_mask:0xf bank_mask:0xf bound_ctrl:1
	v_mov_b32_e32 v3, v136
	v_mov_b32_e32 v136, v135
	v_add_f32_dpp v0, v0, v0 quad_perm:[2,3,0,1] row_mask:0xf bank_mask:0xf bound_ctrl:1
	v_add3_u32 v140, v172, v190, s8
	v_lshlrev_b32_e32 v8, 2, v140
	v_add_f32_dpp v199, v0, v0 row_half_mirror row_mask:0xf bank_mask:0xf bound_ctrl:1
	v_mov_b32_e32 v0, v102
	v_pk_fma_f32 v[138:139], s[80:81], v[0:1], v[2:3]
	v_mov_b32_e32 v0, v98
	v_mov_b32_e32 v1, v106
	v_pk_fma_f32 v[134:135], s[80:81], v[0:1], v[136:137]
	v_mov_b32_dpp v200, v199 row_mirror row_mask:0xf bank_mask:0xf bound_ctrl:1
	v_mov_b32_e32 v0, v138
	v_mov_b32_e32 v1, v134
	v_mov_b32_e32 v2, v139
	v_mov_b32_e32 v3, v135
	s_and_b64 vcc, exec, s[6:7]
	global_store_dwordx4 v8, v[0:3], s[2:3]
	s_cbranch_vccnz .LBB0_1211
	s_nop 0
	v_pk_mul_f32 v[0:1], v[128:129], v[138:139]
	v_pk_mul_f32 v[2:3], v[170:171], v[134:135]
	v_lshlrev_b32_e32 v8, 1, v140
	v_cvt_pk_bf16_f32 v1, v1, v3
	v_cvt_pk_bf16_f32 v0, v0, v2
	global_store_dwordx2 v8, v[0:1], s[90:91]
.LBB0_1211:
	s_nop 0
	v_pk_mul_f32 v[0:1], v[138:139], v[138:139]
	v_pk_mul_f32 v[2:3], v[134:135], v[134:135]
	s_mov_b32 s8, 0x9800
	v_add_f32_e32 v0, v0, v2
	v_add_f32_e32 v0, v1, v0
	v_add_f32_e32 v0, v3, v0
	v_mov_b32_e32 v1, v111
	v_mov_b32_e32 v2, v130
	v_add_f32_dpp v0, v0, v0 quad_perm:[1,0,3,2] row_mask:0xf bank_mask:0xf bound_ctrl:1
	v_mov_b32_e32 v3, v132
	v_mov_b32_e32 v132, v131
	v_add_f32_dpp v0, v0, v0 quad_perm:[2,3,0,1] row_mask:0xf bank_mask:0xf bound_ctrl:1
	v_mov_b64_e32 v[236:237], v[206:207]
	v_add3_u32 v136, v172, v190, s8
	v_add_f32_dpp v202, v0, v0 row_half_mirror row_mask:0xf bank_mask:0xf bound_ctrl:1
	v_mov_b32_e32 v0, v103
	v_pk_fma_f32 v[134:135], s[80:81], v[0:1], v[2:3]
	v_mov_b32_e32 v0, v99
	v_mov_b32_e32 v1, v107
	v_pk_fma_f32 v[130:131], s[80:81], v[0:1], v[132:133]
	v_mov_b64_e32 v[234:235], v[204:205]
	v_mov_b32_dpp v203, v202 row_mirror row_mask:0xf bank_mask:0xf bound_ctrl:1
	v_lshlrev_b32_e32 v8, 2, v136
	v_mov_b32_e32 v0, v134
	v_mov_b32_e32 v1, v130
	v_mov_b32_e32 v2, v135
	v_mov_b32_e32 v3, v131
	s_and_b64 vcc, exec, s[6:7]
	global_store_dwordx4 v8, v[0:3], s[2:3]
	s_cbranch_vccnz .LBB0_1213
	s_nop 0
	v_pk_mul_f32 v[0:1], v[128:129], v[134:135]
	v_pk_mul_f32 v[2:3], v[170:171], v[130:131]
	v_and_b32_sdwa v10, v0, v177 dst_sel:DWORD dst_unused:UNUSED_PAD src0_sel:WORD_1 src1_sel:DWORD
	v_add3_u32 v0, v0, v10, s48
	v_and_b32_sdwa v10, v2, v177 dst_sel:DWORD dst_unused:UNUSED_PAD src0_sel:WORD_1 src1_sel:DWORD
	v_add3_u32 v2, v2, v10, s48
	v_and_b32_e32 v2, 0xffff0000, v2
	v_lshlrev_b32_e32 v8, 1, v136
	v_cvt_pk_bf16_f32 v1, v1, v3
	v_or_b32_sdwa v0, v2, v0 dst_sel:DWORD dst_unused:UNUSED_PAD src0_sel:DWORD src1_sel:WORD_1
	global_store_dwordx2 v8, v[0:1], s[90:91]
; __device__ __forceinline__ float bflo(u32 w) { return __uint_as_float(w << 16); }
; __device__ __forceinline__ float bfhi(u32 w) { return __uint_as_float(w & 0xffff0000u); }
; __device__ __forceinline__ u32 pack2(float a, float b) { return (u32)f2bf(a) | ((u32)f2bf(b) << 16); }
; __device__ __forceinline__ float sigmoidf_(float x) { return __builtin_amdgcn_rcpf(1.f + __expf(-x)); }
; __device__ __forceinline__ void gemm_tile(const GemmArgs& ga, int wgid, int next_wgid, bool prefetched, u16* shm, unsigned char* ws, int wv_) {
;     ...
;       if (!GATE) { EPI_LOADS(0, 0) }
;       _Pragma("unroll") for (int bb = 0; bb < 8; ++bb) {
;         const int ai = bb >> 2, m = bb & 3;
;         const int cur = GATE ? 0 : (bb & 1);
;         if (GATE) { EPI_LOADS(bb, 0) }
;         else if (bb < 7) { EPI_LOADS(bb + 1, (bb + 1) & 1) }
;         _Pragma("unroll") for (int j = 0; j < 4; ++j) {
;           int row = rbase + ai * HALF + m * 16 + j;
;           unsigned eo = (unsigned)row * (unsigned)D_ + (unsigned)col0;
;           float s = 1.f;
;           if (GATE) s = rsqrtf(sc[j] * (1.f / D_) + 1e-6f);
;           const float a0 = acc[ai][0][m][0][j], a1 = acc[ai][0][m][1][j], a2 = acc[ai][1][m][0][j], a3 = acc[ai][1][m][1][j];
;           float4 xv = xin[cur][j];
;           if (GATE) {
;             xv.x += ga.live * (bflo(pin[j].x) * sigmoidf_(a0 * s));
;             xv.y += ga.live * (bfhi(pin[j].x) * sigmoidf_(a1 * s));
;             xv.z += ga.live * (bflo(pin[j].y) * sigmoidf_(a2 * s));
;             xv.w += ga.live * (bfhi(pin[j].y) * sigmoidf_(a3 * s));
;           } else {
;             const float al = ga.live * ga.alpha;
;             xv.x += al * a0; xv.y += al * a1; xv.z += al * a2; xv.w += al * a3;
;           }
;           *(float4*)(const_cast<char*>(xb) + (size_t)(eo * 4u)) = xv;
;           if (e_gn) *(uint2*)(ob + (size_t)(eo * 2u)) = make_uint2(pack2(xv.x * gn4.x, xv.y * gn4.y), pack2(xv.z * gn4.z, xv.w * gn4.w));
;           float sq = xv.x * xv.x + xv.y * xv.y + xv.z * xv.z + xv.w * xv.w;
;           sq = red16(sq);
.LBB0_1213:
	s_nop 0
	v_pk_mul_f32 v[0:1], v[134:135], v[134:135]
	v_pk_mul_f32 v[2:3], v[130:131], v[130:131]
	s_nop 0
	v_add_f32_e32 v0, v0, v2
	v_add_f32_e32 v0, v1, v0
	v_add_f32_e32 v0, v3, v0
	s_nop 1
	v_add_f32_dpp v0, v0, v0 quad_perm:[1,0,3,2] row_mask:0xf bank_mask:0xf bound_ctrl:1
	s_nop 1
	v_add_f32_dpp v0, v0, v0 quad_perm:[2,3,0,1] row_mask:0xf bank_mask:0xf bound_ctrl:1
	s_nop 1
	v_add_f32_dpp v204, v0, v0 row_half_mirror row_mask:0xf bank_mask:0xf bound_ctrl:1
	s_nop 1
	v_mov_b32_dpp v205, v204 row_mirror row_mask:0xf bank_mask:0xf bound_ctrl:1
	v_add_u32_e32 v0, 0x60000, v201
	v_add_u32_e32 v1, 0x62000, v201
	global_load_dwordx4 v[162:165], v0, s[78:79]
	global_load_dwordx4 v[146:149], v1, s[78:79]
	v_add_u32_e32 v0, 0x64000, v201
	v_add_u32_e32 v1, 0x66000, v201
	global_load_dwordx4 v[138:141], v0, s[78:79]
	global_load_dwordx4 v[130:133], v1, s[78:79]
	v_mov_b32_e32 v0, v84
	v_mov_b32_e32 v1, v92
	s_waitcnt vmcnt(11)
	v_mov_b32_e32 v2, v158
	v_mov_b32_e32 v3, v160
	s_mov_b32 s8, 0x10000
	v_pk_fma_f32 v[134:135], s[80:81], v[0:1], v[2:3]
	v_mov_b32_e32 v0, v80
	v_mov_b32_e32 v1, v88
	v_mov_b32_e32 v160, v159
	v_add3_u32 v206, v172, v190, s8
	v_pk_fma_f32 v[136:137], s[80:81], v[0:1], v[160:161]
	v_lshlrev_b32_e32 v8, 2, v206
	v_mov_b32_e32 v0, v134
	v_mov_b32_e32 v1, v136
	v_mov_b32_e32 v2, v135
	v_mov_b32_e32 v3, v137
	s_and_b64 vcc, exec, s[6:7]
	global_store_dwordx4 v8, v[0:3], s[2:3]
	s_cbranch_vccnz .LBB0_1215
	s_nop 0
	v_pk_mul_f32 v[0:1], v[128:129], v[134:135]
	v_pk_mul_f32 v[2:3], v[170:171], v[136:137]
	v_lshlrev_b32_e32 v8, 1, v206
	v_cvt_pk_bf16_f32 v1, v1, v3
	v_cvt_pk_bf16_f32 v0, v0, v2
	global_store_dwordx2 v8, v[0:1], s[90:91]
.LBB0_1215:
	s_nop 0
	v_pk_mul_f32 v[0:1], v[134:135], v[134:135]
	v_pk_mul_f32 v[2:3], v[136:137], v[136:137]
	s_mov_b32 s8, 0x10800
	v_add_f32_e32 v0, v0, v2
	v_add_f32_e32 v0, v1, v0
	v_add_f32_e32 v0, v3, v0
	v_mov_b32_e32 v1, v93
	s_waitcnt vmcnt(11)
	v_mov_b32_e32 v2, v154
	v_add_f32_dpp v0, v0, v0 quad_perm:[1,0,3,2] row_mask:0xf bank_mask:0xf bound_ctrl:1
	v_mov_b32_e32 v3, v156
	v_mov_b32_e32 v156, v155
	v_add_f32_dpp v0, v0, v0 quad_perm:[2,3,0,1] row_mask:0xf bank_mask:0xf bound_ctrl:1
	v_add3_u32 v158, v172, v190, s8
	v_lshlrev_b32_e32 v8, 2, v158
	v_add_f32_dpp v206, v0, v0 row_half_mirror row_mask:0xf bank_mask:0xf bound_ctrl:1
	v_mov_b32_e32 v0, v85
	v_pk_fma_f32 v[134:135], s[80:81], v[0:1], v[2:3]
	v_mov_b32_e32 v0, v81
	v_mov_b32_e32 v1, v89
	v_pk_fma_f32 v[136:137], s[80:81], v[0:1], v[156:157]
	v_mov_b32_dpp v207, v206 row_mirror row_mask:0xf bank_mask:0xf bound_ctrl:1
	v_mov_b32_e32 v0, v134
	v_mov_b32_e32 v1, v136
	v_mov_b32_e32 v2, v135
	v_mov_b32_e32 v3, v137
	s_and_b64 vcc, exec, s[6:7]
	global_store_dwordx4 v8, v[0:3], s[2:3]
	s_cbranch_vccnz .LBB0_1217
	s_nop 0
	v_pk_mul_f32 v[0:1], v[128:129], v[134:135]
	v_pk_mul_f32 v[2:3], v[170:171], v[136:137]
	v_lshlrev_b32_e32 v8, 1, v158
	v_cvt_pk_bf16_f32 v1, v1, v3
	v_cvt_pk_bf16_f32 v0, v0, v2
	global_store_dwordx2 v8, v[0:1], s[90:91]
.LBB0_1217:
	s_nop 0
	v_pk_mul_f32 v[0:1], v[134:135], v[134:135]
	v_pk_mul_f32 v[2:3], v[136:137], v[136:137]
	s_mov_b32 s8, 0x11000
	v_add_f32_e32 v0, v0, v2
	v_add_f32_e32 v0, v1, v0
	v_add_f32_e32 v0, v3, v0
	v_mov_b32_e32 v1, v94
	s_waitcnt vmcnt(11)
	v_mov_b32_e32 v2, v150
	v_add_f32_dpp v0, v0, v0 quad_perm:[1,0,3,2] row_mask:0xf bank_mask:0xf bound_ctrl:1
	v_mov_b32_e32 v3, v152
	v_mov_b32_e32 v152, v151
	v_add_f32_dpp v0, v0, v0 quad_perm:[2,3,0,1] row_mask:0xf bank_mask:0xf bound_ctrl:1
	v_add3_u32 v154, v172, v190, s8
	v_lshlrev_b32_e32 v8, 2, v154
	v_add_f32_dpp v208, v0, v0 row_half_mirror row_mask:0xf bank_mask:0xf bound_ctrl:1
	v_mov_b32_e32 v0, v86
	v_pk_fma_f32 v[134:135], s[80:81], v[0:1], v[2:3]
	v_mov_b32_e32 v0, v82
	v_mov_b32_e32 v1, v90
	v_pk_fma_f32 v[136:137], s[80:81], v[0:1], v[152:153]
	v_mov_b32_dpp v209, v208 row_mirror row_mask:0xf bank_mask:0xf bound_ctrl:1
	v_mov_b32_e32 v0, v134
	v_mov_b32_e32 v1, v136
	v_mov_b32_e32 v2, v135
	v_mov_b32_e32 v3, v137
	s_and_b64 vcc, exec, s[6:7]
	global_store_dwordx4 v8, v[0:3], s[2:3]
	s_cbranch_vccnz .LBB0_1219
	s_nop 0
	v_pk_mul_f32 v[0:1], v[128:129], v[134:135]
	v_pk_mul_f32 v[2:3], v[170:171], v[136:137]
	v_lshlrev_b32_e32 v8, 1, v154
	v_cvt_pk_bf16_f32 v1, v1, v3
	v_cvt_pk_bf16_f32 v0, v0, v2
	global_store_dwordx2 v8, v[0:1], s[90:91]
.LBB0_1219:
	s_nop 0
	v_pk_mul_f32 v[0:1], v[134:135], v[134:135]
	v_pk_mul_f32 v[2:3], v[136:137], v[136:137]
	s_mov_b32 s8, 0x11800
	v_add_f32_e32 v0, v0, v2
	v_add_f32_e32 v0, v1, v0
	v_add_f32_e32 v0, v3, v0
	v_mov_b32_e32 v1, v95
	s_waitcnt vmcnt(11)
	v_mov_b32_e32 v2, v142
	v_add_f32_dpp v0, v0, v0 quad_perm:[1,0,3,2] row_mask:0xf bank_mask:0xf bound_ctrl:1
	v_mov_b32_e32 v3, v144
	v_mov_b32_e32 v144, v143
	v_add_f32_dpp v0, v0, v0 quad_perm:[2,3,0,1] row_mask:0xf bank_mask:0xf bound_ctrl:1
	v_add3_u32 v150, v172, v190, s8
	v_lshlrev_b32_e32 v8, 2, v150
	v_add_f32_dpp v210, v0, v0 row_half_mirror row_mask:0xf bank_mask:0xf bound_ctrl:1
	v_mov_b32_e32 v0, v87
	v_pk_fma_f32 v[134:135], s[80:81], v[0:1], v[2:3]
	v_mov_b32_e32 v0, v83
	v_mov_b32_e32 v1, v91
	v_pk_fma_f32 v[136:137], s[80:81], v[0:1], v[144:145]
	v_mov_b32_dpp v211, v210 row_mirror row_mask:0xf bank_mask:0xf bound_ctrl:1
	v_mov_b32_e32 v0, v134
	v_mov_b32_e32 v1, v136
	v_mov_b32_e32 v2, v135
	v_mov_b32_e32 v3, v137
	s_and_b64 vcc, exec, s[6:7]
	global_store_dwordx4 v8, v[0:3], s[2:3]
	s_cbranch_vccnz .LBB0_1221
	s_nop 0
	v_pk_mul_f32 v[0:1], v[128:129], v[134:135]
	v_pk_mul_f32 v[2:3], v[170:171], v[136:137]
	v_and_b32_sdwa v10, v0, v177 dst_sel:DWORD dst_unused:UNUSED_PAD src0_sel:WORD_1 src1_sel:DWORD
	v_add3_u32 v0, v0, v10, s48
	v_and_b32_sdwa v10, v2, v177 dst_sel:DWORD dst_unused:UNUSED_PAD src0_sel:WORD_1 src1_sel:DWORD
	v_add3_u32 v2, v2, v10, s48
	v_and_b32_e32 v2, 0xffff0000, v2
	v_lshlrev_b32_e32 v8, 1, v150
	v_cvt_pk_bf16_f32 v1, v1, v3
	v_or_b32_sdwa v0, v2, v0 dst_sel:DWORD dst_unused:UNUSED_PAD src0_sel:DWORD src1_sel:WORD_1
	global_store_dwordx2 v8, v[0:1], s[90:91]
; __device__ __forceinline__ float bflo(u32 w) { return __uint_as_float(w << 16); }
; __device__ __forceinline__ float bfhi(u32 w) { return __uint_as_float(w & 0xffff0000u); }
; __device__ __forceinline__ u32 pack2(float a, float b) { return (u32)f2bf(a) | ((u32)f2bf(b) << 16); }
; __device__ __forceinline__ float sigmoidf_(float x) { return __builtin_amdgcn_rcpf(1.f + __expf(-x)); }
; __device__ __forceinline__ void gemm_tile(const GemmArgs& ga, int wgid, int next_wgid, bool prefetched, u16* shm, unsigned char* ws, int wv_) {
;     ...
;       if (!GATE) { EPI_LOADS(0, 0) }
;       _Pragma("unroll") for (int bb = 0; bb < 8; ++bb) {
;         const int ai = bb >> 2, m = bb & 3;
;         const int cur = GATE ? 0 : (bb & 1);
;         if (GATE) { EPI_LOADS(bb, 0) }
;         else if (bb < 7) { EPI_LOADS(bb + 1, (bb + 1) & 1) }
;         _Pragma("unroll") for (int j = 0; j < 4; ++j) {
;           int row = rbase + ai * HALF + m * 16 + j;
;           unsigned eo = (unsigned)row * (unsigned)D_ + (unsigned)col0;
;           float s = 1.f;
;           if (GATE) s = rsqrtf(sc[j] * (1.f / D_) + 1e-6f);
;           const float a0 = acc[ai][0][m][0][j], a1 = acc[ai][0][m][1][j], a2 = acc[ai][1][m][0][j], a3 = acc[ai][1][m][1][j];
;           float4 xv = xin[cur][j];
;           if (GATE) {
;             xv.x += ga.live * (bflo(pin[j].x) * sigmoidf_(a0 * s));
;             xv.y += ga.live * (bfhi(pin[j].x) * sigmoidf_(a1 * s));
;             xv.z += ga.live * (bflo(pin[j].y) * sigmoidf_(a2 * s));
;             xv.w += ga.live * (bfhi(pin[j].y) * sigmoidf_(a3 * s));
;           } else {
;             const float al = ga.live * ga.alpha;
;             xv.x += al * a0; xv.y += al * a1; xv.z += al * a2; xv.w += al * a3;
;           }
;           *(float4*)(const_cast<char*>(xb) + (size_t)(eo * 4u)) = xv;
;           if (e_gn) *(uint2*)(ob + (size_t)(eo * 2u)) = make_uint2(pack2(xv.x * gn4.x, xv.y * gn4.y), pack2(xv.z * gn4.z, xv.w * gn4.w));
;           float sq = xv.x * xv.x + xv.y * xv.y + xv.z * xv.z + xv.w * xv.w;
;           sq = red16(sq);
;           const int ridx = bb * 4 + j;
;           if (ridx < 16) sqA = (fr == ridx) ? sq : sqA;
;           else sqB = (fr == ridx - 16) ? sq : sqB;
.LBB0_1221:
	s_nop 0
	v_pk_mul_f32 v[0:1], v[134:135], v[134:135]
	v_pk_mul_f32 v[2:3], v[136:137], v[136:137]
	s_nop 0
	v_add_f32_e32 v0, v0, v2
	v_add_f32_e32 v0, v1, v0
	v_add_f32_e32 v0, v3, v0
	s_nop 1
	v_add_f32_dpp v0, v0, v0 quad_perm:[1,0,3,2] row_mask:0xf bank_mask:0xf bound_ctrl:1
	s_nop 1
	v_add_f32_dpp v0, v0, v0 quad_perm:[2,3,0,1] row_mask:0xf bank_mask:0xf bound_ctrl:1
	s_nop 1
	v_add_f32_dpp v212, v0, v0 row_half_mirror row_mask:0xf bank_mask:0xf bound_ctrl:1
	s_nop 1
	v_mov_b32_dpp v213, v212 row_mirror row_mask:0xf bank_mask:0xf bound_ctrl:1
	v_add_u32_e32 v0, 0x100000, v201
	v_add_u32_e32 v1, 0x102000, v201
	global_load_dwordx4 v[154:157], v0, s[78:79]
	global_load_dwordx4 v[150:153], v1, s[78:79]
	v_add_u32_e32 v0, 0x104000, v201
	v_add_u32_e32 v1, 0x106000, v201
	global_load_dwordx4 v[142:145], v0, s[78:79]
	global_load_dwordx4 v[134:137], v1, s[78:79]
	v_mov_b32_e32 v0, v68
	v_mov_b32_e32 v1, v76
	s_waitcnt vmcnt(11)
	v_mov_b32_e32 v2, v162
	v_mov_b32_e32 v3, v164
	s_mov_b32 s8, 0x18000
	v_pk_fma_f32 v[158:159], s[80:81], v[0:1], v[2:3]
	v_mov_b32_e32 v0, v64
	v_mov_b32_e32 v1, v72
	v_mov_b32_e32 v164, v163
	v_add3_u32 v214, v172, v190, s8
	v_pk_fma_f32 v[160:161], s[80:81], v[0:1], v[164:165]
	v_lshlrev_b32_e32 v8, 2, v214
	v_mov_b32_e32 v0, v158
	v_mov_b32_e32 v1, v160
	v_mov_b32_e32 v2, v159
	v_mov_b32_e32 v3, v161
	s_and_b64 vcc, exec, s[6:7]
	global_store_dwordx4 v8, v[0:3], s[2:3]
	s_cbranch_vccnz .LBB0_1223
	s_nop 0
	v_pk_mul_f32 v[0:1], v[128:129], v[158:159]
	v_pk_mul_f32 v[2:3], v[170:171], v[160:161]
	v_lshlrev_b32_e32 v8, 1, v214
	v_cvt_pk_bf16_f32 v1, v1, v3
	v_cvt_pk_bf16_f32 v0, v0, v2
	global_store_dwordx2 v8, v[0:1], s[90:91]
.LBB0_1223:
	s_nop 0
	v_pk_mul_f32 v[0:1], v[158:159], v[158:159]
	v_pk_mul_f32 v[2:3], v[160:161], v[160:161]
	s_mov_b32 s8, 0x18800
	v_add_f32_e32 v0, v0, v2
	v_add_f32_e32 v0, v1, v0
	v_add_f32_e32 v0, v3, v0
	v_mov_b32_e32 v1, v77
	s_waitcnt vmcnt(11)
	v_mov_b32_e32 v2, v146
	v_add_f32_dpp v0, v0, v0 quad_perm:[1,0,3,2] row_mask:0xf bank_mask:0xf bound_ctrl:1
	v_mov_b32_e32 v3, v148
	v_mov_b32_e32 v148, v147
	v_add_f32_dpp v0, v0, v0 quad_perm:[2,3,0,1] row_mask:0xf bank_mask:0xf bound_ctrl:1
	v_add3_u32 v160, v172, v190, s8
	v_lshlrev_b32_e32 v8, 2, v160
	v_add_f32_dpp v164, v0, v0 row_half_mirror row_mask:0xf bank_mask:0xf bound_ctrl:1
	v_mov_b32_e32 v0, v69
	v_pk_fma_f32 v[158:159], s[80:81], v[0:1], v[2:3]
	v_mov_b32_e32 v0, v65
	v_mov_b32_e32 v1, v73
	v_pk_fma_f32 v[146:147], s[80:81], v[0:1], v[148:149]
	v_mov_b32_dpp v165, v164 row_mirror row_mask:0xf bank_mask:0xf bound_ctrl:1
	v_mov_b32_e32 v0, v158
	v_mov_b32_e32 v1, v146
	v_mov_b32_e32 v2, v159
	v_mov_b32_e32 v3, v147
	s_and_b64 vcc, exec, s[6:7]
	global_store_dwordx4 v8, v[0:3], s[2:3]
	s_cbranch_vccnz .LBB0_1225
	s_nop 0
	v_pk_mul_f32 v[0:1], v[128:129], v[158:159]
	v_pk_mul_f32 v[2:3], v[170:171], v[146:147]
	v_lshlrev_b32_e32 v8, 1, v160
	v_cvt_pk_bf16_f32 v1, v1, v3
	v_cvt_pk_bf16_f32 v0, v0, v2
	global_store_dwordx2 v8, v[0:1], s[90:91]
.LBB0_1225:
	s_nop 0
	v_pk_mul_f32 v[0:1], v[158:159], v[158:159]
	v_pk_mul_f32 v[2:3], v[146:147], v[146:147]
	s_mov_b32 s8, 0x19000
	v_add_f32_e32 v0, v0, v2
	v_add_f32_e32 v0, v1, v0
	v_add_f32_e32 v0, v3, v0
	v_mov_b32_e32 v1, v78
	s_waitcnt vmcnt(11)
	v_mov_b32_e32 v2, v138
	v_add_f32_dpp v0, v0, v0 quad_perm:[1,0,3,2] row_mask:0xf bank_mask:0xf bound_ctrl:1
	v_mov_b32_e32 v3, v140
	v_mov_b32_e32 v140, v139
	v_add_f32_dpp v0, v0, v0 quad_perm:[2,3,0,1] row_mask:0xf bank_mask:0xf bound_ctrl:1
	v_add3_u32 v148, v172, v190, s8
	v_lshlrev_b32_e32 v8, 2, v148
	v_add_f32_dpp v214, v0, v0 row_half_mirror row_mask:0xf bank_mask:0xf bound_ctrl:1
	v_mov_b32_e32 v0, v70
	v_pk_fma_f32 v[146:147], s[80:81], v[0:1], v[2:3]
	v_mov_b32_e32 v0, v66
	v_mov_b32_e32 v1, v74
	v_pk_fma_f32 v[138:139], s[80:81], v[0:1], v[140:141]
	v_mov_b32_dpp v215, v214 row_mirror row_mask:0xf bank_mask:0xf bound_ctrl:1
	v_mov_b32_e32 v0, v146
	v_mov_b32_e32 v1, v138
	v_mov_b32_e32 v2, v147
	v_mov_b32_e32 v3, v139
	s_and_b64 vcc, exec, s[6:7]
	global_store_dwordx4 v8, v[0:3], s[2:3]
	s_cbranch_vccnz .LBB0_1227
	s_nop 0
	v_pk_mul_f32 v[0:1], v[128:129], v[146:147]
	v_pk_mul_f32 v[2:3], v[170:171], v[138:139]
	v_lshlrev_b32_e32 v8, 1, v148
	v_cvt_pk_bf16_f32 v1, v1, v3
	v_cvt_pk_bf16_f32 v0, v0, v2
	global_store_dwordx2 v8, v[0:1], s[90:91]
.LBB0_1227:
	s_nop 0
	v_pk_mul_f32 v[0:1], v[146:147], v[146:147]
	v_pk_mul_f32 v[2:3], v[138:139], v[138:139]
	s_mov_b32 s8, 0x19800
	v_add_f32_e32 v0, v0, v2
	v_add_f32_e32 v0, v1, v0
	v_add_f32_e32 v0, v3, v0
	v_mov_b32_e32 v1, v79
	s_waitcnt vmcnt(11)
	v_mov_b32_e32 v2, v130
	v_add_f32_dpp v0, v0, v0 quad_perm:[1,0,3,2] row_mask:0xf bank_mask:0xf bound_ctrl:1
	v_mov_b32_e32 v3, v132
	v_mov_b32_e32 v132, v131
	v_add_f32_dpp v0, v0, v0 quad_perm:[2,3,0,1] row_mask:0xf bank_mask:0xf bound_ctrl:1
	v_add3_u32 v140, v172, v190, s8
	v_lshlrev_b32_e32 v8, 2, v140
	v_add_f32_dpp v216, v0, v0 row_half_mirror row_mask:0xf bank_mask:0xf bound_ctrl:1
	v_mov_b32_e32 v0, v71
	v_pk_fma_f32 v[138:139], s[80:81], v[0:1], v[2:3]
	v_mov_b32_e32 v0, v67
	v_mov_b32_e32 v1, v75
	v_pk_fma_f32 v[130:131], s[80:81], v[0:1], v[132:133]
	v_mov_b32_dpp v217, v216 row_mirror row_mask:0xf bank_mask:0xf bound_ctrl:1
	v_mov_b32_e32 v0, v138
	v_mov_b32_e32 v1, v130
	v_mov_b32_e32 v2, v139
	v_mov_b32_e32 v3, v131
	s_and_b64 vcc, exec, s[6:7]
	global_store_dwordx4 v8, v[0:3], s[2:3]
	s_cbranch_vccnz .LBB0_1229
	s_nop 0
	v_pk_mul_f32 v[0:1], v[128:129], v[138:139]
	v_pk_mul_f32 v[2:3], v[170:171], v[130:131]
	v_and_b32_sdwa v10, v0, v177 dst_sel:DWORD dst_unused:UNUSED_PAD src0_sel:WORD_1 src1_sel:DWORD
	v_add3_u32 v0, v0, v10, s48
	v_and_b32_sdwa v10, v2, v177 dst_sel:DWORD dst_unused:UNUSED_PAD src0_sel:WORD_1 src1_sel:DWORD
	v_add3_u32 v2, v2, v10, s48
	v_and_b32_e32 v2, 0xffff0000, v2
	v_lshlrev_b32_e32 v8, 1, v140
	v_cvt_pk_bf16_f32 v1, v1, v3
	v_or_b32_sdwa v0, v2, v0 dst_sel:DWORD dst_unused:UNUSED_PAD src0_sel:DWORD src1_sel:WORD_1
	global_store_dwordx2 v8, v[0:1], s[90:91]
; __device__ __forceinline__ float bflo(u32 w) { return __uint_as_float(w << 16); }
; __device__ __forceinline__ float bfhi(u32 w) { return __uint_as_float(w & 0xffff0000u); }
; __device__ __forceinline__ u32 pack2(float a, float b) { return (u32)f2bf(a) | ((u32)f2bf(b) << 16); }
; __device__ __forceinline__ float sigmoidf_(float x) { return __builtin_amdgcn_rcpf(1.f + __expf(-x)); }
; __device__ __forceinline__ void gemm_tile(const GemmArgs& ga, int wgid, int next_wgid, bool prefetched, u16* shm, unsigned char* ws, int wv_) {
;     ...
;       if (!GATE) { EPI_LOADS(0, 0) }
;       _Pragma("unroll") for (int bb = 0; bb < 8; ++bb) {
;         const int ai = bb >> 2, m = bb & 3;
;         const int cur = GATE ? 0 : (bb & 1);
;         if (GATE) { EPI_LOADS(bb, 0) }
;         else if (bb < 7) { EPI_LOADS(bb + 1, (bb + 1) & 1) }
;         _Pragma("unroll") for (int j = 0; j < 4; ++j) {
;           int row = rbase + ai * HALF + m * 16 + j;
;           unsigned eo = (unsigned)row * (unsigned)D_ + (unsigned)col0;
;           float s = 1.f;
;           if (GATE) s = rsqrtf(sc[j] * (1.f / D_) + 1e-6f);
;           const float a0 = acc[ai][0][m][0][j], a1 = acc[ai][0][m][1][j], a2 = acc[ai][1][m][0][j], a3 = acc[ai][1][m][1][j];
;           float4 xv = xin[cur][j];
;           if (GATE) {
;             xv.x += ga.live * (bflo(pin[j].x) * sigmoidf_(a0 * s));
;             xv.y += ga.live * (bfhi(pin[j].x) * sigmoidf_(a1 * s));
;             xv.z += ga.live * (bflo(pin[j].y) * sigmoidf_(a2 * s));
;             xv.w += ga.live * (bfhi(pin[j].y) * sigmoidf_(a3 * s));
;           } else {
;             const float al = ga.live * ga.alpha;
;             xv.x += al * a0; xv.y += al * a1; xv.z += al * a2; xv.w += al * a3;
;           }
;           *(float4*)(const_cast<char*>(xb) + (size_t)(eo * 4u)) = xv;
;           if (e_gn) *(uint2*)(ob + (size_t)(eo * 2u)) = make_uint2(pack2(xv.x * gn4.x, xv.y * gn4.y), pack2(xv.z * gn4.z, xv.w * gn4.w));
;           float sq = xv.x * xv.x + xv.y * xv.y + xv.z * xv.z + xv.w * xv.w;
;           sq = red16(sq);
;           const int ridx = bb * 4 + j;
;           if (ridx < 16) sqA = (fr == ridx) ? sq : sqA;
;           else sqB = (fr == ridx - 16) ? sq : sqB;
.LBB0_1229:
	s_nop 0
	v_pk_mul_f32 v[0:1], v[138:139], v[138:139]
	v_pk_mul_f32 v[2:3], v[130:131], v[130:131]
	s_nop 0
	v_add_f32_e32 v0, v0, v2
	v_add_f32_e32 v0, v1, v0
	v_add_f32_e32 v0, v3, v0
	s_nop 1
	v_add_f32_dpp v0, v0, v0 quad_perm:[1,0,3,2] row_mask:0xf bank_mask:0xf bound_ctrl:1
	s_nop 1
	v_add_f32_dpp v0, v0, v0 quad_perm:[2,3,0,1] row_mask:0xf bank_mask:0xf bound_ctrl:1
	s_nop 1
	v_add_f32_dpp v172, v0, v0 row_half_mirror row_mask:0xf bank_mask:0xf bound_ctrl:1
	s_nop 1
	v_mov_b32_dpp v190, v172 row_mirror row_mask:0xf bank_mask:0xf bound_ctrl:1
	v_add_u32_e32 v0, 0x120000, v201
	v_add_u32_e32 v1, 0x122000, v201
	global_load_dwordx4 v[158:161], v0, s[78:79]
	global_load_dwordx4 v[146:149], v1, s[78:79]
	v_add_u32_e32 v0, 0x124000, v201
	v_add_u32_e32 v1, 0x126000, v201
	global_load_dwordx4 v[138:141], v0, s[78:79]
	global_load_dwordx4 v[130:133], v1, s[78:79]
	v_mov_b32_e32 v0, v52
	v_mov_b32_e32 v1, v60
	s_waitcnt vmcnt(11)
	v_mov_b32_e32 v2, v154
	v_mov_b32_e32 v3, v156
	v_pk_fma_f32 v[162:163], s[80:81], v[0:1], v[2:3]
	v_mov_b32_e32 v0, v48
	v_mov_b32_e32 v1, v56
	v_mov_b32_e32 v156, v155
	v_add_u32_e32 v218, 0x40000, v173
	v_pk_fma_f32 v[154:155], s[80:81], v[0:1], v[156:157]
	v_lshlrev_b32_e32 v8, 2, v218
	v_mov_b32_e32 v0, v162
	v_mov_b32_e32 v1, v154
	v_mov_b32_e32 v2, v163
	v_mov_b32_e32 v3, v155
	s_and_b64 vcc, exec, s[6:7]
	global_store_dwordx4 v8, v[0:3], s[2:3]
	s_cbranch_vccnz .LBB0_1231
	s_nop 0
	v_pk_mul_f32 v[0:1], v[128:129], v[162:163]
	v_pk_mul_f32 v[2:3], v[170:171], v[154:155]
	v_lshlrev_b32_e32 v8, 1, v218
	v_cvt_pk_bf16_f32 v1, v1, v3
	v_cvt_pk_bf16_f32 v0, v0, v2
	global_store_dwordx2 v8, v[0:1], s[90:91]
.LBB0_1231:
	s_nop 0
	v_pk_mul_f32 v[0:1], v[162:163], v[162:163]
	v_pk_mul_f32 v[2:3], v[154:155], v[154:155]
	v_add_u32_e32 v156, 0x40800, v173
	v_add_f32_e32 v0, v0, v2
	v_add_f32_e32 v0, v1, v0
	v_add_f32_e32 v0, v3, v0
	v_mov_b32_e32 v1, v61
	s_waitcnt vmcnt(11)
	v_mov_b32_e32 v2, v150
	v_add_f32_dpp v0, v0, v0 quad_perm:[1,0,3,2] row_mask:0xf bank_mask:0xf bound_ctrl:1
	v_mov_b32_e32 v3, v152
	v_mov_b32_e32 v152, v151
	v_add_f32_dpp v0, v0, v0 quad_perm:[2,3,0,1] row_mask:0xf bank_mask:0xf bound_ctrl:1
	v_lshlrev_b32_e32 v8, 2, v156
	s_and_b64 vcc, exec, s[6:7]
	v_add_f32_dpp v218, v0, v0 row_half_mirror row_mask:0xf bank_mask:0xf bound_ctrl:1
	v_mov_b32_e32 v0, v53
	v_pk_fma_f32 v[154:155], s[80:81], v[0:1], v[2:3]
	v_mov_b32_e32 v0, v49
	v_mov_b32_e32 v1, v57
	v_pk_fma_f32 v[150:151], s[80:81], v[0:1], v[152:153]
	v_mov_b32_dpp v219, v218 row_mirror row_mask:0xf bank_mask:0xf bound_ctrl:1
	v_mov_b32_e32 v0, v154
	v_mov_b32_e32 v1, v150
	v_mov_b32_e32 v2, v155
	v_mov_b32_e32 v3, v151
	global_store_dwordx4 v8, v[0:3], s[2:3]
	s_cbranch_vccnz .LBB0_1233
	s_nop 0
	v_pk_mul_f32 v[0:1], v[128:129], v[154:155]
	v_pk_mul_f32 v[2:3], v[170:171], v[150:151]
	v_and_b32_sdwa v9, v1, v177 dst_sel:DWORD dst_unused:UNUSED_PAD src0_sel:WORD_1 src1_sel:DWORD
	v_add3_u32 v1, v1, v9, s48
	v_and_b32_sdwa v9, v3, v177 dst_sel:DWORD dst_unused:UNUSED_PAD src0_sel:WORD_1 src1_sel:DWORD
	v_add3_u32 v3, v3, v9, s48
	v_and_b32_e32 v3, 0xffff0000, v3
	v_lshlrev_b32_e32 v8, 1, v156
	v_or_b32_sdwa v1, v3, v1 dst_sel:DWORD dst_unused:UNUSED_PAD src0_sel:DWORD src1_sel:WORD_1
	v_cvt_pk_bf16_f32 v0, v0, v2
	global_store_dwordx2 v8, v[0:1], s[90:91]
.LBB0_1233:
	s_nop 0
	v_pk_mul_f32 v[0:1], v[154:155], v[154:155]
	v_pk_mul_f32 v[2:3], v[150:151], v[150:151]
	v_add_u32_e32 v152, 0x41000, v173
	v_add_f32_e32 v0, v0, v2
	v_add_f32_e32 v0, v1, v0
	v_add_f32_e32 v0, v3, v0
	v_mov_b32_e32 v1, v62
	s_waitcnt vmcnt(11)
	v_mov_b32_e32 v2, v142
	v_add_f32_dpp v0, v0, v0 quad_perm:[1,0,3,2] row_mask:0xf bank_mask:0xf bound_ctrl:1
	v_mov_b32_e32 v3, v144
	v_mov_b32_e32 v144, v143
	v_add_f32_dpp v0, v0, v0 quad_perm:[2,3,0,1] row_mask:0xf bank_mask:0xf bound_ctrl:1
	v_lshlrev_b32_e32 v8, 2, v152
	s_and_b64 vcc, exec, s[6:7]
	v_add_f32_dpp v220, v0, v0 row_half_mirror row_mask:0xf bank_mask:0xf bound_ctrl:1
	v_mov_b32_e32 v0, v54
	v_pk_fma_f32 v[150:151], s[80:81], v[0:1], v[2:3]
	v_mov_b32_e32 v0, v50
	v_mov_b32_e32 v1, v58
	v_pk_fma_f32 v[142:143], s[80:81], v[0:1], v[144:145]
	v_mov_b32_dpp v221, v220 row_mirror row_mask:0xf bank_mask:0xf bound_ctrl:1
	v_mov_b32_e32 v0, v150
	v_mov_b32_e32 v1, v142
	v_mov_b32_e32 v2, v151
	v_mov_b32_e32 v3, v143
	global_store_dwordx4 v8, v[0:3], s[2:3]
	s_cbranch_vccnz .LBB0_1235
	s_nop 0
	v_pk_mul_f32 v[0:1], v[128:129], v[150:151]
	v_pk_mul_f32 v[2:3], v[170:171], v[142:143]
	v_and_b32_sdwa v9, v1, v177 dst_sel:DWORD dst_unused:UNUSED_PAD src0_sel:WORD_1 src1_sel:DWORD
	v_add3_u32 v1, v1, v9, s48
	v_and_b32_sdwa v9, v3, v177 dst_sel:DWORD dst_unused:UNUSED_PAD src0_sel:WORD_1 src1_sel:DWORD
	v_add3_u32 v3, v3, v9, s48
	v_and_b32_e32 v3, 0xffff0000, v3
	v_lshlrev_b32_e32 v8, 1, v152
	v_or_b32_sdwa v1, v3, v1 dst_sel:DWORD dst_unused:UNUSED_PAD src0_sel:DWORD src1_sel:WORD_1
	v_cvt_pk_bf16_f32 v0, v0, v2
	global_store_dwordx2 v8, v[0:1], s[90:91]

; __device__ __forceinline__ float bflo(u32 w) { return __uint_as_float(w << 16); }
; __device__ __forceinline__ float bfhi(u32 w) { return __uint_as_float(w & 0xffff0000u); }
; __device__ __forceinline__ u32 pack2(float a, float b) { return (u32)f2bf(a) | ((u32)f2bf(b) << 16); }
; __device__ __forceinline__ float sigmoidf_(float x) { return __builtin_amdgcn_rcpf(1.f + __expf(-x)); }
; __device__ __forceinline__ void gemm_tile(const GemmArgs& ga, int wgid, int next_wgid, bool prefetched, u16* shm, unsigned char* ws, int wv_) {
;     ...
;       if (!GATE) { EPI_LOADS(0, 0) }
;       _Pragma("unroll") for (int bb = 0; bb < 8; ++bb) {
;         const int ai = bb >> 2, m = bb & 3;
;         const int cur = GATE ? 0 : (bb & 1);
;         if (GATE) { EPI_LOADS(bb, 0) }
;         else if (bb < 7) { EPI_LOADS(bb + 1, (bb + 1) & 1) }
;         _Pragma("unroll") for (int j = 0; j < 4; ++j) {
;           int row = rbase + ai * HALF + m * 16 + j;
;           unsigned eo = (unsigned)row * (unsigned)D_ + (unsigned)col0;
;           float s = 1.f;
;           if (GATE) s = rsqrtf(sc[j] * (1.f / D_) + 1e-6f);
;           const float a0 = acc[ai][0][m][0][j], a1 = acc[ai][0][m][1][j], a2 = acc[ai][1][m][0][j], a3 = acc[ai][1][m][1][j];
;           float4 xv = xin[cur][j];
;           if (GATE) {
;             xv.x += ga.live * (bflo(pin[j].x) * sigmoidf_(a0 * s));
;             xv.y += ga.live * (bfhi(pin[j].x) * sigmoidf_(a1 * s));
;             xv.z += ga.live * (bflo(pin[j].y) * sigmoidf_(a2 * s));
;             xv.w += ga.live * (bfhi(pin[j].y) * sigmoidf_(a3 * s));
;           } else {
;             const float al = ga.live * ga.alpha;
;             xv.x += al * a0; xv.y += al * a1; xv.z += al * a2; xv.w += al * a3;
;           }
;           *(float4*)(const_cast<char*>(xb) + (size_t)(eo * 4u)) = xv;
;           if (e_gn) *(uint2*)(ob + (size_t)(eo * 2u)) = make_uint2(pack2(xv.x * gn4.x, xv.y * gn4.y), pack2(xv.z * gn4.z, xv.w * gn4.w));
;           float sq = xv.x * xv.x + xv.y * xv.y + xv.z * xv.z + xv.w * xv.w;
;           sq = red16(sq);
;           const int ridx = bb * 4 + j;
;           if (ridx < 16) sqA = (fr == ridx) ? sq : sqA;
;           else sqB = (fr == ridx - 16) ? sq : sqB;
.LBB0_1237:
	s_nop 0
	v_pk_mul_f32 v[0:1], v[142:143], v[142:143]
	v_pk_mul_f32 v[2:3], v[134:135], v[134:135]
	s_nop 0
	v_add_f32_e32 v0, v0, v2
	v_add_f32_e32 v0, v1, v0
	v_add_f32_e32 v0, v3, v0
	s_nop 1
	v_add_f32_dpp v0, v0, v0 quad_perm:[1,0,3,2] row_mask:0xf bank_mask:0xf bound_ctrl:1
	s_nop 1
	v_add_f32_dpp v0, v0, v0 quad_perm:[2,3,0,1] row_mask:0xf bank_mask:0xf bound_ctrl:1
	s_nop 1
	v_add_f32_dpp v224, v0, v0 row_half_mirror row_mask:0xf bank_mask:0xf bound_ctrl:1
	s_nop 1
	v_mov_b32_dpp v225, v224 row_mirror row_mask:0xf bank_mask:0xf bound_ctrl:1
	v_add_u32_e32 v0, 0x140000, v201
	v_add_u32_e32 v1, 0x142000, v201
	global_load_dwordx4 v[154:157], v0, s[78:79]
	global_load_dwordx4 v[150:153], v1, s[78:79]
	v_add_u32_e32 v0, 0x144000, v201
	v_add_u32_e32 v1, 0x146000, v201
	global_load_dwordx4 v[142:145], v0, s[78:79]
	global_load_dwordx4 v[134:137], v1, s[78:79]
	v_mov_b32_e32 v0, v36
	v_mov_b32_e32 v1, v44
	s_waitcnt vmcnt(11)
	v_mov_b32_e32 v2, v158
	v_mov_b32_e32 v3, v160
	v_pk_fma_f32 v[162:163], s[80:81], v[0:1], v[2:3]
	v_mov_b32_e32 v0, v32
	v_mov_b32_e32 v1, v40
	v_mov_b32_e32 v160, v159
	v_add_u32_e32 v226, 0x48000, v173
	v_pk_fma_f32 v[158:159], s[80:81], v[0:1], v[160:161]
	v_lshlrev_b32_e32 v8, 2, v226
	v_mov_b32_e32 v0, v162
	v_mov_b32_e32 v1, v158
	v_mov_b32_e32 v2, v163
	v_mov_b32_e32 v3, v159
	s_and_b64 vcc, exec, s[6:7]
	global_store_dwordx4 v8, v[0:3], s[2:3]
	s_cbranch_vccnz .LBB0_1239
	s_nop 0
	v_pk_mul_f32 v[0:1], v[128:129], v[162:163]
	v_pk_mul_f32 v[2:3], v[170:171], v[158:159]
	v_lshlrev_b32_e32 v8, 1, v226
	v_cvt_pk_bf16_f32 v1, v1, v3
	v_cvt_pk_bf16_f32 v0, v0, v2
	global_store_dwordx2 v8, v[0:1], s[90:91]
.LBB0_1239:
	s_nop 0
	v_pk_mul_f32 v[0:1], v[162:163], v[162:163]
	v_pk_mul_f32 v[2:3], v[158:159], v[158:159]
	v_add_u32_e32 v160, 0x48800, v173
	v_add_f32_e32 v0, v0, v2
	v_add_f32_e32 v0, v1, v0
	v_add_f32_e32 v0, v3, v0
	v_mov_b32_e32 v1, v45
	s_waitcnt vmcnt(11)
	v_mov_b32_e32 v2, v146
	v_add_f32_dpp v0, v0, v0 quad_perm:[1,0,3,2] row_mask:0xf bank_mask:0xf bound_ctrl:1
	v_mov_b32_e32 v3, v148
	v_mov_b32_e32 v148, v147
	v_add_f32_dpp v0, v0, v0 quad_perm:[2,3,0,1] row_mask:0xf bank_mask:0xf bound_ctrl:1
	v_lshlrev_b32_e32 v8, 2, v160
	s_and_b64 vcc, exec, s[6:7]
	v_add_f32_dpp v226, v0, v0 row_half_mirror row_mask:0xf bank_mask:0xf bound_ctrl:1
	v_mov_b32_e32 v0, v37
	v_pk_fma_f32 v[158:159], s[80:81], v[0:1], v[2:3]
	v_mov_b32_e32 v0, v33
	v_mov_b32_e32 v1, v41
	v_pk_fma_f32 v[146:147], s[80:81], v[0:1], v[148:149]
	v_mov_b32_dpp v227, v226 row_mirror row_mask:0xf bank_mask:0xf bound_ctrl:1
	v_mov_b32_e32 v0, v158
	v_mov_b32_e32 v1, v146
	v_mov_b32_e32 v2, v159
	v_mov_b32_e32 v3, v147
	global_store_dwordx4 v8, v[0:3], s[2:3]
	s_cbranch_vccnz .LBB0_1241
	s_nop 0
	v_pk_mul_f32 v[0:1], v[128:129], v[158:159]
	v_pk_mul_f32 v[2:3], v[170:171], v[146:147]
	v_and_b32_sdwa v9, v1, v177 dst_sel:DWORD dst_unused:UNUSED_PAD src0_sel:WORD_1 src1_sel:DWORD
	v_add3_u32 v1, v1, v9, s48
	v_and_b32_sdwa v9, v3, v177 dst_sel:DWORD dst_unused:UNUSED_PAD src0_sel:WORD_1 src1_sel:DWORD
	v_add3_u32 v3, v3, v9, s48
	v_and_b32_e32 v3, 0xffff0000, v3
	v_lshlrev_b32_e32 v8, 1, v160
	v_or_b32_sdwa v1, v3, v1 dst_sel:DWORD dst_unused:UNUSED_PAD src0_sel:DWORD src1_sel:WORD_1
	v_cvt_pk_bf16_f32 v0, v0, v2
	global_store_dwordx2 v8, v[0:1], s[90:91]
.LBB0_1241:
	s_nop 0
	v_pk_mul_f32 v[0:1], v[158:159], v[158:159]
	v_pk_mul_f32 v[2:3], v[146:147], v[146:147]
	v_add_u32_e32 v148, 0x49000, v173
	v_add_f32_e32 v0, v0, v2
	v_add_f32_e32 v0, v1, v0
	v_add_f32_e32 v0, v3, v0
	v_mov_b32_e32 v1, v46
	s_waitcnt vmcnt(11)
	v_mov_b32_e32 v2, v138
	v_add_f32_dpp v0, v0, v0 quad_perm:[1,0,3,2] row_mask:0xf bank_mask:0xf bound_ctrl:1
	v_mov_b32_e32 v3, v140
	v_mov_b32_e32 v140, v139
	v_add_f32_dpp v0, v0, v0 quad_perm:[2,3,0,1] row_mask:0xf bank_mask:0xf bound_ctrl:1
	v_lshlrev_b32_e32 v8, 2, v148
	s_and_b64 vcc, exec, s[6:7]
	v_add_f32_dpp v228, v0, v0 row_half_mirror row_mask:0xf bank_mask:0xf bound_ctrl:1
	v_mov_b32_e32 v0, v38
	v_pk_fma_f32 v[146:147], s[80:81], v[0:1], v[2:3]
	v_mov_b32_e32 v0, v34
	v_mov_b32_e32 v1, v42
	v_pk_fma_f32 v[138:139], s[80:81], v[0:1], v[140:141]
	v_mov_b32_dpp v229, v228 row_mirror row_mask:0xf bank_mask:0xf bound_ctrl:1
	v_mov_b32_e32 v0, v146
	v_mov_b32_e32 v1, v138
	v_mov_b32_e32 v2, v147
	v_mov_b32_e32 v3, v139
	global_store_dwordx4 v8, v[0:3], s[2:3]
	s_cbranch_vccnz .LBB0_1243
	s_nop 0
	v_pk_mul_f32 v[0:1], v[128:129], v[146:147]
	v_pk_mul_f32 v[2:3], v[170:171], v[138:139]
	v_and_b32_sdwa v9, v1, v177 dst_sel:DWORD dst_unused:UNUSED_PAD src0_sel:WORD_1 src1_sel:DWORD
	v_add3_u32 v1, v1, v9, s48
	v_and_b32_sdwa v9, v3, v177 dst_sel:DWORD dst_unused:UNUSED_PAD src0_sel:WORD_1 src1_sel:DWORD
	v_add3_u32 v3, v3, v9, s48
	v_and_b32_e32 v3, 0xffff0000, v3
	v_lshlrev_b32_e32 v8, 1, v148
	v_or_b32_sdwa v1, v3, v1 dst_sel:DWORD dst_unused:UNUSED_PAD src0_sel:DWORD src1_sel:WORD_1
	v_cvt_pk_bf16_f32 v0, v0, v2
	global_store_dwordx2 v8, v[0:1], s[90:91]

; __device__ __forceinline__ float bflo(u32 w) { return __uint_as_float(w << 16); }
; __device__ __forceinline__ float bfhi(u32 w) { return __uint_as_float(w & 0xffff0000u); }
; __device__ __forceinline__ u32 pack2(float a, float b) { return (u32)f2bf(a) | ((u32)f2bf(b) << 16); }
; __device__ __forceinline__ float sigmoidf_(float x) { return __builtin_amdgcn_rcpf(1.f + __expf(-x)); }
; __device__ __forceinline__ void gemm_tile(const GemmArgs& ga, int wgid, int next_wgid, bool prefetched, u16* shm, unsigned char* ws, int wv_) {
;     ...
;       if (!GATE) { EPI_LOADS(0, 0) }
;       _Pragma("unroll") for (int bb = 0; bb < 8; ++bb) {
;         const int ai = bb >> 2, m = bb & 3;
;         const int cur = GATE ? 0 : (bb & 1);
;         if (GATE) { EPI_LOADS(bb, 0) }
;         else if (bb < 7) { EPI_LOADS(bb + 1, (bb + 1) & 1) }
;         _Pragma("unroll") for (int j = 0; j < 4; ++j) {
;           int row = rbase + ai * HALF + m * 16 + j;
;           unsigned eo = (unsigned)row * (unsigned)D_ + (unsigned)col0;
;           float s = 1.f;
;           if (GATE) s = rsqrtf(sc[j] * (1.f / D_) + 1e-6f);
;           const float a0 = acc[ai][0][m][0][j], a1 = acc[ai][0][m][1][j], a2 = acc[ai][1][m][0][j], a3 = acc[ai][1][m][1][j];
;           float4 xv = xin[cur][j];
;           if (GATE) {
;             xv.x += ga.live * (bflo(pin[j].x) * sigmoidf_(a0 * s));
;             xv.y += ga.live * (bfhi(pin[j].x) * sigmoidf_(a1 * s));
;             xv.z += ga.live * (bflo(pin[j].y) * sigmoidf_(a2 * s));
;             xv.w += ga.live * (bfhi(pin[j].y) * sigmoidf_(a3 * s));
;           } else {
;             const float al = ga.live * ga.alpha;
;             xv.x += al * a0; xv.y += al * a1; xv.z += al * a2; xv.w += al * a3;
;           }
;           *(float4*)(const_cast<char*>(xb) + (size_t)(eo * 4u)) = xv;
;           if (e_gn) *(uint2*)(ob + (size_t)(eo * 2u)) = make_uint2(pack2(xv.x * gn4.x, xv.y * gn4.y), pack2(xv.z * gn4.z, xv.w * gn4.w));
;           float sq = xv.x * xv.x + xv.y * xv.y + xv.z * xv.z + xv.w * xv.w;
;           sq = red16(sq);
;           const int ridx = bb * 4 + j;
;           if (ridx < 16) sqA = (fr == ridx) ? sq : sqA;
;           else sqB = (fr == ridx - 16) ? sq : sqB;
.LBB0_1245:
	s_nop 0
	v_pk_mul_f32 v[0:1], v[138:139], v[138:139]
	v_pk_mul_f32 v[2:3], v[130:131], v[130:131]
	s_nop 0
	v_add_f32_e32 v0, v0, v2
	v_add_f32_e32 v0, v1, v0
	v_add_f32_e32 v0, v3, v0
	s_nop 1
	v_add_f32_dpp v0, v0, v0 quad_perm:[1,0,3,2] row_mask:0xf bank_mask:0xf bound_ctrl:1
	s_nop 1
	v_add_f32_dpp v0, v0, v0 quad_perm:[2,3,0,1] row_mask:0xf bank_mask:0xf bound_ctrl:1
	s_nop 1
	v_add_f32_dpp v232, v0, v0 row_half_mirror row_mask:0xf bank_mask:0xf bound_ctrl:1
	s_nop 1
	v_mov_b32_dpp v233, v232 row_mirror row_mask:0xf bank_mask:0xf bound_ctrl:1
	v_add_u32_e32 v0, 0x160000, v201
	v_add_u32_e32 v1, 0x162000, v201
	global_load_dwordx4 v[158:161], v0, s[78:79]
	global_load_dwordx4 v[146:149], v1, s[78:79]
	v_add_u32_e32 v0, 0x164000, v201
	v_add_u32_e32 v1, 0x166000, v201
	global_load_dwordx4 v[138:141], v0, s[78:79]
	global_load_dwordx4 v[130:133], v1, s[78:79]
	v_mov_b32_e32 v0, v20
	v_mov_b32_e32 v1, v244
	s_waitcnt vmcnt(11)
	v_mov_b32_e32 v2, v154
	v_mov_b32_e32 v3, v156
	v_pk_fma_f32 v[162:163], s[80:81], v[0:1], v[2:3]
	v_mov_b32_e32 v0, v240
	v_mov_b32_e32 v1, v24
	v_mov_b32_e32 v156, v155
	v_add_u32_e32 v201, 0x50000, v173
	v_pk_fma_f32 v[154:155], s[80:81], v[0:1], v[156:157]
	v_lshlrev_b32_e32 v8, 2, v201
	v_mov_b32_e32 v0, v162
	v_mov_b32_e32 v1, v154
	v_mov_b32_e32 v2, v163
	v_mov_b32_e32 v3, v155
	s_and_b64 vcc, exec, s[6:7]
	global_store_dwordx4 v8, v[0:3], s[2:3]
	s_cbranch_vccnz .LBB0_1247
	s_nop 0
	v_pk_mul_f32 v[0:1], v[128:129], v[162:163]
	v_pk_mul_f32 v[2:3], v[170:171], v[154:155]
	v_lshlrev_b32_e32 v8, 1, v201
	v_cvt_pk_bf16_f32 v1, v1, v3
	v_cvt_pk_bf16_f32 v0, v0, v2
	global_store_dwordx2 v8, v[0:1], s[90:91]
.LBB0_1247:
	s_nop 0
	v_pk_mul_f32 v[0:1], v[162:163], v[162:163]
	v_pk_mul_f32 v[2:3], v[154:155], v[154:155]
	v_add_u32_e32 v162, 0x50800, v173
	v_add_f32_e32 v0, v0, v2
	v_add_f32_e32 v0, v1, v0
	v_add_f32_e32 v0, v3, v0
	v_mov_b32_e32 v1, v245
	s_waitcnt vmcnt(11)
	v_mov_b32_e32 v2, v150
	v_add_f32_dpp v0, v0, v0 quad_perm:[1,0,3,2] row_mask:0xf bank_mask:0xf bound_ctrl:1
	v_mov_b32_e32 v3, v152
	v_mov_b32_e32 v152, v151
	v_add_f32_dpp v0, v0, v0 quad_perm:[2,3,0,1] row_mask:0xf bank_mask:0xf bound_ctrl:1
	v_lshlrev_b32_e32 v8, 2, v162
	s_and_b64 vcc, exec, s[6:7]
	v_add_f32_dpp v156, v0, v0 row_half_mirror row_mask:0xf bank_mask:0xf bound_ctrl:1
	v_mov_b32_e32 v0, v21
	v_pk_fma_f32 v[154:155], s[80:81], v[0:1], v[2:3]
	v_mov_b32_e32 v0, v241
	v_mov_b32_e32 v1, v25
	v_pk_fma_f32 v[150:151], s[80:81], v[0:1], v[152:153]
	v_mov_b32_dpp v157, v156 row_mirror row_mask:0xf bank_mask:0xf bound_ctrl:1
	v_mov_b32_e32 v0, v154
	v_mov_b32_e32 v1, v150
	v_mov_b32_e32 v2, v155
	v_mov_b32_e32 v3, v151
	global_store_dwordx4 v8, v[0:3], s[2:3]
	s_cbranch_vccnz .LBB0_1249
	s_nop 0
	v_pk_mul_f32 v[0:1], v[128:129], v[154:155]
	v_pk_mul_f32 v[2:3], v[170:171], v[150:151]
	v_and_b32_sdwa v9, v1, v177 dst_sel:DWORD dst_unused:UNUSED_PAD src0_sel:WORD_1 src1_sel:DWORD
	v_add3_u32 v1, v1, v9, s48
	v_and_b32_sdwa v9, v3, v177 dst_sel:DWORD dst_unused:UNUSED_PAD src0_sel:WORD_1 src1_sel:DWORD
	v_add3_u32 v3, v3, v9, s48
	v_and_b32_e32 v3, 0xffff0000, v3
	v_lshlrev_b32_e32 v8, 1, v162
	v_or_b32_sdwa v1, v3, v1 dst_sel:DWORD dst_unused:UNUSED_PAD src0_sel:DWORD src1_sel:WORD_1
	v_cvt_pk_bf16_f32 v0, v0, v2
	global_store_dwordx2 v8, v[0:1], s[90:91]
.LBB0_1249:
	s_nop 0
	v_pk_mul_f32 v[0:1], v[154:155], v[154:155]
	v_pk_mul_f32 v[2:3], v[150:151], v[150:151]
	v_add_u32_e32 v154, 0x51000, v173
	v_add_f32_e32 v0, v0, v2
	v_add_f32_e32 v0, v1, v0
	v_add_f32_e32 v0, v3, v0
	v_mov_b32_e32 v1, v246
	s_waitcnt vmcnt(11)
	v_mov_b32_e32 v2, v142
	v_add_f32_dpp v0, v0, v0 quad_perm:[1,0,3,2] row_mask:0xf bank_mask:0xf bound_ctrl:1
	v_mov_b32_e32 v3, v144
	v_mov_b32_e32 v144, v143
	v_add_f32_dpp v0, v0, v0 quad_perm:[2,3,0,1] row_mask:0xf bank_mask:0xf bound_ctrl:1
	v_lshlrev_b32_e32 v8, 2, v154
	s_and_b64 vcc, exec, s[6:7]
	v_add_f32_dpp v152, v0, v0 row_half_mirror row_mask:0xf bank_mask:0xf bound_ctrl:1
	v_mov_b32_e32 v0, v22
	v_pk_fma_f32 v[150:151], s[80:81], v[0:1], v[2:3]
	v_mov_b32_e32 v0, v242
	v_mov_b32_e32 v1, v26
	v_pk_fma_f32 v[142:143], s[80:81], v[0:1], v[144:145]
	v_mov_b32_dpp v153, v152 row_mirror row_mask:0xf bank_mask:0xf bound_ctrl:1
	v_mov_b32_e32 v0, v150
	v_mov_b32_e32 v1, v142
	v_mov_b32_e32 v2, v151
	v_mov_b32_e32 v3, v143
	global_store_dwordx4 v8, v[0:3], s[2:3]
	s_cbranch_vccnz .LBB0_1251
	s_nop 0
	v_pk_mul_f32 v[0:1], v[128:129], v[150:151]
	v_pk_mul_f32 v[2:3], v[170:171], v[142:143]
	v_and_b32_sdwa v9, v1, v177 dst_sel:DWORD dst_unused:UNUSED_PAD src0_sel:WORD_1 src1_sel:DWORD
	v_add3_u32 v1, v1, v9, s48
	v_and_b32_sdwa v9, v3, v177 dst_sel:DWORD dst_unused:UNUSED_PAD src0_sel:WORD_1 src1_sel:DWORD
	v_add3_u32 v3, v3, v9, s48
	v_and_b32_e32 v3, 0xffff0000, v3
	v_lshlrev_b32_e32 v8, 1, v154
	v_or_b32_sdwa v1, v3, v1 dst_sel:DWORD dst_unused:UNUSED_PAD src0_sel:DWORD src1_sel:WORD_1
	v_cvt_pk_bf16_f32 v0, v0, v2
	global_store_dwordx2 v8, v[0:1], s[90:91]

; __device__ __forceinline__ float bflo(u32 w) { return __uint_as_float(w << 16); }
; __device__ __forceinline__ float bfhi(u32 w) { return __uint_as_float(w & 0xffff0000u); }
; __device__ __forceinline__ u32 pack2(float a, float b) { return (u32)f2bf(a) | ((u32)f2bf(b) << 16); }
; __device__ __forceinline__ float sigmoidf_(float x) { return __builtin_amdgcn_rcpf(1.f + __expf(-x)); }
; __device__ __forceinline__ void gemm_tile(const GemmArgs& ga, int wgid, int next_wgid, bool prefetched, u16* shm, unsigned char* ws, int wv_) {
;     ...
;       if (!GATE) { EPI_LOADS(0, 0) }
;       _Pragma("unroll") for (int bb = 0; bb < 8; ++bb) {
;         const int ai = bb >> 2, m = bb & 3;
;         const int cur = GATE ? 0 : (bb & 1);
;         if (GATE) { EPI_LOADS(bb, 0) }
;         else if (bb < 7) { EPI_LOADS(bb + 1, (bb + 1) & 1) }
;         _Pragma("unroll") for (int j = 0; j < 4; ++j) {
;           int row = rbase + ai * HALF + m * 16 + j;
;           unsigned eo = (unsigned)row * (unsigned)D_ + (unsigned)col0;
;           float s = 1.f;
;           if (GATE) s = rsqrtf(sc[j] * (1.f / D_) + 1e-6f);
;           const float a0 = acc[ai][0][m][0][j], a1 = acc[ai][0][m][1][j], a2 = acc[ai][1][m][0][j], a3 = acc[ai][1][m][1][j];
;           float4 xv = xin[cur][j];
;           if (GATE) {
;             xv.x += ga.live * (bflo(pin[j].x) * sigmoidf_(a0 * s));
;             xv.y += ga.live * (bfhi(pin[j].x) * sigmoidf_(a1 * s));
;             xv.z += ga.live * (bflo(pin[j].y) * sigmoidf_(a2 * s));
;             xv.w += ga.live * (bfhi(pin[j].y) * sigmoidf_(a3 * s));
;           } else {
;             const float al = ga.live * ga.alpha;
;             xv.x += al * a0; xv.y += al * a1; xv.z += al * a2; xv.w += al * a3;
;           }
;           *(float4*)(const_cast<char*>(xb) + (size_t)(eo * 4u)) = xv;
;           if (e_gn) *(uint2*)(ob + (size_t)(eo * 2u)) = make_uint2(pack2(xv.x * gn4.x, xv.y * gn4.y), pack2(xv.z * gn4.z, xv.w * gn4.w));
;           float sq = xv.x * xv.x + xv.y * xv.y + xv.z * xv.z + xv.w * xv.w;
;           sq = red16(sq);
;           const int ridx = bb * 4 + j;
;           if (ridx < 16) sqA = (fr == ridx) ? sq : sqA;
;           else sqB = (fr == ridx - 16) ? sq : sqB;
.LBB0_1253:
	s_nop 0
	v_pk_mul_f32 v[0:1], v[142:143], v[142:143]
	v_pk_mul_f32 v[2:3], v[134:135], v[134:135]
	s_nop 0
	v_add_f32_e32 v0, v0, v2
	v_add_f32_e32 v0, v1, v0
	v_add_f32_e32 v0, v3, v0
	s_nop 1
	v_add_f32_dpp v0, v0, v0 quad_perm:[1,0,3,2] row_mask:0xf bank_mask:0xf bound_ctrl:1
	s_nop 1
	v_add_f32_dpp v0, v0, v0 quad_perm:[2,3,0,1] row_mask:0xf bank_mask:0xf bound_ctrl:1
	s_nop 1
	v_add_f32_dpp v142, v0, v0 row_half_mirror row_mask:0xf bank_mask:0xf bound_ctrl:1
	s_nop 1
	v_mov_b32_dpp v143, v142 row_mirror row_mask:0xf bank_mask:0xf bound_ctrl:1
	v_mov_b32_e32 v0, v234
	v_mov_b32_e32 v1, v12
	s_waitcnt vmcnt(7)
	v_mov_b32_e32 v2, v158
	v_mov_b32_e32 v3, v160
	v_pk_fma_f32 v[134:135], s[80:81], v[0:1], v[2:3]
	v_mov_b32_e32 v0, v182
	v_mov_b32_e32 v1, v4
	v_mov_b32_e32 v160, v159
	v_add_u32_e32 v150, 0x58000, v173
	v_pk_fma_f32 v[136:137], s[80:81], v[0:1], v[160:161]
	v_lshlrev_b32_e32 v8, 2, v150
	v_mov_b32_e32 v0, v134
	v_mov_b32_e32 v1, v136
	v_mov_b32_e32 v2, v135
	v_mov_b32_e32 v3, v137
	s_and_b64 vcc, exec, s[6:7]
	global_store_dwordx4 v8, v[0:3], s[2:3]
	s_cbranch_vccnz .LBB0_1255
	s_nop 0
	v_pk_mul_f32 v[0:1], v[128:129], v[134:135]
	v_pk_mul_f32 v[2:3], v[170:171], v[136:137]
	v_lshlrev_b32_e32 v8, 1, v150
	v_cvt_pk_bf16_f32 v1, v1, v3
	v_cvt_pk_bf16_f32 v0, v0, v2
	global_store_dwordx2 v8, v[0:1], s[90:91]
.LBB0_1255:
	s_nop 0
	v_pk_mul_f32 v[0:1], v[134:135], v[134:135]
	v_pk_mul_f32 v[2:3], v[136:137], v[136:137]
	v_add_u32_e32 v154, 0x58800, v173
	v_add_f32_e32 v0, v0, v2
	v_add_f32_e32 v0, v1, v0
	v_add_f32_e32 v0, v3, v0
	v_mov_b32_e32 v1, v13
	s_waitcnt vmcnt(7)
	v_mov_b32_e32 v2, v146
	v_add_f32_dpp v0, v0, v0 quad_perm:[1,0,3,2] row_mask:0xf bank_mask:0xf bound_ctrl:1
	v_mov_b32_e32 v3, v148
	v_mov_b32_e32 v148, v147
	v_add_f32_dpp v0, v0, v0 quad_perm:[2,3,0,1] row_mask:0xf bank_mask:0xf bound_ctrl:1
	v_lshlrev_b32_e32 v8, 2, v154
	s_and_b64 vcc, exec, s[6:7]
	v_add_f32_dpp v150, v0, v0 row_half_mirror row_mask:0xf bank_mask:0xf bound_ctrl:1
	v_mov_b32_e32 v0, v235
	v_pk_fma_f32 v[134:135], s[80:81], v[0:1], v[2:3]
	v_mov_b32_e32 v0, v183
	v_mov_b32_e32 v1, v5
	v_pk_fma_f32 v[136:137], s[80:81], v[0:1], v[148:149]
	v_mov_b32_dpp v151, v150 row_mirror row_mask:0xf bank_mask:0xf bound_ctrl:1
	v_mov_b32_e32 v0, v134
	v_mov_b32_e32 v1, v136
	v_mov_b32_e32 v2, v135
	v_mov_b32_e32 v3, v137
	global_store_dwordx4 v8, v[0:3], s[2:3]
	s_cbranch_vccnz .LBB0_1257
	s_nop 0
	v_pk_mul_f32 v[0:1], v[128:129], v[134:135]
	v_pk_mul_f32 v[2:3], v[170:171], v[136:137]
	v_and_b32_sdwa v9, v1, v177 dst_sel:DWORD dst_unused:UNUSED_PAD src0_sel:WORD_1 src1_sel:DWORD
	v_add3_u32 v1, v1, v9, s48
	v_and_b32_sdwa v9, v3, v177 dst_sel:DWORD dst_unused:UNUSED_PAD src0_sel:WORD_1 src1_sel:DWORD
	v_add3_u32 v3, v3, v9, s48
	v_and_b32_e32 v3, 0xffff0000, v3
	v_lshlrev_b32_e32 v8, 1, v154
	v_or_b32_sdwa v1, v3, v1 dst_sel:DWORD dst_unused:UNUSED_PAD src0_sel:DWORD src1_sel:WORD_1
	v_cvt_pk_bf16_f32 v0, v0, v2
	global_store_dwordx2 v8, v[0:1], s[90:91]
.LBB0_1257:
	s_nop 0
	v_pk_mul_f32 v[0:1], v[134:135], v[134:135]
	v_pk_mul_f32 v[2:3], v[136:137], v[136:137]
	v_add_u32_e32 v148, 0x59000, v173
	v_add_f32_e32 v0, v0, v2
	v_add_f32_e32 v0, v1, v0
	v_add_f32_e32 v0, v3, v0
	v_mov_b32_e32 v1, v14
	s_waitcnt vmcnt(7)
	v_mov_b32_e32 v2, v138
	v_add_f32_dpp v0, v0, v0 quad_perm:[1,0,3,2] row_mask:0xf bank_mask:0xf bound_ctrl:1
	v_mov_b32_e32 v3, v140
	v_mov_b32_e32 v140, v139
	v_add_f32_dpp v0, v0, v0 quad_perm:[2,3,0,1] row_mask:0xf bank_mask:0xf bound_ctrl:1
	v_lshlrev_b32_e32 v8, 2, v148
	s_and_b64 vcc, exec, s[6:7]
	v_add_f32_dpp v146, v0, v0 row_half_mirror row_mask:0xf bank_mask:0xf bound_ctrl:1
	v_mov_b32_e32 v0, v236
	v_pk_fma_f32 v[134:135], s[80:81], v[0:1], v[2:3]
	v_mov_b32_e32 v0, v184
	v_mov_b32_e32 v1, v6
	v_pk_fma_f32 v[136:137], s[80:81], v[0:1], v[140:141]
	v_mov_b32_dpp v147, v146 row_mirror row_mask:0xf bank_mask:0xf bound_ctrl:1
	v_mov_b32_e32 v0, v134
	v_mov_b32_e32 v1, v136
	v_mov_b32_e32 v2, v135
	v_mov_b32_e32 v3, v137
	global_store_dwordx4 v8, v[0:3], s[2:3]
	s_cbranch_vccnz .LBB0_1259
	s_nop 0
	v_pk_mul_f32 v[0:1], v[128:129], v[134:135]
	v_pk_mul_f32 v[2:3], v[170:171], v[136:137]
	v_and_b32_sdwa v9, v1, v177 dst_sel:DWORD dst_unused:UNUSED_PAD src0_sel:WORD_1 src1_sel:DWORD
	v_add3_u32 v1, v1, v9, s48
	v_and_b32_sdwa v9, v3, v177 dst_sel:DWORD dst_unused:UNUSED_PAD src0_sel:WORD_1 src1_sel:DWORD
	v_add3_u32 v3, v3, v9, s48
	v_and_b32_e32 v3, 0xffff0000, v3
	v_lshlrev_b32_e32 v8, 1, v148
	v_or_b32_sdwa v1, v3, v1 dst_sel:DWORD dst_unused:UNUSED_PAD src0_sel:DWORD src1_sel:WORD_1
	v_cvt_pk_bf16_f32 v0, v0, v2
	global_store_dwordx2 v8, v[0:1], s[90:91]
.LBB0_1259:
	s_nop 0
	v_pk_mul_f32 v[0:1], v[134:135], v[134:135]
	v_pk_mul_f32 v[2:3], v[136:137], v[136:137]
	v_add_u32_e32 v138, 0x59800, v173
	v_add_f32_e32 v0, v0, v2
	v_add_f32_e32 v0, v1, v0
	v_add_f32_e32 v0, v3, v0
	v_mov_b32_e32 v1, v15
	s_waitcnt vmcnt(7)
	v_mov_b32_e32 v2, v130
	v_add_f32_dpp v0, v0, v0 quad_perm:[1,0,3,2] row_mask:0xf bank_mask:0xf bound_ctrl:1
	v_mov_b32_e32 v3, v132
	v_mov_b32_e32 v132, v131
	v_add_f32_dpp v0, v0, v0 quad_perm:[2,3,0,1] row_mask:0xf bank_mask:0xf bound_ctrl:1
	s_mov_b64 s[78:79], s[18:19]
	s_mov_b32 s57, s35
	v_add_f32_dpp v136, v0, v0 row_half_mirror row_mask:0xf bank_mask:0xf bound_ctrl:1
	v_mov_b32_e32 v0, v237
	v_pk_fma_f32 v[134:135], s[80:81], v[0:1], v[2:3]
	v_mov_b32_e32 v0, v185
	v_mov_b32_e32 v1, v7
	v_pk_fma_f32 v[130:131], s[80:81], v[0:1], v[132:133]
	v_mov_b32_dpp v137, v136 row_mirror row_mask:0xf bank_mask:0xf bound_ctrl:1
	v_lshlrev_b32_e32 v8, 2, v138
	v_mov_b32_e32 v0, v134
	v_mov_b32_e32 v1, v130
	v_mov_b32_e32 v2, v135
	v_mov_b32_e32 v3, v131
	s_and_b64 vcc, exec, s[6:7]
	global_store_dwordx4 v8, v[0:3], s[2:3]
	s_cbranch_vccnz .LBB0_1261
	s_nop 0
	v_pk_mul_f32 v[0:1], v[128:129], v[134:135]
	v_pk_mul_f32 v[2:3], v[170:171], v[130:131]
	v_lshlrev_b32_e32 v8, 1, v138
	v_cvt_pk_bf16_f32 v1, v1, v3
	v_cvt_pk_bf16_f32 v0, v0, v2
	global_store_dwordx2 v8, v[0:1], s[90:91]
